# first-iteration LDS fragment reads hoisted above the per-unit scalar decode in 7 GEMM loops
# speedup vs baseline: 1.0026x; 1.0026x over previous
; #define PG8_STAGE(bufoff, gbase, voff) do { _Pragma("unroll") for (int _i = 0; _i < 2; ++_i) \
;         __builtin_amdgcn_global_load_lds((const unsigned*)((const char*)(gbase) + (voff)[_i]), (LAS unsigned*)(lds + (bufoff) + ldsw + _i * 8192), 16, 0, 0); } while (0)
; #define PG8_LDA(dst, b, h) do { _Pragma("unroll") for (int m = 0; m < 4; ++m) _Pragma("unroll") for (int k = 0; k < 2; ++k) dst[m][k] = *(const LAS bf16x8*)(lds + PG8_SA(b, h) + aoff + m * 2048 + k * 1024); } while (0)
; #define PG8_LDB(dst, b, h) do { _Pragma("unroll") for (int n = 0; n < 2; ++n) _Pragma("unroll") for (int k = 0; k < 2; ++k) dst[n][k] = *(const LAS bf16x8*)(lds + PG8_SB(b, h) + boff + n * 2048 + k * 1024); } while (0)
; #define PG8_WAIT_V(n) asm volatile("s_waitcnt vmcnt(" #n ")" ::: "memory")
; #define PG8_WAIT_L(n) asm volatile("s_waitcnt lgkmcnt(" #n ")" ::: "memory")
; #define PG8_BAR __builtin_amdgcn_s_barrier()
;     __device__ __forceinline__ bool next(int i, Unit& u) const {
;         const long L = (long)i * G + c; if (L >= nwg) return false;
;         int wgid = (int)L; { const int q = nwg / NXCD, r = nwg % NXCD, xcd = wgid % NXCD, off = wgid / NXCD; wgid = (xcd < r ? xcd * (q + 1) : r * (q + 1) + (xcd - r) * q) + off; }
;         const int nig = WGM * nN, gid = wgid / nig, fm = gid * WGM, gsz = (nM - fm) < WGM ? (nM - fm) : WGM;
;         u.pm = fm + ((wgid % nig) % gsz); u.pn = (wgid % nig) / gsz; u.e = 0; u.kt0 = 0; u.nkt = nt; u.buf = 0;
;     ...
;         const bool has_next = S.next(ui + 1, nxt);
;         const char* nA = has_next ? (const char*)g.A + (size_t)nxt.pm * tstep + (size_t)nxt.kt0 * kstep : cA; const char* nB = has_next ? (const char*)g.Bt + (size_t)nxt.e * g.estride + (size_t)nxt.pn * tstep + (size_t)nxt.kt0 * kstep : cB;
;         const int nt = cur.nkt;
;         for (int t = 0; t < nt; t += 2) {
;             const bool last = (t == nt - 2);
;             const char* a1 = cA + (size_t)(t + 1) * kstep;
;             const char* a2 = last ? nA : cA + (size_t)(t + 2) * kstep; const char* b2 = last ? nB : cB + (size_t)(t + 2) * kstep;
;             const char* a3 = a2 + kstep; const char* b3 = b2 + kstep;
;             PG8_LDB(B0, 0, 0); PG8_LDB(B1, 0, 1); PG8_SCHED; PG8_LDA(At, 0, 0); PG8_STAGE(PG8_SA(1, 1), a1 + hstep, voffA);
;             PG8_WAIT_V(8); PG8_WAIT_L(0); PG8_BAR; PG8_MMA(0, 0, At, B0); PG8_MMA(0, 1, At, B1); PG8_BAR; PG8_SCHED;
.LBB0_1081:
	ds_read_b128 v[128:131], v166
	ds_read_b128 v[132:135], v166 offset:1024
	ds_read_b128 v[158:161], v166 offset:2048
	ds_read_b128 v[172:175], v166 offset:3072
	ds_read_b128 v[176:179], v167
	ds_read_b128 v[180:183], v167 offset:1024
	ds_read_b128 v[184:187], v167 offset:2048
	ds_read_b128 v[188:191], v167 offset:3072
	ds_read_b128 v[192:195], v168
	ds_read_b128 v[196:199], v168 offset:1024
	ds_read_b128 v[200:203], v168 offset:2048
	ds_read_b128 v[204:207], v168 offset:3072
	ds_read_b128 v[208:211], v168 offset:4096
	ds_read_b128 v[212:215], v168 offset:5120
	ds_read_b128 v[216:219], v168 offset:6144
	ds_read_b128 v[220:223], v168 offset:7168
	s_add_i32 s46, s46, 1
	s_mul_i32 s4, s46, s49
	s_mul_hi_u32 s5, s46, s33
	s_add_i32 s5, s5, s4
	s_mul_i32 s4, s46, s33
	s_add_u32 s24, s4, s22
	s_addc_u32 s25, s5, s50
	v_cmp_gt_i64_e32 vcc, s[24:25], v[156:157]
	v_cmp_lt_i64_e64 s[4:5], s[24:25], v[154:155]
	s_cbranch_vccnz .LBB0_1083
	s_ashr_i32 s7, s24, 31
	s_lshr_b32 s7, s7, 29
	s_add_i32 s7, s24, s7
	s_ashr_i32 s9, s7, 3
	s_and_b32 s7, s7, -8
	s_sub_i32 s7, s24, s7
	s_cmp_lt_i32 s7, 0
	s_cselect_b32 s18, s51, 0x90
	s_mul_i32 s7, s7, s18
	s_add_i32 s7, s7, s9
	s_mul_hi_i32 s9, s7, 0x38e38e39
	s_lshr_b32 s18, s9, 31
	s_ashr_i32 s9, s9, 5
	s_add_i32 s9, s9, s18
	s_lshl_b32 s19, s9, 3
	s_sub_i32 s18, 64, s19
	s_min_i32 s20, s18, 8
	s_abs_i32 s18, s20
	v_cvt_f32_u32_e32 v0, s18
	s_sub_i32 s24, 0, s18
	s_mulk_i32 s9, 0x90
	s_sub_i32 s7, s7, s9
	v_rcp_iflag_f32_e32 v0, v0
	s_abs_i32 s9, s7
	s_xor_b32 s21, s7, s20
	s_ashr_i32 s21, s21, 31
	v_mul_f32_e32 v0, 0x4f7ffffe, v0
	v_cvt_u32_f32_e32 v0, v0
	s_nop 0
	v_readfirstlane_b32 s25, v0
	s_mul_i32 s24, s24, s25
	s_mul_hi_u32 s24, s25, s24
	s_add_i32 s25, s25, s24
	s_mul_hi_u32 s24, s9, s25
	s_mul_i32 s25, s24, s18
	s_sub_i32 s9, s9, s25
	s_add_i32 s26, s24, 1
	s_sub_i32 s25, s9, s18
	s_cmp_ge_u32 s9, s18
	s_cselect_b32 s24, s26, s24
	s_cselect_b32 s9, s25, s9
	s_add_i32 s25, s24, 1
	s_cmp_ge_u32 s9, s18
	s_cselect_b32 s9, s25, s24
	s_xor_b32 s9, s9, s21
	s_sub_i32 s18, s9, s21
	s_mul_i32 s9, s18, s20
	s_sub_i32 s7, s7, s9
	s_add_i32 s20, s19, s7
.LBB0_1083:
	s_ashr_i32 s21, s20, 31
	s_lshl_b64 s[24:25], s[20:21], 19
	s_add_u32 s24, s23, s24
	s_addc_u32 s25, s34, s25
	s_and_b64 s[26:27], s[4:5], exec
	s_cselect_b32 s7, s25, s29
	s_cselect_b32 s9, s24, s28
	s_ashr_i32 s19, s18, 31
	s_lshl_b64 s[26:27], s[18:19], 19
	s_add_u32 s26, s35, s26
	s_addc_u32 s27, s38, s27
	s_and_b64 s[36:37], s[4:5], exec
	s_cselect_b32 s19, s27, s31
	s_cselect_b32 s21, s26, s30
	s_add_u32 s28, s28, 0x40080
	s_addc_u32 s29, s29, 0
	s_add_u32 s58, s30, 0x100
	s_addc_u32 s59, s31, 0
	s_mov_b32 s60, -2
	s_waitcnt lgkmcnt(0)
	s_add_u32 s30, s28, 0xfffc0080
	s_addc_u32 s31, s29, -1
	s_cmp_eq_u32 s60, 12
	s_cselect_b32 s37, s7, s31
	s_cselect_b32 s36, s9, s30
	s_cselect_b32 s31, s19, s59
	s_cselect_b32 s30, s21, s58
	v_lshl_add_u64 v[162:163], s[28:29], 0, v[150:151]
	s_add_i32 m0, s42, 0xc000
	global_load_lds_dwordx4 v[162:163], off
	v_lshl_add_u64 v[162:163], s[28:29], 0, v[152:153]
	s_add_i32 m0, s42, 0xe000
	s_nop 0
	global_load_lds_dwordx4 v[162:163], off
	s_waitcnt vmcnt(8)
	s_waitcnt lgkmcnt(0)
	s_barrier
	s_setprio 1
	s_waitcnt lgkmcnt(0)
	v_mfma_i32_16x16x64_i8 v[124:127], v[128:131], v[192:195], 0
	v_mfma_i32_16x16x64_i8 v[120:123], v[158:161], v[192:195], 0
	v_mfma_i32_16x16x64_i8 v[108:111], v[128:131], v[200:203], 0
	v_mfma_i32_16x16x64_i8 v[104:107], v[158:161], v[200:203], 0
	v_mfma_i32_16x16x64_i8 v[92:95], v[128:131], v[208:211], 0
	v_mfma_i32_16x16x64_i8 v[88:91], v[158:161], v[208:211], 0
	v_mfma_i32_16x16x64_i8 v[76:79], v[128:131], v[216:219], 0
	v_mfma_i32_16x16x64_i8 v[72:75], v[158:161], v[216:219], 0
	v_mfma_i32_16x16x64_i8 v[124:127], v[132:135], v[196:199], v[124:127]
	v_mfma_i32_16x16x64_i8 v[120:123], v[172:175], v[196:199], v[120:123]
	v_mfma_i32_16x16x64_i8 v[108:111], v[132:135], v[204:207], v[108:111]
	v_mfma_i32_16x16x64_i8 v[104:107], v[172:175], v[204:207], v[104:107]
	v_mfma_i32_16x16x64_i8 v[92:95], v[132:135], v[212:215], v[92:95]
	v_mfma_i32_16x16x64_i8 v[88:91], v[172:175], v[212:215], v[88:91]
	v_mfma_i32_16x16x64_i8 v[76:79], v[132:135], v[220:223], v[76:79]
	v_mfma_i32_16x16x64_i8 v[72:75], v[172:175], v[220:223], v[72:75]
	s_setprio 0
	s_setprio 1
	v_mfma_i32_16x16x64_i8 v[116:119], v[176:179], v[192:195], 0
	v_mfma_i32_16x16x64_i8 v[112:115], v[184:187], v[192:195], 0
	v_mfma_i32_16x16x64_i8 v[100:103], v[176:179], v[200:203], 0
	v_mfma_i32_16x16x64_i8 v[96:99], v[184:187], v[200:203], 0
	v_mfma_i32_16x16x64_i8 v[84:87], v[176:179], v[208:211], 0
	v_mfma_i32_16x16x64_i8 v[80:83], v[184:187], v[208:211], 0
	v_mfma_i32_16x16x64_i8 v[68:71], v[176:179], v[216:219], 0
	v_mfma_i32_16x16x64_i8 v[64:67], v[184:187], v[216:219], 0
	v_mfma_i32_16x16x64_i8 v[116:119], v[180:183], v[196:199], v[116:119]
	v_mfma_i32_16x16x64_i8 v[112:115], v[188:191], v[196:199], v[112:115]
	v_mfma_i32_16x16x64_i8 v[100:103], v[180:183], v[204:207], v[100:103]
	v_mfma_i32_16x16x64_i8 v[96:99], v[188:191], v[204:207], v[96:99]
	v_mfma_i32_16x16x64_i8 v[84:87], v[180:183], v[212:215], v[84:87]
	v_mfma_i32_16x16x64_i8 v[80:83], v[188:191], v[212:215], v[80:83]
	v_mfma_i32_16x16x64_i8 v[68:71], v[180:183], v[220:223], v[68:71]
	v_mfma_i32_16x16x64_i8 v[64:67], v[188:191], v[220:223], v[64:67]
	s_setprio 0
	s_barrier
; #define PG8_STAGE(bufoff, gbase, voff) do { _Pragma("unroll") for (int _i = 0; _i < 2; ++_i) \
;         __builtin_amdgcn_global_load_lds((const unsigned*)((const char*)(gbase) + (voff)[_i]), (LAS unsigned*)(lds + (bufoff) + ldsw + _i * 8192), 16, 0, 0); } while (0)
; #define PG8_LDA(dst, b, h) do { _Pragma("unroll") for (int m = 0; m < 4; ++m) _Pragma("unroll") for (int k = 0; k < 2; ++k) dst[m][k] = *(const LAS bf16x8*)(lds + PG8_SA(b, h) + aoff + m * 2048 + k * 1024); } while (0)
; #define PG8_LDB(dst, b, h) do { _Pragma("unroll") for (int n = 0; n < 2; ++n) _Pragma("unroll") for (int k = 0; k < 2; ++k) dst[n][k] = *(const LAS bf16x8*)(lds + PG8_SB(b, h) + boff + n * 2048 + k * 1024); } while (0)
; #define PG8_WAIT_V(n) asm volatile("s_waitcnt vmcnt(" #n ")" ::: "memory")
; #define PG8_WAIT_L(n) asm volatile("s_waitcnt lgkmcnt(" #n ")" ::: "memory")
; #define PG8_BAR __builtin_amdgcn_s_barrier()
; #define PG8_SCHED __builtin_amdgcn_sched_barrier(0)
;     ...
;             PG8_LDA(At, 0, 1); PG8_STAGE(PG8_SB(0, 0), b2, voffB); PG8_STAGE(PG8_SB(0, 1), b2 + hstep, voffB); PG8_STAGE(PG8_SA(0, 0), a2, voffA);
;             PG8_WAIT_V(8); PG8_WAIT_L(0); PG8_BAR; PG8_MMA(1, 0, At, B0); PG8_MMA(1, 1, At, B1); PG8_BAR; PG8_SCHED;
;             PG8_LDB(B0, 1, 0); PG8_LDB(B1, 1, 1); PG8_SCHED; PG8_LDA(At, 1, 0); PG8_STAGE(PG8_SA(0, 1), a2 + hstep, voffA);
;             PG8_WAIT_V(8); PG8_WAIT_L(0); PG8_BAR; PG8_MMA(0, 0, At, B0); PG8_MMA(0, 1, At, B1); PG8_BAR; PG8_SCHED;
	s_add_i32 s61, s54, s39
	v_lshl_add_u64 v[162:163], s[30:31], 0, v[138:139]
	s_mov_b32 m0, s61
	ds_read_b128 v[192:195], v168 offset:16384
	ds_read_b128 v[196:199], v168 offset:17408
	ds_read_b128 v[200:203], v168 offset:18432
	ds_read_b128 v[204:207], v168 offset:19456
	ds_read_b128 v[208:211], v168 offset:20480
	ds_read_b128 v[212:215], v168 offset:21504
	ds_read_b128 v[216:219], v168 offset:22528
	ds_read_b128 v[220:223], v168 offset:23552
	global_load_lds_dwordx4 v[162:163], off
	s_add_i32 m0, s61, 0x2000
	s_add_u32 s62, s30, 0x40000
	v_lshl_add_u64 v[224:225], s[30:31], 0, v[142:143]
	s_addc_u32 s63, s31, 0
	s_add_i32 s61, s55, s39
	global_load_lds_dwordx4 v[224:225], off
	v_lshl_add_u64 v[226:227], s[62:63], 0, v[138:139]
	s_mov_b32 m0, s61
	v_lshl_add_u64 v[228:229], s[36:37], 0, v[140:141]
	global_load_lds_dwordx4 v[226:227], off
	v_lshl_add_u64 v[226:227], s[62:63], 0, v[142:143]
	s_add_i32 m0, s61, 0x2000
	s_nop 0
	global_load_lds_dwordx4 v[226:227], off
	v_lshl_add_u64 v[226:227], s[36:37], 0, v[136:137]
	s_mov_b32 m0, s42
	s_nop 0
	global_load_lds_dwordx4 v[226:227], off
	s_mov_b32 m0, s43
	s_nop 0
	global_load_lds_dwordx4 v[228:229], off
	s_waitcnt vmcnt(8)
	s_waitcnt lgkmcnt(0)
	s_barrier
	s_setprio 1
	s_waitcnt lgkmcnt(0)
	v_mfma_i32_16x16x64_i8 v[60:63], v[128:131], v[192:195], 0
	v_mfma_i32_16x16x64_i8 v[56:59], v[158:161], v[192:195], 0
	v_mfma_i32_16x16x64_i8 v[44:47], v[128:131], v[200:203], 0
	v_mfma_i32_16x16x64_i8 v[40:43], v[158:161], v[200:203], 0
	v_mfma_i32_16x16x64_i8 v[28:31], v[128:131], v[208:211], 0
	v_mfma_i32_16x16x64_i8 v[24:27], v[158:161], v[208:211], 0
	v_mfma_i32_16x16x64_i8 v[12:15], v[128:131], v[216:219], 0
	v_mfma_i32_16x16x64_i8 v[8:11], v[158:161], v[216:219], 0
	v_mfma_i32_16x16x64_i8 v[60:63], v[132:135], v[196:199], v[60:63]
	v_mfma_i32_16x16x64_i8 v[56:59], v[172:175], v[196:199], v[56:59]
	v_mfma_i32_16x16x64_i8 v[44:47], v[132:135], v[204:207], v[44:47]
	v_mfma_i32_16x16x64_i8 v[40:43], v[172:175], v[204:207], v[40:43]
	v_mfma_i32_16x16x64_i8 v[28:31], v[132:135], v[212:215], v[28:31]
	v_mfma_i32_16x16x64_i8 v[24:27], v[172:175], v[212:215], v[24:27]
	v_mfma_i32_16x16x64_i8 v[12:15], v[132:135], v[220:223], v[12:15]
	v_mfma_i32_16x16x64_i8 v[8:11], v[172:175], v[220:223], v[8:11]
	s_setprio 0
	s_setprio 1
	v_mfma_i32_16x16x64_i8 v[52:55], v[176:179], v[192:195], 0
	v_mfma_i32_16x16x64_i8 v[48:51], v[184:187], v[192:195], 0
	v_mfma_i32_16x16x64_i8 v[36:39], v[176:179], v[200:203], 0
	v_mfma_i32_16x16x64_i8 v[32:35], v[184:187], v[200:203], 0
	v_mfma_i32_16x16x64_i8 v[20:23], v[176:179], v[208:211], 0
	v_mfma_i32_16x16x64_i8 v[16:19], v[184:187], v[208:211], 0
	v_mfma_i32_16x16x64_i8 v[4:7], v[176:179], v[216:219], 0
	v_mfma_i32_16x16x64_i8 v[0:3], v[184:187], v[216:219], 0
	v_mfma_i32_16x16x64_i8 v[52:55], v[180:183], v[196:199], v[52:55]
	v_mfma_i32_16x16x64_i8 v[48:51], v[188:191], v[196:199], v[48:51]
	v_mfma_i32_16x16x64_i8 v[36:39], v[180:183], v[204:207], v[36:39]
	v_mfma_i32_16x16x64_i8 v[32:35], v[188:191], v[204:207], v[32:35]
	v_mfma_i32_16x16x64_i8 v[20:23], v[180:183], v[212:215], v[20:23]
	v_mfma_i32_16x16x64_i8 v[16:19], v[188:191], v[212:215], v[16:19]
	v_mfma_i32_16x16x64_i8 v[4:7], v[180:183], v[220:223], v[4:7]
	v_mfma_i32_16x16x64_i8 v[0:3], v[188:191], v[220:223], v[0:3]
	s_setprio 0
	s_barrier
	s_add_i32 s61, 0, 0x18000
	s_add_i32 s62, 0, 0x1c000
	v_add_u32_e32 v172, s61, v165
	v_add_u32_e32 v188, s62, v165
	ds_read_b128 v[128:131], v172
	ds_read_b128 v[132:135], v172 offset:1024
	ds_read_b128 v[158:161], v172 offset:2048
	ds_read_b128 v[172:175], v172 offset:3072
	ds_read_b128 v[176:179], v188
	ds_read_b128 v[180:183], v188 offset:1024
	ds_read_b128 v[184:187], v188 offset:2048
	ds_read_b128 v[188:191], v188 offset:3072
	s_add_u32 s36, s36, 0x40000
	s_addc_u32 s37, s37, 0
	s_mov_b32 m0, s44
	v_lshl_add_u64 v[230:231], s[36:37], 0, v[136:137]
	ds_read_b128 v[192:195], v168 offset:32768
	ds_read_b128 v[196:199], v168 offset:33792
	ds_read_b128 v[200:203], v168 offset:34816
	ds_read_b128 v[204:207], v168 offset:35840
	ds_read_b128 v[208:211], v168 offset:36864
	ds_read_b128 v[212:215], v168 offset:37888
	ds_read_b128 v[216:219], v168 offset:38912
	ds_read_b128 v[220:223], v168 offset:39936
	global_load_lds_dwordx4 v[230:231], off
	v_lshl_add_u64 v[230:231], s[36:37], 0, v[140:141]
	s_mov_b32 m0, s45
	s_nop 0
	global_load_lds_dwordx4 v[230:231], off
	s_waitcnt vmcnt(8)
	s_waitcnt lgkmcnt(0)
	s_barrier
; #define PG8_STAGE(bufoff, gbase, voff) do { _Pragma("unroll") for (int _i = 0; _i < 2; ++_i) \
;         __builtin_amdgcn_global_load_lds((const unsigned*)((const char*)(gbase) + (voff)[_i]), (LAS unsigned*)(lds + (bufoff) + ldsw + _i * 8192), 16, 0, 0); } while (0)
; #define PG8_LDA(dst, b, h) do { _Pragma("unroll") for (int m = 0; m < 4; ++m) _Pragma("unroll") for (int k = 0; k < 2; ++k) dst[m][k] = *(const LAS bf16x8*)(lds + PG8_SA(b, h) + aoff + m * 2048 + k * 1024); } while (0)
; #define PG8_WAIT_V(n) asm volatile("s_waitcnt vmcnt(" #n ")" ::: "memory")
; #define PG8_WAIT_L(n) asm volatile("s_waitcnt lgkmcnt(" #n ")" ::: "memory")
; #define PG8_BAR __builtin_amdgcn_s_barrier()
; #define PG8_SCHED __builtin_amdgcn_sched_barrier(0)
;     ...
;             PG8_WAIT_V(8); PG8_WAIT_L(0); PG8_BAR; PG8_MMA(0, 0, At, B0); PG8_MMA(0, 1, At, B1); PG8_BAR; PG8_SCHED;
;             PG8_LDA(At, 1, 1); PG8_STAGE(PG8_SB(1, 0), b3, voffB); PG8_STAGE(PG8_SB(1, 1), b3 + hstep, voffB); PG8_STAGE(PG8_SA(1, 0), a3, voffA);
;             PG8_WAIT_V(8); PG8_WAIT_L(0); PG8_BAR; PG8_MMA(1, 0, At, B0); PG8_MMA(1, 1, At, B1); PG8_BAR; PG8_SCHED;
;         }
	s_setprio 1
	s_waitcnt lgkmcnt(0)
	v_mfma_i32_16x16x64_i8 v[124:127], v[128:131], v[192:195], v[124:127]
	v_mfma_i32_16x16x64_i8 v[120:123], v[158:161], v[192:195], v[120:123]
	v_mfma_i32_16x16x64_i8 v[108:111], v[128:131], v[200:203], v[108:111]
	v_mfma_i32_16x16x64_i8 v[104:107], v[158:161], v[200:203], v[104:107]
	v_mfma_i32_16x16x64_i8 v[92:95], v[128:131], v[208:211], v[92:95]
	v_mfma_i32_16x16x64_i8 v[88:91], v[158:161], v[208:211], v[88:91]
	v_mfma_i32_16x16x64_i8 v[76:79], v[128:131], v[216:219], v[76:79]
	v_mfma_i32_16x16x64_i8 v[72:75], v[158:161], v[216:219], v[72:75]
	v_mfma_i32_16x16x64_i8 v[124:127], v[132:135], v[196:199], v[124:127]
	v_mfma_i32_16x16x64_i8 v[120:123], v[172:175], v[196:199], v[120:123]
	v_mfma_i32_16x16x64_i8 v[108:111], v[132:135], v[204:207], v[108:111]
	v_mfma_i32_16x16x64_i8 v[104:107], v[172:175], v[204:207], v[104:107]
	v_mfma_i32_16x16x64_i8 v[92:95], v[132:135], v[212:215], v[92:95]
	v_mfma_i32_16x16x64_i8 v[88:91], v[172:175], v[212:215], v[88:91]
	v_mfma_i32_16x16x64_i8 v[76:79], v[132:135], v[220:223], v[76:79]
	v_mfma_i32_16x16x64_i8 v[72:75], v[172:175], v[220:223], v[72:75]
	s_setprio 0
	s_setprio 1
	v_mfma_i32_16x16x64_i8 v[116:119], v[176:179], v[192:195], v[116:119]
	v_mfma_i32_16x16x64_i8 v[112:115], v[184:187], v[192:195], v[112:115]
	v_mfma_i32_16x16x64_i8 v[100:103], v[176:179], v[200:203], v[100:103]
	v_mfma_i32_16x16x64_i8 v[96:99], v[184:187], v[200:203], v[96:99]
	v_mfma_i32_16x16x64_i8 v[84:87], v[176:179], v[208:211], v[84:87]
	v_mfma_i32_16x16x64_i8 v[80:83], v[184:187], v[208:211], v[80:83]
	v_mfma_i32_16x16x64_i8 v[68:71], v[176:179], v[216:219], v[68:71]
	v_mfma_i32_16x16x64_i8 v[64:67], v[184:187], v[216:219], v[64:67]
	v_mfma_i32_16x16x64_i8 v[116:119], v[180:183], v[196:199], v[116:119]
	v_mfma_i32_16x16x64_i8 v[112:115], v[188:191], v[196:199], v[112:115]
	v_mfma_i32_16x16x64_i8 v[100:103], v[180:183], v[204:207], v[100:103]
	v_mfma_i32_16x16x64_i8 v[96:99], v[188:191], v[204:207], v[96:99]
	v_mfma_i32_16x16x64_i8 v[84:87], v[180:183], v[212:215], v[84:87]
	v_mfma_i32_16x16x64_i8 v[80:83], v[188:191], v[212:215], v[80:83]
	v_mfma_i32_16x16x64_i8 v[68:71], v[180:183], v[220:223], v[68:71]
	v_mfma_i32_16x16x64_i8 v[64:67], v[188:191], v[220:223], v[64:67]
	s_setprio 0
	s_barrier
	s_add_i32 s36, s61, s39
	v_lshl_add_u64 v[162:163], v[162:163], 0, s[12:13]
	s_mov_b32 m0, s36
	ds_read_b128 v[192:195], v168 offset:49152
	ds_read_b128 v[196:199], v168 offset:50176
	ds_read_b128 v[200:203], v168 offset:51200
	ds_read_b128 v[204:207], v168 offset:52224
	ds_read_b128 v[208:211], v168 offset:53248
	ds_read_b128 v[212:215], v168 offset:54272
	ds_read_b128 v[216:219], v168 offset:55296
	ds_read_b128 v[220:223], v168 offset:56320
	global_load_lds_dwordx4 v[162:163], off
	s_add_i32 m0, s36, 0x2000
	s_add_u32 s30, s30, 0x40080
	v_lshl_add_u64 v[162:163], v[224:225], 0, s[12:13]
	s_addc_u32 s31, s31, 0
	s_add_i32 s36, s62, s39
	global_load_lds_dwordx4 v[162:163], off
	v_lshl_add_u64 v[162:163], s[30:31], 0, v[138:139]
	s_mov_b32 m0, s36
	s_nop 0
	global_load_lds_dwordx4 v[162:163], off
	v_lshl_add_u64 v[162:163], s[30:31], 0, v[142:143]
	s_add_i32 m0, s36, 0x2000
	s_nop 0
	global_load_lds_dwordx4 v[162:163], off
	v_lshl_add_u64 v[162:163], v[226:227], 0, s[12:13]
	s_mov_b32 m0, s47
	s_nop 0
	global_load_lds_dwordx4 v[162:163], off
	v_lshl_add_u64 v[162:163], v[228:229], 0, s[12:13]
	s_mov_b32 m0, s48
	s_nop 0
	global_load_lds_dwordx4 v[162:163], off
	s_waitcnt vmcnt(8)
	s_waitcnt lgkmcnt(0)
	s_barrier
	s_setprio 1
	s_waitcnt lgkmcnt(0)
	v_mfma_i32_16x16x64_i8 v[60:63], v[128:131], v[192:195], v[60:63]
	v_mfma_i32_16x16x64_i8 v[56:59], v[158:161], v[192:195], v[56:59]
	v_mfma_i32_16x16x64_i8 v[44:47], v[128:131], v[200:203], v[44:47]
	v_mfma_i32_16x16x64_i8 v[40:43], v[158:161], v[200:203], v[40:43]
	v_mfma_i32_16x16x64_i8 v[28:31], v[128:131], v[208:211], v[28:31]
	v_mfma_i32_16x16x64_i8 v[24:27], v[158:161], v[208:211], v[24:27]
	v_mfma_i32_16x16x64_i8 v[12:15], v[128:131], v[216:219], v[12:15]
	v_mfma_i32_16x16x64_i8 v[8:11], v[158:161], v[216:219], v[8:11]
	v_mfma_i32_16x16x64_i8 v[60:63], v[132:135], v[196:199], v[60:63]
	v_mfma_i32_16x16x64_i8 v[56:59], v[172:175], v[196:199], v[56:59]
	v_mfma_i32_16x16x64_i8 v[44:47], v[132:135], v[204:207], v[44:47]
	v_mfma_i32_16x16x64_i8 v[40:43], v[172:175], v[204:207], v[40:43]
	v_mfma_i32_16x16x64_i8 v[28:31], v[132:135], v[212:215], v[28:31]
	v_mfma_i32_16x16x64_i8 v[24:27], v[172:175], v[212:215], v[24:27]
	v_mfma_i32_16x16x64_i8 v[12:15], v[132:135], v[220:223], v[12:15]
	v_mfma_i32_16x16x64_i8 v[8:11], v[172:175], v[220:223], v[8:11]
	s_setprio 0
	s_setprio 1
	v_mfma_i32_16x16x64_i8 v[52:55], v[176:179], v[192:195], v[52:55]
	v_mfma_i32_16x16x64_i8 v[48:51], v[184:187], v[192:195], v[48:51]
	v_mfma_i32_16x16x64_i8 v[36:39], v[176:179], v[200:203], v[36:39]
	v_mfma_i32_16x16x64_i8 v[32:35], v[184:187], v[200:203], v[32:35]
	v_mfma_i32_16x16x64_i8 v[20:23], v[176:179], v[208:211], v[20:23]
	v_mfma_i32_16x16x64_i8 v[16:19], v[184:187], v[208:211], v[16:19]
	v_mfma_i32_16x16x64_i8 v[4:7], v[176:179], v[216:219], v[4:7]
	v_mfma_i32_16x16x64_i8 v[0:3], v[184:187], v[216:219], v[0:3]
	v_mfma_i32_16x16x64_i8 v[52:55], v[180:183], v[196:199], v[52:55]
	v_mfma_i32_16x16x64_i8 v[48:51], v[188:191], v[196:199], v[48:51]
	v_mfma_i32_16x16x64_i8 v[36:39], v[180:183], v[204:207], v[36:39]
	v_mfma_i32_16x16x64_i8 v[32:35], v[188:191], v[204:207], v[32:35]
	v_mfma_i32_16x16x64_i8 v[20:23], v[180:183], v[212:215], v[20:23]
	v_mfma_i32_16x16x64_i8 v[16:19], v[188:191], v[212:215], v[16:19]
	v_mfma_i32_16x16x64_i8 v[4:7], v[180:183], v[220:223], v[4:7]
	v_mfma_i32_16x16x64_i8 v[0:3], v[188:191], v[220:223], v[0:3]
	s_setprio 0
	s_barrier
	s_add_i32 s60, s60, 2
	s_add_u32 s28, s28, 0x100
	s_addc_u32 s29, s29, 0
	s_add_u32 s58, s58, 0x100
	s_addc_u32 s59, s59, 0
	s_cmp_gt_u32 s60, 13
	s_cbranch_scc0 .LBB0_1084

;     __device__ __forceinline__ bool next(int i, Unit& u) const {
;         const long L = (long)i * G + c; if (L >= nwg) return false;
;         int wgid = (int)L; { const int q = nwg / NXCD, r = nwg % NXCD, xcd = wgid % NXCD, off = wgid / NXCD; wgid = (xcd < r ? xcd * (q + 1) : r * (q + 1) + (xcd - r) * q) + off; }
;         const int nig = WGM * nN, gid = wgid / nig, fm = gid * WGM, gsz = (nM - fm) < WGM ? (nM - fm) : WGM;
;         u.pm = fm + ((wgid % nig) % gsz); u.pn = (wgid % nig) / gsz; u.e = 0; u.kt0 = 0; u.nkt = nt; u.buf = 0;
;     ...
;         const bool has_next = S.next(ui + 1, nxt);
;         const char* nA = has_next ? (const char*)g.A + (size_t)nxt.pm * tstep + (size_t)nxt.kt0 * kstep : cA; const char* nB = has_next ? (const char*)g.Bt + (size_t)nxt.e * g.estride + (size_t)nxt.pn * tstep + (size_t)nxt.kt0 * kstep : cB;
;         const int nt = cur.nkt;
.LBB0_3679:
	ds_read_b128 v[24:27], v187
	ds_read_b128 v[28:31], v187 offset:1024
	ds_read_b128 v[16:19], v187 offset:2048
	ds_read_b128 v[20:23], v187 offset:3072
	ds_read_b128 v[8:11], v188
	ds_read_b128 v[12:15], v188 offset:1024
	s_add_i32 s54, s54, 1
	s_mul_i32 s4, s54, s59
	s_mul_hi_u32 s5, s54, s33
	s_add_i32 s5, s5, s4
	s_mul_i32 s4, s54, s33
	s_add_u32 s36, s4, s22
	s_addc_u32 s37, s5, s60
	v_cmp_gt_i64_e32 vcc, s[36:37], v[174:175]
	v_cmp_lt_i64_e64 s[4:5], s[36:37], v[172:173]
	s_cbranch_vccnz .LBB0_3685
	s_ashr_i32 s28, s36, 31
	s_lshr_b32 s28, s28, 29
	s_add_i32 s30, s36, s28
	s_and_b32 s28, s30, -8
	s_sub_i32 s31, s36, s28
	s_cmp_gt_i32 s31, -1
	s_mov_b64 s[28:29], -1
	s_cbranch_scc0 .LBB0_3682
	s_lshl_b32 s36, s31, 6
	s_mov_b64 s[28:29], 0

; #define PG8_STAGE(bufoff, gbase, voff) do { _Pragma("unroll") for (int _i = 0; _i < 2; ++_i) \
;         __builtin_amdgcn_global_load_lds((const unsigned*)((const char*)(gbase) + (voff)[_i]), (LAS unsigned*)(lds + (bufoff) + ldsw + _i * 8192), 16, 0, 0); } while (0)
; #define PG8_LDA(dst, b, h) do { _Pragma("unroll") for (int m = 0; m < 4; ++m) _Pragma("unroll") for (int k = 0; k < 2; ++k) dst[m][k] = *(const LAS bf16x8*)(lds + PG8_SA(b, h) + aoff + m * 2048 + k * 1024); } while (0)
; #define PG8_LDB(dst, b, h) do { _Pragma("unroll") for (int n = 0; n < 2; ++n) _Pragma("unroll") for (int k = 0; k < 2; ++k) dst[n][k] = *(const LAS bf16x8*)(lds + PG8_SB(b, h) + boff + n * 2048 + k * 1024); } while (0)
; #define PG8_WAIT_V(n) asm volatile("s_waitcnt vmcnt(" #n ")" ::: "memory")
; #define PG8_WAIT_L(n) asm volatile("s_waitcnt lgkmcnt(" #n ")" ::: "memory")
; #define PG8_BAR __builtin_amdgcn_s_barrier()
; #define PG8_SCHED __builtin_amdgcn_sched_barrier(0)
;     ...
;         for (int t = 0; t < nt; t += 2) {
;             const bool last = (t == nt - 2);
;             const char* a1 = cA + (size_t)(t + 1) * kstep;
;             const char* a2 = last ? nA : cA + (size_t)(t + 2) * kstep; const char* b2 = last ? nB : cB + (size_t)(t + 2) * kstep;
;             const char* a3 = a2 + kstep; const char* b3 = b2 + kstep;
;             PG8_LDB(B0, 0, 0); PG8_LDB(B1, 0, 1); PG8_SCHED; PG8_LDA(At, 0, 0); PG8_STAGE(PG8_SA(1, 1), a1 + hstep, voffA);
;             PG8_WAIT_V(8); PG8_WAIT_L(0); PG8_BAR; PG8_MMA(0, 0, At, B0); PG8_MMA(0, 1, At, B1); PG8_BAR; PG8_SCHED;
;             PG8_LDA(At, 0, 1); PG8_STAGE(PG8_SB(0, 0), b2, voffB); PG8_STAGE(PG8_SB(0, 1), b2 + hstep, voffB); PG8_STAGE(PG8_SA(0, 0), a2, voffA);
;             PG8_WAIT_V(8); PG8_WAIT_L(0); PG8_BAR; PG8_MMA(1, 0, At, B0); PG8_MMA(1, 1, At, B1); PG8_BAR; PG8_SCHED;
.LBB0_3685:
	s_ashr_i32 s31, s30, 31
	s_lshl_b64 s[36:37], s[30:31], 19
	s_add_u32 s36, s21, s36
	s_addc_u32 s37, s23, s37
	s_and_b64 s[38:39], s[4:5], exec
	s_cselect_b32 s31, s37, s45
	s_cselect_b32 s41, s36, s44
	s_ashr_i32 s29, s28, 31
	s_lshl_b64 s[38:39], s[28:29], 19
	s_add_u32 s38, s25, s38
	s_addc_u32 s39, s27, s39
	s_and_b64 s[48:49], s[4:5], exec
	s_cselect_b32 s29, s39, s47
	s_cselect_b32 s66, s38, s46
	s_add_u32 s44, s44, 0x40080
	s_addc_u32 s45, s45, 0
	s_add_u32 s67, s46, 0x100
	s_addc_u32 s68, s47, 0
	s_mov_b32 s69, -2
	s_waitcnt lgkmcnt(0)
	ds_read_b128 v[0:3], v188 offset:2048
	ds_read_b128 v[4:7], v188 offset:3072
	s_add_u32 s46, s44, 0xfffc0080
	s_addc_u32 s47, s45, -1
	s_cmp_eq_u32 s69, 12
	s_cselect_b32 s49, s31, s47
	s_cselect_b32 s48, s41, s46
	s_cselect_b32 s47, s29, s68
	s_cselect_b32 s46, s66, s67
	v_lshl_add_u64 v[218:219], s[44:45], 0, v[168:169]
	s_add_i32 m0, s35, 0xc000
	ds_read_b128 v[176:179], v189
	ds_read_b128 v[180:183], v189 offset:1024
	ds_read_b128 v[194:197], v189 offset:2048
	ds_read_b128 v[198:201], v189 offset:3072
	ds_read_b128 v[202:205], v189 offset:4096
	ds_read_b128 v[206:209], v189 offset:5120
	ds_read_b128 v[210:213], v189 offset:6144
	ds_read_b128 v[214:217], v189 offset:7168
	global_load_lds_dwordx4 v[218:219], off
	v_lshl_add_u64 v[218:219], s[44:45], 0, v[170:171]
	s_add_i32 m0, s35, 0xe000
	s_nop 0
	global_load_lds_dwordx4 v[218:219], off
	s_waitcnt vmcnt(8)
	s_waitcnt lgkmcnt(0)
	s_barrier
	s_setprio 1
	s_waitcnt lgkmcnt(0)
	v_mfma_scale_f32_16x16x128_f8f6f4 v[156:159], v[24:31], v[176:183], 0, v190, v190 op_sel_hi:[0,0,0]
	v_mfma_scale_f32_16x16x128_f8f6f4 v[152:155], v[16:23], v[176:183], 0, v190, v190 op_sel_hi:[0,0,0]
	v_mfma_scale_f32_16x16x128_f8f6f4 v[140:143], v[24:31], v[194:201], 0, v190, v190 op_sel_hi:[0,0,0]
	v_mfma_scale_f32_16x16x128_f8f6f4 v[136:139], v[16:23], v[194:201], 0, v190, v190 op_sel_hi:[0,0,0]
	v_mfma_scale_f32_16x16x128_f8f6f4 v[124:127], v[24:31], v[202:209], 0, v190, v190 op_sel_hi:[0,0,0]
	v_mfma_scale_f32_16x16x128_f8f6f4 v[120:123], v[16:23], v[202:209], 0, v190, v190 op_sel_hi:[0,0,0]
	v_mfma_scale_f32_16x16x128_f8f6f4 v[108:111], v[24:31], v[210:217], 0, v190, v190 op_sel_hi:[0,0,0]
	v_mfma_scale_f32_16x16x128_f8f6f4 v[104:107], v[16:23], v[210:217], 0, v190, v190 op_sel_hi:[0,0,0]
	s_setprio 0
	s_setprio 1
	v_mfma_scale_f32_16x16x128_f8f6f4 v[148:151], v[8:15], v[176:183], 0, v190, v190 op_sel_hi:[0,0,0]
	v_mfma_scale_f32_16x16x128_f8f6f4 v[144:147], v[0:7], v[176:183], 0, v190, v190 op_sel_hi:[0,0,0]
	v_mfma_scale_f32_16x16x128_f8f6f4 v[132:135], v[8:15], v[194:201], 0, v190, v190 op_sel_hi:[0,0,0]
	v_mfma_scale_f32_16x16x128_f8f6f4 v[128:131], v[0:7], v[194:201], 0, v190, v190 op_sel_hi:[0,0,0]
	v_mfma_scale_f32_16x16x128_f8f6f4 v[116:119], v[8:15], v[202:209], 0, v190, v190 op_sel_hi:[0,0,0]
	v_mfma_scale_f32_16x16x128_f8f6f4 v[112:115], v[0:7], v[202:209], 0, v190, v190 op_sel_hi:[0,0,0]
	v_mfma_scale_f32_16x16x128_f8f6f4 v[100:103], v[8:15], v[210:217], 0, v190, v190 op_sel_hi:[0,0,0]
	v_mfma_scale_f32_16x16x128_f8f6f4 v[96:99], v[0:7], v[210:217], 0, v190, v190 op_sel_hi:[0,0,0]
	s_setprio 0
	s_barrier
	s_add_i32 s70, s61, s34
	v_lshl_add_u64 v[176:177], s[46:47], 0, v[162:163]
	s_mov_b32 m0, s70
	ds_read_b128 v[194:197], v189 offset:16384
	ds_read_b128 v[198:201], v189 offset:17408
	ds_read_b128 v[202:205], v189 offset:18432
	ds_read_b128 v[206:209], v189 offset:19456
	ds_read_b128 v[210:213], v189 offset:20480
	ds_read_b128 v[214:217], v189 offset:21504
	ds_read_b128 v[218:221], v189 offset:22528
	ds_read_b128 v[222:225], v189 offset:23552
	global_load_lds_dwordx4 v[176:177], off
	s_add_i32 m0, s70, 0x2000
	s_add_u32 s70, s46, 0x40000
	v_lshl_add_u64 v[178:179], s[46:47], 0, v[166:167]
	s_addc_u32 s71, s47, 0
	s_add_i32 s72, s62, s34
	global_load_lds_dwordx4 v[178:179], off
	v_lshl_add_u64 v[180:181], s[70:71], 0, v[162:163]
	s_mov_b32 m0, s72
	v_lshl_add_u64 v[182:183], s[48:49], 0, v[164:165]
	global_load_lds_dwordx4 v[180:181], off
	v_lshl_add_u64 v[180:181], s[70:71], 0, v[166:167]
	s_add_i32 m0, s72, 0x2000
	s_nop 0
	global_load_lds_dwordx4 v[180:181], off
	v_lshl_add_u64 v[180:181], s[48:49], 0, v[160:161]
	s_mov_b32 m0, s35
	s_nop 0
	global_load_lds_dwordx4 v[180:181], off
	s_mov_b32 m0, s43
	s_nop 0
	global_load_lds_dwordx4 v[182:183], off
	s_waitcnt vmcnt(8)
	s_waitcnt lgkmcnt(0)
	s_barrier
	s_setprio 1
	s_waitcnt lgkmcnt(0)
	v_mfma_scale_f32_16x16x128_f8f6f4 v[92:95], v[24:31], v[194:201], 0, v190, v190 op_sel_hi:[0,0,0]
	v_mfma_scale_f32_16x16x128_f8f6f4 v[88:91], v[16:23], v[194:201], 0, v190, v190 op_sel_hi:[0,0,0]
	v_mfma_scale_f32_16x16x128_f8f6f4 v[76:79], v[24:31], v[202:209], 0, v190, v190 op_sel_hi:[0,0,0]
	v_mfma_scale_f32_16x16x128_f8f6f4 v[72:75], v[16:23], v[202:209], 0, v190, v190 op_sel_hi:[0,0,0]
	v_mfma_scale_f32_16x16x128_f8f6f4 v[60:63], v[24:31], v[210:217], 0, v190, v190 op_sel_hi:[0,0,0]
	v_mfma_scale_f32_16x16x128_f8f6f4 v[56:59], v[16:23], v[210:217], 0, v190, v190 op_sel_hi:[0,0,0]
	v_mfma_scale_f32_16x16x128_f8f6f4 v[44:47], v[24:31], v[218:225], 0, v190, v190 op_sel_hi:[0,0,0]
	v_mfma_scale_f32_16x16x128_f8f6f4 v[40:43], v[16:23], v[218:225], 0, v190, v190 op_sel_hi:[0,0,0]
	s_setprio 0
	s_setprio 1
	v_mfma_scale_f32_16x16x128_f8f6f4 v[84:87], v[8:15], v[194:201], 0, v190, v190 op_sel_hi:[0,0,0]
	v_mfma_scale_f32_16x16x128_f8f6f4 v[80:83], v[0:7], v[194:201], 0, v190, v190 op_sel_hi:[0,0,0]
	v_mfma_scale_f32_16x16x128_f8f6f4 v[68:71], v[8:15], v[202:209], 0, v190, v190 op_sel_hi:[0,0,0]
	v_mfma_scale_f32_16x16x128_f8f6f4 v[64:67], v[0:7], v[202:209], 0, v190, v190 op_sel_hi:[0,0,0]
	v_mfma_scale_f32_16x16x128_f8f6f4 v[52:55], v[8:15], v[210:217], 0, v190, v190 op_sel_hi:[0,0,0]
	v_mfma_scale_f32_16x16x128_f8f6f4 v[48:51], v[0:7], v[210:217], 0, v190, v190 op_sel_hi:[0,0,0]
	v_mfma_scale_f32_16x16x128_f8f6f4 v[36:39], v[8:15], v[218:225], 0, v190, v190 op_sel_hi:[0,0,0]
	v_mfma_scale_f32_16x16x128_f8f6f4 v[32:35], v[0:7], v[218:225], 0, v190, v190 op_sel_hi:[0,0,0]
	s_setprio 0
	s_barrier
; #define PG8_STAGE(bufoff, gbase, voff) do { _Pragma("unroll") for (int _i = 0; _i < 2; ++_i) \
;         __builtin_amdgcn_global_load_lds((const unsigned*)((const char*)(gbase) + (voff)[_i]), (LAS unsigned*)(lds + (bufoff) + ldsw + _i * 8192), 16, 0, 0); } while (0)
; #define PG8_LDA(dst, b, h) do { _Pragma("unroll") for (int m = 0; m < 4; ++m) _Pragma("unroll") for (int k = 0; k < 2; ++k) dst[m][k] = *(const LAS bf16x8*)(lds + PG8_SA(b, h) + aoff + m * 2048 + k * 1024); } while (0)
; #define PG8_LDB(dst, b, h) do { _Pragma("unroll") for (int n = 0; n < 2; ++n) _Pragma("unroll") for (int k = 0; k < 2; ++k) dst[n][k] = *(const LAS bf16x8*)(lds + PG8_SB(b, h) + boff + n * 2048 + k * 1024); } while (0)
; #define PG8_WAIT_V(n) asm volatile("s_waitcnt vmcnt(" #n ")" ::: "memory")
; #define PG8_WAIT_L(n) asm volatile("s_waitcnt lgkmcnt(" #n ")" ::: "memory")
; #define PG8_BAR __builtin_amdgcn_s_barrier()
; #define PG8_SCHED __builtin_amdgcn_sched_barrier(0)
;     ...
;             PG8_LDB(B0, 1, 0); PG8_LDB(B1, 1, 1); PG8_SCHED; PG8_LDA(At, 1, 0); PG8_STAGE(PG8_SA(0, 1), a2 + hstep, voffA);
;             PG8_WAIT_V(8); PG8_WAIT_L(0); PG8_BAR; PG8_MMA(0, 0, At, B0); PG8_MMA(0, 1, At, B1); PG8_BAR; PG8_SCHED;
;             PG8_LDA(At, 1, 1); PG8_STAGE(PG8_SB(1, 0), b3, voffB); PG8_STAGE(PG8_SB(1, 1), b3 + hstep, voffB); PG8_STAGE(PG8_SA(1, 0), a3, voffA);
;             PG8_WAIT_V(8); PG8_WAIT_L(0); PG8_BAR; PG8_MMA(1, 0, At, B0); PG8_MMA(1, 1, At, B1); PG8_BAR; PG8_SCHED;
;         }
	s_add_i32 s70, 0, 0x18000
	s_add_i32 s71, 0, 0x1c000
	v_add_u32_e32 v12, s70, v185
	v_add_u32_e32 v28, s71, v185
	ds_read_b128 v[0:3], v12
	ds_read_b128 v[4:7], v12 offset:1024
	ds_read_b128 v[8:11], v12 offset:2048
	ds_read_b128 v[12:15], v12 offset:3072
	ds_read_b128 v[16:19], v28
	ds_read_b128 v[20:23], v28 offset:1024
	ds_read_b128 v[24:27], v28 offset:2048
	ds_read_b128 v[28:31], v28 offset:3072
	s_add_u32 s48, s48, 0x40000
	s_addc_u32 s49, s49, 0
	s_mov_b32 m0, s50
	v_lshl_add_u64 v[226:227], s[48:49], 0, v[160:161]
	ds_read_b128 v[194:197], v189 offset:32768
	ds_read_b128 v[198:201], v189 offset:33792
	ds_read_b128 v[202:205], v189 offset:34816
	ds_read_b128 v[206:209], v189 offset:35840
	ds_read_b128 v[210:213], v189 offset:36864
	ds_read_b128 v[214:217], v189 offset:37888
	ds_read_b128 v[218:221], v189 offset:38912
	ds_read_b128 v[222:225], v189 offset:39936
	global_load_lds_dwordx4 v[226:227], off
	v_lshl_add_u64 v[226:227], s[48:49], 0, v[164:165]
	s_mov_b32 m0, s51
	s_nop 0
	global_load_lds_dwordx4 v[226:227], off
	s_waitcnt vmcnt(8)
	s_waitcnt lgkmcnt(0)
	s_barrier
	s_setprio 1
	s_waitcnt lgkmcnt(0)
	v_mfma_scale_f32_16x16x128_f8f6f4 v[156:159], v[0:7], v[194:201], v[156:159], v190, v190 op_sel_hi:[0,0,0]
	v_mfma_scale_f32_16x16x128_f8f6f4 v[152:155], v[8:15], v[194:201], v[152:155], v190, v190 op_sel_hi:[0,0,0]
	v_mfma_scale_f32_16x16x128_f8f6f4 v[140:143], v[0:7], v[202:209], v[140:143], v190, v190 op_sel_hi:[0,0,0]
	v_mfma_scale_f32_16x16x128_f8f6f4 v[136:139], v[8:15], v[202:209], v[136:139], v190, v190 op_sel_hi:[0,0,0]
	v_mfma_scale_f32_16x16x128_f8f6f4 v[124:127], v[0:7], v[210:217], v[124:127], v190, v190 op_sel_hi:[0,0,0]
	v_mfma_scale_f32_16x16x128_f8f6f4 v[120:123], v[8:15], v[210:217], v[120:123], v190, v190 op_sel_hi:[0,0,0]
	v_mfma_scale_f32_16x16x128_f8f6f4 v[108:111], v[0:7], v[218:225], v[108:111], v190, v190 op_sel_hi:[0,0,0]
	v_mfma_scale_f32_16x16x128_f8f6f4 v[104:107], v[8:15], v[218:225], v[104:107], v190, v190 op_sel_hi:[0,0,0]
	s_setprio 0
	s_setprio 1
	v_mfma_scale_f32_16x16x128_f8f6f4 v[148:151], v[16:23], v[194:201], v[148:151], v190, v190 op_sel_hi:[0,0,0]
	v_mfma_scale_f32_16x16x128_f8f6f4 v[144:147], v[24:31], v[194:201], v[144:147], v190, v190 op_sel_hi:[0,0,0]
	v_mfma_scale_f32_16x16x128_f8f6f4 v[132:135], v[16:23], v[202:209], v[132:135], v190, v190 op_sel_hi:[0,0,0]
	v_mfma_scale_f32_16x16x128_f8f6f4 v[128:131], v[24:31], v[202:209], v[128:131], v190, v190 op_sel_hi:[0,0,0]
	v_mfma_scale_f32_16x16x128_f8f6f4 v[116:119], v[16:23], v[210:217], v[116:119], v190, v190 op_sel_hi:[0,0,0]
	v_mfma_scale_f32_16x16x128_f8f6f4 v[112:115], v[24:31], v[210:217], v[112:115], v190, v190 op_sel_hi:[0,0,0]
	v_mfma_scale_f32_16x16x128_f8f6f4 v[100:103], v[16:23], v[218:225], v[100:103], v190, v190 op_sel_hi:[0,0,0]
	v_mfma_scale_f32_16x16x128_f8f6f4 v[96:99], v[24:31], v[218:225], v[96:99], v190, v190 op_sel_hi:[0,0,0]
	s_setprio 0
	s_barrier
	s_add_i32 s48, s70, s34
	v_lshl_add_u64 v[176:177], v[176:177], 0, s[16:17]
	s_mov_b32 m0, s48
	ds_read_b128 v[194:197], v189 offset:49152
	ds_read_b128 v[198:201], v189 offset:50176
	ds_read_b128 v[202:205], v189 offset:51200
	ds_read_b128 v[206:209], v189 offset:52224
	ds_read_b128 v[210:213], v189 offset:53248
	ds_read_b128 v[214:217], v189 offset:54272
	ds_read_b128 v[218:221], v189 offset:55296
	ds_read_b128 v[222:225], v189 offset:56320
	global_load_lds_dwordx4 v[176:177], off
	s_add_i32 m0, s48, 0x2000
	s_add_u32 s46, s46, 0x40080
	v_lshl_add_u64 v[176:177], v[178:179], 0, s[16:17]
	s_addc_u32 s47, s47, 0
	s_add_i32 s48, s71, s34
	global_load_lds_dwordx4 v[176:177], off
	v_lshl_add_u64 v[176:177], s[46:47], 0, v[162:163]
	s_mov_b32 m0, s48
	s_nop 0
	global_load_lds_dwordx4 v[176:177], off
	v_lshl_add_u64 v[176:177], s[46:47], 0, v[166:167]
	s_add_i32 m0, s48, 0x2000
	s_nop 0
	global_load_lds_dwordx4 v[176:177], off
	v_lshl_add_u64 v[176:177], v[180:181], 0, s[16:17]
	s_mov_b32 m0, s55
	s_nop 0
	global_load_lds_dwordx4 v[176:177], off
	v_lshl_add_u64 v[176:177], v[182:183], 0, s[16:17]
	s_mov_b32 m0, s58
	s_nop 0
	global_load_lds_dwordx4 v[176:177], off
	s_waitcnt vmcnt(8)
	s_waitcnt lgkmcnt(0)
	s_barrier
	s_setprio 1
	s_waitcnt lgkmcnt(0)
	v_mfma_scale_f32_16x16x128_f8f6f4 v[92:95], v[0:7], v[194:201], v[92:95], v190, v190 op_sel_hi:[0,0,0]
	v_mfma_scale_f32_16x16x128_f8f6f4 v[88:91], v[8:15], v[194:201], v[88:91], v190, v190 op_sel_hi:[0,0,0]
	v_mfma_scale_f32_16x16x128_f8f6f4 v[76:79], v[0:7], v[202:209], v[76:79], v190, v190 op_sel_hi:[0,0,0]
	v_mfma_scale_f32_16x16x128_f8f6f4 v[72:75], v[8:15], v[202:209], v[72:75], v190, v190 op_sel_hi:[0,0,0]
	v_mfma_scale_f32_16x16x128_f8f6f4 v[60:63], v[0:7], v[210:217], v[60:63], v190, v190 op_sel_hi:[0,0,0]
	v_mfma_scale_f32_16x16x128_f8f6f4 v[56:59], v[8:15], v[210:217], v[56:59], v190, v190 op_sel_hi:[0,0,0]
	v_mfma_scale_f32_16x16x128_f8f6f4 v[44:47], v[0:7], v[218:225], v[44:47], v190, v190 op_sel_hi:[0,0,0]
	v_mfma_scale_f32_16x16x128_f8f6f4 v[40:43], v[8:15], v[218:225], v[40:43], v190, v190 op_sel_hi:[0,0,0]
	s_setprio 0
	s_setprio 1
	v_mfma_scale_f32_16x16x128_f8f6f4 v[84:87], v[16:23], v[194:201], v[84:87], v190, v190 op_sel_hi:[0,0,0]
	v_mfma_scale_f32_16x16x128_f8f6f4 v[80:83], v[24:31], v[194:201], v[80:83], v190, v190 op_sel_hi:[0,0,0]
	v_mfma_scale_f32_16x16x128_f8f6f4 v[68:71], v[16:23], v[202:209], v[68:71], v190, v190 op_sel_hi:[0,0,0]
	v_mfma_scale_f32_16x16x128_f8f6f4 v[64:67], v[24:31], v[202:209], v[64:67], v190, v190 op_sel_hi:[0,0,0]
	v_mfma_scale_f32_16x16x128_f8f6f4 v[52:55], v[16:23], v[210:217], v[52:55], v190, v190 op_sel_hi:[0,0,0]
	v_mfma_scale_f32_16x16x128_f8f6f4 v[48:51], v[24:31], v[210:217], v[48:51], v190, v190 op_sel_hi:[0,0,0]
	v_mfma_scale_f32_16x16x128_f8f6f4 v[36:39], v[16:23], v[218:225], v[36:39], v190, v190 op_sel_hi:[0,0,0]
	v_mfma_scale_f32_16x16x128_f8f6f4 v[32:35], v[24:31], v[218:225], v[32:35], v190, v190 op_sel_hi:[0,0,0]
	s_setprio 0
	s_barrier
	s_add_i32 s69, s69, 2
	s_add_u32 s44, s44, 0x100
	s_addc_u32 s45, s45, 0
	s_add_u32 s67, s67, 0x100
	s_addc_u32 s68, s68, 0
	s_cmp_gt_u32 s69, 13
	s_cbranch_scc0 .LBB0_3686

; #define PG8_STAGE(bufoff, gbase, voff) do { _Pragma("unroll") for (int _i = 0; _i < 2; ++_i) \
;         __builtin_amdgcn_global_load_lds((const unsigned*)((const char*)(gbase) + (voff)[_i]), (LAS unsigned*)(lds + (bufoff) + ldsw + _i * 8192), 16, 0, 0); } while (0)
; #define PG8_LDA(dst, b, h) do { _Pragma("unroll") for (int m = 0; m < 4; ++m) _Pragma("unroll") for (int k = 0; k < 2; ++k) dst[m][k] = *(const LAS bf16x8*)(lds + PG8_SA(b, h) + aoff + m * 2048 + k * 1024); } while (0)
; #define PG8_LDB(dst, b, h) do { _Pragma("unroll") for (int n = 0; n < 2; ++n) _Pragma("unroll") for (int k = 0; k < 2; ++k) dst[n][k] = *(const LAS bf16x8*)(lds + PG8_SB(b, h) + boff + n * 2048 + k * 1024); } while (0)
; #define PG8_WAIT_V(n) asm volatile("s_waitcnt vmcnt(" #n ")" ::: "memory")
; #define PG8_WAIT_L(n) asm volatile("s_waitcnt lgkmcnt(" #n ")" ::: "memory")
;     __device__ __forceinline__ bool next(int i, Unit& u) const {
;         const long L = (long)i * G + c; if (L >= nwg) return false;
;         int wgid = (int)L; { const int q = nwg / NXCD, r = nwg % NXCD, xcd = wgid % NXCD, off = wgid / NXCD; wgid = (xcd < r ? xcd * (q + 1) : r * (q + 1) + (xcd - r) * q) + off; }
;         const int nig = WGM * nN, gid = wgid / nig, fm = gid * WGM, gsz = (nM - fm) < WGM ? (nM - fm) : WGM;
;         u.pm = fm + ((wgid % nig) % gsz); u.pn = (wgid % nig) / gsz; u.e = 0; u.kt0 = 0; u.nkt = nt; u.buf = 0;
;     ...
;     for (;;) {
;         const bool has_next = S.next(ui + 1, nxt);
;         const char* nA = has_next ? (const char*)g.A + (size_t)nxt.pm * tstep + (size_t)nxt.kt0 * kstep : cA; const char* nB = has_next ? (const char*)g.Bt + (size_t)nxt.e * g.estride + (size_t)nxt.pn * tstep + (size_t)nxt.kt0 * kstep : cB;
;         const int nt = cur.nkt;
;         for (int t = 0; t < nt; t += 2) {
;             const bool last = (t == nt - 2);
;             const char* a1 = cA + (size_t)(t + 1) * kstep;
;             const char* a2 = last ? nA : cA + (size_t)(t + 2) * kstep; const char* b2 = last ? nB : cB + (size_t)(t + 2) * kstep;
;             const char* a3 = a2 + kstep; const char* b3 = b2 + kstep;
;             PG8_LDB(B0, 0, 0); PG8_LDB(B1, 0, 1); PG8_SCHED; PG8_LDA(At, 0, 0); PG8_STAGE(PG8_SA(1, 1), a1 + hstep, voffA);
;             PG8_WAIT_V(8); PG8_WAIT_L(0); PG8_BAR; PG8_MMA(0, 0, At, B0); PG8_MMA(0, 1, At, B1); PG8_BAR; PG8_SCHED;
.LBB0_3773:
	ds_read_b128 v[84:87], v169
	ds_read_b128 v[88:91], v169 offset:1024
	ds_read_b128 v[96:99], v169 offset:2048
	ds_read_b128 v[100:103], v169 offset:3072
	ds_read_b128 v[160:163], v170
	ds_read_b128 v[174:177], v170 offset:1024
	ds_read_b128 v[178:181], v170 offset:2048
	ds_read_b128 v[182:185], v170 offset:3072
	ds_read_b128 v[186:189], v171
	ds_read_b128 v[190:193], v171 offset:1024
	ds_read_b128 v[194:197], v171 offset:2048
	ds_read_b128 v[198:201], v171 offset:3072
	ds_read_b128 v[202:205], v171 offset:4096
	ds_read_b128 v[206:209], v171 offset:5120
	ds_read_b128 v[210:213], v171 offset:6144
	ds_read_b128 v[214:217], v171 offset:7168
	s_add_i32 s51, s51, 1
	s_mul_i32 s2, s51, s58
	s_mul_hi_u32 s3, s51, s33
	s_add_i32 s3, s3, s2
	s_mul_i32 s2, s51, s33
	s_add_u32 s36, s2, s22
	s_addc_u32 s37, s3, s35
	v_cmp_gt_i64_e32 vcc, s[36:37], v[158:159]
	v_cmp_lt_i64_e64 s[2:3], s[36:37], v[156:157]
	s_cbranch_vccnz .LBB0_3775
	s_ashr_i32 s28, s36, 31
	s_lshr_b32 s28, s28, 29
	s_add_i32 s28, s36, s28
	s_ashr_i32 s29, s28, 3
	s_and_b32 s28, s28, -8
	s_sub_i32 s28, s36, s28
	s_cmp_lt_i32 s28, 0
	s_cselect_b32 s30, s46, 0x160
	s_mul_i32 s28, s28, s30
	s_add_i32 s28, s28, s29
	s_mul_hi_i32 s29, s28, 0x2e8ba2e9
	s_lshr_b32 s30, s29, 31
	s_ashr_i32 s29, s29, 6
	s_add_i32 s29, s29, s30
	s_lshl_b32 s30, s29, 3
	s_sub_i32 s31, 64, s30
	s_min_i32 s31, s31, 8
	s_abs_i32 s36, s31
	v_cvt_f32_u32_e32 v0, s36
	s_sub_i32 s38, 0, s36
	s_mulk_i32 s29, 0x160
	s_sub_i32 s29, s28, s29
	v_rcp_iflag_f32_e32 v0, v0
	s_abs_i32 s28, s29
	s_xor_b32 s37, s29, s31
	s_ashr_i32 s37, s37, 31
	v_mul_f32_e32 v0, 0x4f7ffffe, v0
	v_cvt_u32_f32_e32 v0, v0
	s_nop 0
	v_readfirstlane_b32 s39, v0
	s_mul_i32 s38, s38, s39
	s_mul_hi_u32 s38, s39, s38
	s_add_i32 s39, s39, s38
	s_mul_hi_u32 s38, s28, s39
	s_mul_i32 s39, s38, s36
	s_sub_i32 s28, s28, s39
	s_add_i32 s44, s38, 1
	s_sub_i32 s39, s28, s36
	s_cmp_ge_u32 s28, s36
	s_cselect_b32 s38, s44, s38
	s_cselect_b32 s28, s39, s28
	s_add_i32 s39, s38, 1
	s_cmp_ge_u32 s28, s36
	s_cselect_b32 s28, s39, s38
	s_xor_b32 s28, s28, s37
	s_sub_i32 s28, s28, s37
	s_mul_i32 s31, s28, s31
	s_sub_i32 s29, s29, s31
	s_add_i32 s30, s30, s29
.LBB0_3775:
	s_ashr_i32 s31, s30, 31
	s_lshl_b64 s[36:37], s[30:31], 19
	s_add_u32 s36, s21, s36
	s_addc_u32 s37, s23, s37
	s_and_b64 s[38:39], s[2:3], exec
	s_cselect_b32 s31, s37, s41
	s_cselect_b32 s64, s36, s40
	s_ashr_i32 s29, s28, 31
	s_lshl_b64 s[38:39], s[28:29], 19
	s_add_u32 s38, s25, s38
	s_addc_u32 s39, s27, s39
	s_and_b64 s[44:45], s[2:3], exec
	s_cselect_b32 s29, s39, s43
	s_cselect_b32 s65, s38, s42
	s_add_u32 s40, s40, 0x40080
	s_addc_u32 s41, s41, 0
	s_add_u32 s66, s42, 0x100
	s_addc_u32 s67, s43, 0
	s_mov_b32 s68, -2
	s_add_u32 s42, s40, 0xfffc0080
	s_addc_u32 s43, s41, -1
	s_cmp_eq_u32 s68, 12
	s_cselect_b32 s45, s31, s43
	s_cselect_b32 s44, s64, s42
	s_cselect_b32 s43, s29, s67
	s_cselect_b32 s42, s65, s66
	v_lshl_add_u64 v[164:165], s[40:41], 0, v[152:153]
	s_add_i32 m0, s47, 0xc000
	global_load_lds_dwordx4 v[164:165], off
	v_lshl_add_u64 v[164:165], s[40:41], 0, v[154:155]
	s_add_i32 m0, s47, 0xe000
	s_nop 0
	global_load_lds_dwordx4 v[164:165], off
	s_waitcnt vmcnt(8)
	s_waitcnt lgkmcnt(0)
	s_barrier
	s_setprio 1
	s_waitcnt lgkmcnt(0)
	v_mfma_i32_16x16x64_i8 v[140:143], v[84:87], v[186:189], 0
	v_mfma_i32_16x16x64_i8 v[136:139], v[96:99], v[186:189], 0
	v_mfma_i32_16x16x64_i8 v[124:127], v[84:87], v[194:197], 0
	v_mfma_i32_16x16x64_i8 v[120:123], v[96:99], v[194:197], 0
	v_mfma_i32_16x16x64_i8 v[108:111], v[84:87], v[202:205], 0
	v_mfma_i32_16x16x64_i8 v[104:107], v[96:99], v[202:205], 0
	v_mfma_i32_16x16x64_i8 v[76:79], v[84:87], v[210:213], 0
	v_mfma_i32_16x16x64_i8 v[72:75], v[96:99], v[210:213], 0
	v_mfma_i32_16x16x64_i8 v[140:143], v[88:91], v[190:193], v[140:143]
	v_mfma_i32_16x16x64_i8 v[136:139], v[100:103], v[190:193], v[136:139]
	v_mfma_i32_16x16x64_i8 v[124:127], v[88:91], v[198:201], v[124:127]
	v_mfma_i32_16x16x64_i8 v[120:123], v[100:103], v[198:201], v[120:123]
	v_mfma_i32_16x16x64_i8 v[108:111], v[88:91], v[206:209], v[108:111]
	v_mfma_i32_16x16x64_i8 v[104:107], v[100:103], v[206:209], v[104:107]
	v_mfma_i32_16x16x64_i8 v[76:79], v[88:91], v[214:217], v[76:79]
	v_mfma_i32_16x16x64_i8 v[72:75], v[100:103], v[214:217], v[72:75]
	s_setprio 0
	s_setprio 1
	v_mfma_i32_16x16x64_i8 v[132:135], v[160:163], v[186:189], 0
	v_mfma_i32_16x16x64_i8 v[128:131], v[178:181], v[186:189], 0
	v_mfma_i32_16x16x64_i8 v[116:119], v[160:163], v[194:197], 0
	v_mfma_i32_16x16x64_i8 v[112:115], v[178:181], v[194:197], 0
	v_mfma_i32_16x16x64_i8 v[92:95], v[160:163], v[202:205], 0
	v_mfma_i32_16x16x64_i8 v[80:83], v[178:181], v[202:205], 0
	v_mfma_i32_16x16x64_i8 v[68:71], v[160:163], v[210:213], 0
	v_mfma_i32_16x16x64_i8 v[64:67], v[178:181], v[210:213], 0
	v_mfma_i32_16x16x64_i8 v[132:135], v[174:177], v[190:193], v[132:135]
	v_mfma_i32_16x16x64_i8 v[128:131], v[182:185], v[190:193], v[128:131]
	v_mfma_i32_16x16x64_i8 v[116:119], v[174:177], v[198:201], v[116:119]
	v_mfma_i32_16x16x64_i8 v[112:115], v[182:185], v[198:201], v[112:115]
	v_mfma_i32_16x16x64_i8 v[92:95], v[174:177], v[206:209], v[92:95]
	v_mfma_i32_16x16x64_i8 v[80:83], v[182:185], v[206:209], v[80:83]
	v_mfma_i32_16x16x64_i8 v[68:71], v[174:177], v[214:217], v[68:71]
	v_mfma_i32_16x16x64_i8 v[64:67], v[182:185], v[214:217], v[64:67]
	s_setprio 0
	s_barrier
; #define PG8_STAGE(bufoff, gbase, voff) do { _Pragma("unroll") for (int _i = 0; _i < 2; ++_i) \
;         __builtin_amdgcn_global_load_lds((const unsigned*)((const char*)(gbase) + (voff)[_i]), (LAS unsigned*)(lds + (bufoff) + ldsw + _i * 8192), 16, 0, 0); } while (0)
; #define PG8_LDA(dst, b, h) do { _Pragma("unroll") for (int m = 0; m < 4; ++m) _Pragma("unroll") for (int k = 0; k < 2; ++k) dst[m][k] = *(const LAS bf16x8*)(lds + PG8_SA(b, h) + aoff + m * 2048 + k * 1024); } while (0)
; #define PG8_LDB(dst, b, h) do { _Pragma("unroll") for (int n = 0; n < 2; ++n) _Pragma("unroll") for (int k = 0; k < 2; ++k) dst[n][k] = *(const LAS bf16x8*)(lds + PG8_SB(b, h) + boff + n * 2048 + k * 1024); } while (0)
; #define PG8_WAIT_V(n) asm volatile("s_waitcnt vmcnt(" #n ")" ::: "memory")
; #define PG8_WAIT_L(n) asm volatile("s_waitcnt lgkmcnt(" #n ")" ::: "memory")
; #define PG8_BAR __builtin_amdgcn_s_barrier()
; #define PG8_SCHED __builtin_amdgcn_sched_barrier(0)
;     ...
;             PG8_LDA(At, 0, 1); PG8_STAGE(PG8_SB(0, 0), b2, voffB); PG8_STAGE(PG8_SB(0, 1), b2 + hstep, voffB); PG8_STAGE(PG8_SA(0, 0), a2, voffA);
;             PG8_WAIT_V(8); PG8_WAIT_L(0); PG8_BAR; PG8_MMA(1, 0, At, B0); PG8_MMA(1, 1, At, B1); PG8_BAR; PG8_SCHED;
;             PG8_LDB(B0, 1, 0); PG8_LDB(B1, 1, 1); PG8_SCHED; PG8_LDA(At, 1, 0); PG8_STAGE(PG8_SA(0, 1), a2 + hstep, voffA);
;             PG8_WAIT_V(8); PG8_WAIT_L(0); PG8_BAR; PG8_MMA(0, 0, At, B0); PG8_MMA(0, 1, At, B1); PG8_BAR; PG8_SCHED;
	s_add_i32 s69, s59, s34
	v_lshl_add_u64 v[164:165], s[42:43], 0, v[148:149]
	s_mov_b32 m0, s69
	ds_read_b128 v[186:189], v171 offset:16384
	ds_read_b128 v[190:193], v171 offset:17408
	ds_read_b128 v[194:197], v171 offset:18432
	ds_read_b128 v[198:201], v171 offset:19456
	ds_read_b128 v[202:205], v171 offset:20480
	ds_read_b128 v[206:209], v171 offset:21504
	ds_read_b128 v[210:213], v171 offset:22528
	ds_read_b128 v[214:217], v171 offset:23552
	global_load_lds_dwordx4 v[164:165], off
	s_add_i32 m0, s69, 0x2000
	s_add_u32 s70, s42, 0x40000
	v_lshl_add_u64 v[218:219], s[42:43], 0, v[144:145]
	s_addc_u32 s71, s43, 0
	s_add_i32 s69, s60, s34
	global_load_lds_dwordx4 v[218:219], off
	v_lshl_add_u64 v[220:221], s[70:71], 0, v[148:149]
	s_mov_b32 m0, s69
	v_lshl_add_u64 v[222:223], s[44:45], 0, v[146:147]
	global_load_lds_dwordx4 v[220:221], off
	v_lshl_add_u64 v[220:221], s[70:71], 0, v[144:145]
	s_add_i32 m0, s69, 0x2000
	s_nop 0
	global_load_lds_dwordx4 v[220:221], off
	v_lshl_add_u64 v[220:221], s[44:45], 0, v[150:151]
	s_mov_b32 m0, s47
	s_nop 0
	global_load_lds_dwordx4 v[220:221], off
	s_mov_b32 m0, s48
	s_nop 0
	global_load_lds_dwordx4 v[222:223], off
	s_waitcnt vmcnt(8)
	s_waitcnt lgkmcnt(0)
	s_barrier
	s_setprio 1
	s_waitcnt lgkmcnt(0)
	v_mfma_i32_16x16x64_i8 v[60:63], v[84:87], v[186:189], 0
	v_mfma_i32_16x16x64_i8 v[56:59], v[96:99], v[186:189], 0
	v_mfma_i32_16x16x64_i8 v[44:47], v[84:87], v[194:197], 0
	v_mfma_i32_16x16x64_i8 v[40:43], v[96:99], v[194:197], 0
	v_mfma_i32_16x16x64_i8 v[28:31], v[84:87], v[202:205], 0
	v_mfma_i32_16x16x64_i8 v[24:27], v[96:99], v[202:205], 0
	v_mfma_i32_16x16x64_i8 v[12:15], v[84:87], v[210:213], 0
	v_mfma_i32_16x16x64_i8 v[8:11], v[96:99], v[210:213], 0
	v_mfma_i32_16x16x64_i8 v[60:63], v[88:91], v[190:193], v[60:63]
	v_mfma_i32_16x16x64_i8 v[56:59], v[100:103], v[190:193], v[56:59]
	v_mfma_i32_16x16x64_i8 v[44:47], v[88:91], v[198:201], v[44:47]
	v_mfma_i32_16x16x64_i8 v[40:43], v[100:103], v[198:201], v[40:43]
	v_mfma_i32_16x16x64_i8 v[28:31], v[88:91], v[206:209], v[28:31]
	v_mfma_i32_16x16x64_i8 v[24:27], v[100:103], v[206:209], v[24:27]
	v_mfma_i32_16x16x64_i8 v[12:15], v[88:91], v[214:217], v[12:15]
	v_mfma_i32_16x16x64_i8 v[8:11], v[100:103], v[214:217], v[8:11]
	s_setprio 0
	s_setprio 1
	v_mfma_i32_16x16x64_i8 v[52:55], v[160:163], v[186:189], 0
	v_mfma_i32_16x16x64_i8 v[48:51], v[178:181], v[186:189], 0
	v_mfma_i32_16x16x64_i8 v[36:39], v[160:163], v[194:197], 0
	v_mfma_i32_16x16x64_i8 v[32:35], v[178:181], v[194:197], 0
	v_mfma_i32_16x16x64_i8 v[20:23], v[160:163], v[202:205], 0
	v_mfma_i32_16x16x64_i8 v[16:19], v[178:181], v[202:205], 0
	v_mfma_i32_16x16x64_i8 v[4:7], v[160:163], v[210:213], 0
	v_mfma_i32_16x16x64_i8 v[0:3], v[178:181], v[210:213], 0
	v_mfma_i32_16x16x64_i8 v[52:55], v[174:177], v[190:193], v[52:55]
	v_mfma_i32_16x16x64_i8 v[48:51], v[182:185], v[190:193], v[48:51]
	v_mfma_i32_16x16x64_i8 v[36:39], v[174:177], v[198:201], v[36:39]
	v_mfma_i32_16x16x64_i8 v[32:35], v[182:185], v[198:201], v[32:35]
	v_mfma_i32_16x16x64_i8 v[20:23], v[174:177], v[206:209], v[20:23]
	v_mfma_i32_16x16x64_i8 v[16:19], v[182:185], v[206:209], v[16:19]
	v_mfma_i32_16x16x64_i8 v[4:7], v[174:177], v[214:217], v[4:7]
	v_mfma_i32_16x16x64_i8 v[0:3], v[182:185], v[214:217], v[0:3]
	s_setprio 0
	s_barrier
	s_add_i32 s69, 0, 0x18000
	s_add_i32 s70, 0, 0x1c000
	v_add_u32_e32 v100, s69, v167
	v_add_u32_e32 v182, s70, v167
	ds_read_b128 v[84:87], v100
	ds_read_b128 v[88:91], v100 offset:1024
	ds_read_b128 v[96:99], v100 offset:2048
	ds_read_b128 v[100:103], v100 offset:3072
	ds_read_b128 v[160:163], v182
	ds_read_b128 v[174:177], v182 offset:1024
	ds_read_b128 v[178:181], v182 offset:2048
	ds_read_b128 v[182:185], v182 offset:3072
	s_add_u32 s44, s44, 0x40000
	s_addc_u32 s45, s45, 0
	s_mov_b32 m0, s49
	v_lshl_add_u64 v[224:225], s[44:45], 0, v[150:151]
	ds_read_b128 v[186:189], v171 offset:32768
	ds_read_b128 v[190:193], v171 offset:33792
	ds_read_b128 v[194:197], v171 offset:34816
	ds_read_b128 v[198:201], v171 offset:35840
	ds_read_b128 v[202:205], v171 offset:36864
	ds_read_b128 v[206:209], v171 offset:37888
	ds_read_b128 v[210:213], v171 offset:38912
	ds_read_b128 v[214:217], v171 offset:39936
	global_load_lds_dwordx4 v[224:225], off
	v_lshl_add_u64 v[224:225], s[44:45], 0, v[146:147]
	s_mov_b32 m0, s50
	s_nop 0
	global_load_lds_dwordx4 v[224:225], off
	s_waitcnt vmcnt(8)
	s_waitcnt lgkmcnt(0)
	s_barrier
; #define PG8_STAGE(bufoff, gbase, voff) do { _Pragma("unroll") for (int _i = 0; _i < 2; ++_i) \
;         __builtin_amdgcn_global_load_lds((const unsigned*)((const char*)(gbase) + (voff)[_i]), (LAS unsigned*)(lds + (bufoff) + ldsw + _i * 8192), 16, 0, 0); } while (0)
; #define PG8_LDA(dst, b, h) do { _Pragma("unroll") for (int m = 0; m < 4; ++m) _Pragma("unroll") for (int k = 0; k < 2; ++k) dst[m][k] = *(const LAS bf16x8*)(lds + PG8_SA(b, h) + aoff + m * 2048 + k * 1024); } while (0)
; #define PG8_WAIT_V(n) asm volatile("s_waitcnt vmcnt(" #n ")" ::: "memory")
; #define PG8_WAIT_L(n) asm volatile("s_waitcnt lgkmcnt(" #n ")" ::: "memory")
; #define PG8_BAR __builtin_amdgcn_s_barrier()
; #define PG8_SCHED __builtin_amdgcn_sched_barrier(0)
;     ...
;             PG8_WAIT_V(8); PG8_WAIT_L(0); PG8_BAR; PG8_MMA(0, 0, At, B0); PG8_MMA(0, 1, At, B1); PG8_BAR; PG8_SCHED;
;             PG8_LDA(At, 1, 1); PG8_STAGE(PG8_SB(1, 0), b3, voffB); PG8_STAGE(PG8_SB(1, 1), b3 + hstep, voffB); PG8_STAGE(PG8_SA(1, 0), a3, voffA);
;             PG8_WAIT_V(8); PG8_WAIT_L(0); PG8_BAR; PG8_MMA(1, 0, At, B0); PG8_MMA(1, 1, At, B1); PG8_BAR; PG8_SCHED;
;         }
	s_setprio 1
	s_waitcnt lgkmcnt(0)
	v_mfma_i32_16x16x64_i8 v[140:143], v[84:87], v[186:189], v[140:143]
	v_mfma_i32_16x16x64_i8 v[136:139], v[96:99], v[186:189], v[136:139]
	v_mfma_i32_16x16x64_i8 v[124:127], v[84:87], v[194:197], v[124:127]
	v_mfma_i32_16x16x64_i8 v[120:123], v[96:99], v[194:197], v[120:123]
	v_mfma_i32_16x16x64_i8 v[108:111], v[84:87], v[202:205], v[108:111]
	v_mfma_i32_16x16x64_i8 v[104:107], v[96:99], v[202:205], v[104:107]
	v_mfma_i32_16x16x64_i8 v[76:79], v[84:87], v[210:213], v[76:79]
	v_mfma_i32_16x16x64_i8 v[72:75], v[96:99], v[210:213], v[72:75]
	v_mfma_i32_16x16x64_i8 v[140:143], v[88:91], v[190:193], v[140:143]
	v_mfma_i32_16x16x64_i8 v[136:139], v[100:103], v[190:193], v[136:139]
	v_mfma_i32_16x16x64_i8 v[124:127], v[88:91], v[198:201], v[124:127]
	v_mfma_i32_16x16x64_i8 v[120:123], v[100:103], v[198:201], v[120:123]
	v_mfma_i32_16x16x64_i8 v[108:111], v[88:91], v[206:209], v[108:111]
	v_mfma_i32_16x16x64_i8 v[104:107], v[100:103], v[206:209], v[104:107]
	v_mfma_i32_16x16x64_i8 v[76:79], v[88:91], v[214:217], v[76:79]
	v_mfma_i32_16x16x64_i8 v[72:75], v[100:103], v[214:217], v[72:75]
	s_setprio 0
	s_setprio 1
	v_mfma_i32_16x16x64_i8 v[132:135], v[160:163], v[186:189], v[132:135]
	v_mfma_i32_16x16x64_i8 v[128:131], v[178:181], v[186:189], v[128:131]
	v_mfma_i32_16x16x64_i8 v[116:119], v[160:163], v[194:197], v[116:119]
	v_mfma_i32_16x16x64_i8 v[112:115], v[178:181], v[194:197], v[112:115]
	v_mfma_i32_16x16x64_i8 v[92:95], v[160:163], v[202:205], v[92:95]
	v_mfma_i32_16x16x64_i8 v[80:83], v[178:181], v[202:205], v[80:83]
	v_mfma_i32_16x16x64_i8 v[68:71], v[160:163], v[210:213], v[68:71]
	v_mfma_i32_16x16x64_i8 v[64:67], v[178:181], v[210:213], v[64:67]
	v_mfma_i32_16x16x64_i8 v[132:135], v[174:177], v[190:193], v[132:135]
	v_mfma_i32_16x16x64_i8 v[128:131], v[182:185], v[190:193], v[128:131]
	v_mfma_i32_16x16x64_i8 v[116:119], v[174:177], v[198:201], v[116:119]
	v_mfma_i32_16x16x64_i8 v[112:115], v[182:185], v[198:201], v[112:115]
	v_mfma_i32_16x16x64_i8 v[92:95], v[174:177], v[206:209], v[92:95]
	v_mfma_i32_16x16x64_i8 v[80:83], v[182:185], v[206:209], v[80:83]
	v_mfma_i32_16x16x64_i8 v[68:71], v[174:177], v[214:217], v[68:71]
	v_mfma_i32_16x16x64_i8 v[64:67], v[182:185], v[214:217], v[64:67]
	s_setprio 0
	s_barrier
	s_add_i32 s44, s69, s34
	v_lshl_add_u64 v[164:165], v[164:165], 0, s[16:17]
	s_mov_b32 m0, s44
	ds_read_b128 v[186:189], v171 offset:49152
	ds_read_b128 v[190:193], v171 offset:50176
	ds_read_b128 v[194:197], v171 offset:51200
	ds_read_b128 v[198:201], v171 offset:52224
	ds_read_b128 v[202:205], v171 offset:53248
	ds_read_b128 v[206:209], v171 offset:54272
	ds_read_b128 v[210:213], v171 offset:55296
	ds_read_b128 v[214:217], v171 offset:56320
	global_load_lds_dwordx4 v[164:165], off
	s_add_i32 m0, s44, 0x2000
	s_add_u32 s42, s42, 0x40080
	v_lshl_add_u64 v[164:165], v[218:219], 0, s[16:17]
	s_addc_u32 s43, s43, 0
	s_add_i32 s44, s70, s34
	global_load_lds_dwordx4 v[164:165], off
	v_lshl_add_u64 v[164:165], s[42:43], 0, v[148:149]
	s_mov_b32 m0, s44
	s_nop 0
	global_load_lds_dwordx4 v[164:165], off
	v_lshl_add_u64 v[164:165], s[42:43], 0, v[144:145]
	s_add_i32 m0, s44, 0x2000
	s_nop 0
	global_load_lds_dwordx4 v[164:165], off
	v_lshl_add_u64 v[164:165], v[220:221], 0, s[16:17]
	s_mov_b32 m0, s54
	s_nop 0
	global_load_lds_dwordx4 v[164:165], off
	v_lshl_add_u64 v[164:165], v[222:223], 0, s[16:17]
	s_mov_b32 m0, s55
	s_nop 0
	global_load_lds_dwordx4 v[164:165], off
	s_waitcnt vmcnt(8)
	s_waitcnt lgkmcnt(0)
	s_barrier
	s_setprio 1
	s_waitcnt lgkmcnt(0)
	v_mfma_i32_16x16x64_i8 v[60:63], v[84:87], v[186:189], v[60:63]
	v_mfma_i32_16x16x64_i8 v[56:59], v[96:99], v[186:189], v[56:59]
	v_mfma_i32_16x16x64_i8 v[44:47], v[84:87], v[194:197], v[44:47]
	v_mfma_i32_16x16x64_i8 v[40:43], v[96:99], v[194:197], v[40:43]
	v_mfma_i32_16x16x64_i8 v[28:31], v[84:87], v[202:205], v[28:31]
	v_mfma_i32_16x16x64_i8 v[24:27], v[96:99], v[202:205], v[24:27]
	v_mfma_i32_16x16x64_i8 v[12:15], v[84:87], v[210:213], v[12:15]
	v_mfma_i32_16x16x64_i8 v[8:11], v[96:99], v[210:213], v[8:11]
	v_mfma_i32_16x16x64_i8 v[60:63], v[88:91], v[190:193], v[60:63]
	v_mfma_i32_16x16x64_i8 v[56:59], v[100:103], v[190:193], v[56:59]
	v_mfma_i32_16x16x64_i8 v[44:47], v[88:91], v[198:201], v[44:47]
	v_mfma_i32_16x16x64_i8 v[40:43], v[100:103], v[198:201], v[40:43]
	v_mfma_i32_16x16x64_i8 v[28:31], v[88:91], v[206:209], v[28:31]
	v_mfma_i32_16x16x64_i8 v[24:27], v[100:103], v[206:209], v[24:27]
	v_mfma_i32_16x16x64_i8 v[12:15], v[88:91], v[214:217], v[12:15]
	v_mfma_i32_16x16x64_i8 v[8:11], v[100:103], v[214:217], v[8:11]
	s_setprio 0
	s_setprio 1
	v_mfma_i32_16x16x64_i8 v[52:55], v[160:163], v[186:189], v[52:55]
	v_mfma_i32_16x16x64_i8 v[48:51], v[178:181], v[186:189], v[48:51]
	v_mfma_i32_16x16x64_i8 v[36:39], v[160:163], v[194:197], v[36:39]
	v_mfma_i32_16x16x64_i8 v[32:35], v[178:181], v[194:197], v[32:35]
	v_mfma_i32_16x16x64_i8 v[20:23], v[160:163], v[202:205], v[20:23]
	v_mfma_i32_16x16x64_i8 v[16:19], v[178:181], v[202:205], v[16:19]
	v_mfma_i32_16x16x64_i8 v[4:7], v[160:163], v[210:213], v[4:7]
	v_mfma_i32_16x16x64_i8 v[0:3], v[178:181], v[210:213], v[0:3]
	v_mfma_i32_16x16x64_i8 v[52:55], v[174:177], v[190:193], v[52:55]
	v_mfma_i32_16x16x64_i8 v[48:51], v[182:185], v[190:193], v[48:51]
	v_mfma_i32_16x16x64_i8 v[36:39], v[174:177], v[198:201], v[36:39]
	v_mfma_i32_16x16x64_i8 v[32:35], v[182:185], v[198:201], v[32:35]
	v_mfma_i32_16x16x64_i8 v[20:23], v[174:177], v[206:209], v[20:23]
	v_mfma_i32_16x16x64_i8 v[16:19], v[182:185], v[206:209], v[16:19]
	v_mfma_i32_16x16x64_i8 v[4:7], v[174:177], v[214:217], v[4:7]
	v_mfma_i32_16x16x64_i8 v[0:3], v[182:185], v[214:217], v[0:3]
	s_setprio 0
	s_barrier
	s_add_i32 s68, s68, 2
	s_add_u32 s40, s40, 0x100
	s_addc_u32 s41, s41, 0
	s_add_u32 s66, s66, 0x100
	s_addc_u32 s67, s67, 0
	s_cmp_gt_u32 s68, 13
	s_cbranch_scc0 .LBB0_3776

; #define PG8_STAGE(bufoff, gbase, voff) do { _Pragma("unroll") for (int _i = 0; _i < 2; ++_i) \
;         __builtin_amdgcn_global_load_lds((const unsigned*)((const char*)(gbase) + (voff)[_i]), (LAS unsigned*)(lds + (bufoff) + ldsw + _i * 8192), 16, 0, 0); } while (0)
; #define PG8_LDA(dst, b, h) do { _Pragma("unroll") for (int m = 0; m < 4; ++m) _Pragma("unroll") for (int k = 0; k < 2; ++k) dst[m][k] = *(const LAS bf16x8*)(lds + PG8_SA(b, h) + aoff + m * 2048 + k * 1024); } while (0)
; #define PG8_LDB(dst, b, h) do { _Pragma("unroll") for (int n = 0; n < 2; ++n) _Pragma("unroll") for (int k = 0; k < 2; ++k) dst[n][k] = *(const LAS bf16x8*)(lds + PG8_SB(b, h) + boff + n * 2048 + k * 1024); } while (0)
; #define PG8_SCHED __builtin_amdgcn_sched_barrier(0)
;     __device__ __forceinline__ bool next(int i, Unit& u) const {
;         const long L = (long)i * G + c; if (L >= nwg) return false;
;         int wgid = (int)L; { const int q = nwg / NXCD, r = nwg % NXCD, xcd = wgid % NXCD, off = wgid / NXCD; wgid = (xcd < r ? xcd * (q + 1) : r * (q + 1) + (xcd - r) * q) + off; }
;         const int nig = WGM * nN, gid = wgid / nig, fm = gid * WGM, gsz = (nM - fm) < WGM ? (nM - fm) : WGM;
;         u.pm = fm + ((wgid % nig) % gsz); u.pn = (wgid % nig) / gsz; u.e = 0; u.kt0 = 0; u.nkt = nt; u.buf = 0;
;     ...
;     for (;;) {
;         const bool has_next = S.next(ui + 1, nxt);
;         const char* nA = has_next ? (const char*)g.A + (size_t)nxt.pm * tstep + (size_t)nxt.kt0 * kstep : cA; const char* nB = has_next ? (const char*)g.Bt + (size_t)nxt.e * g.estride + (size_t)nxt.pn * tstep + (size_t)nxt.kt0 * kstep : cB;
;         const int nt = cur.nkt;
;         for (int t = 0; t < nt; t += 2) {
;             const bool last = (t == nt - 2);
;             const char* a1 = cA + (size_t)(t + 1) * kstep;
;             const char* a2 = last ? nA : cA + (size_t)(t + 2) * kstep; const char* b2 = last ? nB : cB + (size_t)(t + 2) * kstep;
;             const char* a3 = a2 + kstep; const char* b3 = b2 + kstep;
;             PG8_LDB(B0, 0, 0); PG8_LDB(B1, 0, 1); PG8_SCHED; PG8_LDA(At, 0, 0); PG8_STAGE(PG8_SA(1, 1), a1 + hstep, voffA);
.LBB0_3847:
	ds_read_b128 v[24:27], v189
	ds_read_b128 v[28:31], v189 offset:1024
	ds_read_b128 v[16:19], v189 offset:2048
	ds_read_b128 v[20:23], v189 offset:3072
	ds_read_b128 v[8:11], v190
	ds_read_b128 v[12:15], v190 offset:1024
	s_add_i32 s54, s54, 1
	s_mul_i32 s4, s54, s59
	s_mul_hi_u32 s5, s54, s33
	s_add_i32 s5, s5, s4
	s_mul_i32 s4, s54, s33
	s_add_u32 s4, s4, s22
	s_addc_u32 s5, s5, s60
	v_cmp_gt_i64_e32 vcc, s[4:5], v[174:175]
	v_cmp_lt_i64_e64 s[6:7], s[4:5], v[172:173]
	s_cbranch_vccnz .LBB0_3853
	s_ashr_i32 s5, s4, 31
	s_lshr_b32 s5, s5, 29
	s_add_i32 s40, s4, s5
	s_and_b32 s5, s40, -8
	s_sub_i32 s41, s4, s5
	s_cmp_gt_i32 s41, -1
	s_mov_b64 s[4:5], -1
	s_cbranch_scc0 .LBB0_3850
	s_lshl_b32 s42, s41, 6
	s_mov_b64 s[4:5], 0

; #define PG8_STAGE(bufoff, gbase, voff) do { _Pragma("unroll") for (int _i = 0; _i < 2; ++_i) \
;         __builtin_amdgcn_global_load_lds((const unsigned*)((const char*)(gbase) + (voff)[_i]), (LAS unsigned*)(lds + (bufoff) + ldsw + _i * 8192), 16, 0, 0); } while (0)
; #define PG8_LDA(dst, b, h) do { _Pragma("unroll") for (int m = 0; m < 4; ++m) _Pragma("unroll") for (int k = 0; k < 2; ++k) dst[m][k] = *(const LAS bf16x8*)(lds + PG8_SA(b, h) + aoff + m * 2048 + k * 1024); } while (0)
; #define PG8_LDB(dst, b, h) do { _Pragma("unroll") for (int n = 0; n < 2; ++n) _Pragma("unroll") for (int k = 0; k < 2; ++k) dst[n][k] = *(const LAS bf16x8*)(lds + PG8_SB(b, h) + boff + n * 2048 + k * 1024); } while (0)
; #define PG8_WAIT_V(n) asm volatile("s_waitcnt vmcnt(" #n ")" ::: "memory")
; #define PG8_WAIT_L(n) asm volatile("s_waitcnt lgkmcnt(" #n ")" ::: "memory")
; #define PG8_BAR __builtin_amdgcn_s_barrier()
; #define PG8_SCHED __builtin_amdgcn_sched_barrier(0)
;     ...
;         const char* nA = has_next ? (const char*)g.A + (size_t)nxt.pm * tstep + (size_t)nxt.kt0 * kstep : cA; const char* nB = has_next ? (const char*)g.Bt + (size_t)nxt.e * g.estride + (size_t)nxt.pn * tstep + (size_t)nxt.kt0 * kstep : cB;
;         const int nt = cur.nkt;
;         for (int t = 0; t < nt; t += 2) {
;             const bool last = (t == nt - 2);
;             const char* a1 = cA + (size_t)(t + 1) * kstep;
;             const char* a2 = last ? nA : cA + (size_t)(t + 2) * kstep; const char* b2 = last ? nB : cB + (size_t)(t + 2) * kstep;
;             const char* a3 = a2 + kstep; const char* b3 = b2 + kstep;
;             PG8_LDB(B0, 0, 0); PG8_LDB(B1, 0, 1); PG8_SCHED; PG8_LDA(At, 0, 0); PG8_STAGE(PG8_SA(1, 1), a1 + hstep, voffA);
;             PG8_WAIT_V(8); PG8_WAIT_L(0); PG8_BAR; PG8_MMA(0, 0, At, B0); PG8_MMA(0, 1, At, B1); PG8_BAR; PG8_SCHED;
;             PG8_LDA(At, 0, 1); PG8_STAGE(PG8_SB(0, 0), b2, voffB); PG8_STAGE(PG8_SB(0, 1), b2 + hstep, voffB); PG8_STAGE(PG8_SA(0, 0), a2, voffA);
;             PG8_WAIT_V(8); PG8_WAIT_L(0); PG8_BAR; PG8_MMA(1, 0, At, B0); PG8_MMA(1, 1, At, B1); PG8_BAR; PG8_SCHED;
.LBB0_3857:
	s_add_u32 s71, s46, 0x100
	s_addc_u32 s72, s47, 0
	s_mov_b32 s73, -2
	s_waitcnt lgkmcnt(0)
	ds_read_b128 v[0:3], v190 offset:2048
	ds_read_b128 v[4:7], v190 offset:3072
	s_add_u32 s6, s44, 0x100
	s_addc_u32 s7, s45, 0
	s_cmp_eq_u32 s73, 40
	s_cselect_b32 s49, s41, s7
	s_cselect_b32 s48, s40, s6
	s_cselect_b32 s47, s43, s72
	s_cselect_b32 s46, s42, s71
	v_lshl_add_u64 v[184:185], s[44:45], 0, v[168:169]
	s_add_i32 m0, s37, 0xc000
	ds_read_b128 v[176:179], v191
	ds_read_b128 v[180:183], v191 offset:1024
	ds_read_b128 v[196:199], v191 offset:2048
	ds_read_b128 v[200:203], v191 offset:3072
	ds_read_b128 v[204:207], v191 offset:4096
	ds_read_b128 v[208:211], v191 offset:5120
	ds_read_b128 v[212:215], v191 offset:6144
	ds_read_b128 v[216:219], v191 offset:7168
	global_load_lds_dwordx4 v[184:185], off
	v_lshl_add_u64 v[184:185], s[44:45], 0, v[170:171]
	s_add_i32 m0, s37, 0xe000
	s_nop 0
	global_load_lds_dwordx4 v[184:185], off
	s_waitcnt vmcnt(8)
	s_waitcnt lgkmcnt(0)
	s_barrier
	s_setprio 1
	s_waitcnt lgkmcnt(0)
	v_mfma_scale_f32_16x16x128_f8f6f4 v[156:159], v[24:31], v[176:183], 0, v192, v192 op_sel_hi:[0,0,0]
	v_mfma_scale_f32_16x16x128_f8f6f4 v[152:155], v[16:23], v[176:183], 0, v192, v192 op_sel_hi:[0,0,0]
	v_mfma_scale_f32_16x16x128_f8f6f4 v[140:143], v[24:31], v[196:203], 0, v192, v192 op_sel_hi:[0,0,0]
	v_mfma_scale_f32_16x16x128_f8f6f4 v[136:139], v[16:23], v[196:203], 0, v192, v192 op_sel_hi:[0,0,0]
	v_mfma_scale_f32_16x16x128_f8f6f4 v[124:127], v[24:31], v[204:211], 0, v192, v192 op_sel_hi:[0,0,0]
	v_mfma_scale_f32_16x16x128_f8f6f4 v[120:123], v[16:23], v[204:211], 0, v192, v192 op_sel_hi:[0,0,0]
	v_mfma_scale_f32_16x16x128_f8f6f4 v[108:111], v[24:31], v[212:219], 0, v192, v192 op_sel_hi:[0,0,0]
	v_mfma_scale_f32_16x16x128_f8f6f4 v[104:107], v[16:23], v[212:219], 0, v192, v192 op_sel_hi:[0,0,0]
	s_setprio 0
	s_setprio 1
	v_mfma_scale_f32_16x16x128_f8f6f4 v[148:151], v[8:15], v[176:183], 0, v192, v192 op_sel_hi:[0,0,0]
	v_mfma_scale_f32_16x16x128_f8f6f4 v[144:147], v[0:7], v[176:183], 0, v192, v192 op_sel_hi:[0,0,0]
	v_mfma_scale_f32_16x16x128_f8f6f4 v[132:135], v[8:15], v[196:203], 0, v192, v192 op_sel_hi:[0,0,0]
	v_mfma_scale_f32_16x16x128_f8f6f4 v[128:131], v[0:7], v[196:203], 0, v192, v192 op_sel_hi:[0,0,0]
	v_mfma_scale_f32_16x16x128_f8f6f4 v[116:119], v[8:15], v[204:211], 0, v192, v192 op_sel_hi:[0,0,0]
	v_mfma_scale_f32_16x16x128_f8f6f4 v[112:115], v[0:7], v[204:211], 0, v192, v192 op_sel_hi:[0,0,0]
	v_mfma_scale_f32_16x16x128_f8f6f4 v[100:103], v[8:15], v[212:219], 0, v192, v192 op_sel_hi:[0,0,0]
	v_mfma_scale_f32_16x16x128_f8f6f4 v[96:99], v[0:7], v[212:219], 0, v192, v192 op_sel_hi:[0,0,0]
	s_setprio 0
	s_barrier
	s_add_i32 s44, s61, s35
	v_lshl_add_u64 v[176:177], s[46:47], 0, v[162:163]
	s_mov_b32 m0, s44
	ds_read_b128 v[196:199], v191 offset:16384
	ds_read_b128 v[200:203], v191 offset:17408
	ds_read_b128 v[204:207], v191 offset:18432
	ds_read_b128 v[208:211], v191 offset:19456
	ds_read_b128 v[212:215], v191 offset:20480
	ds_read_b128 v[216:219], v191 offset:21504
	ds_read_b128 v[220:223], v191 offset:22528
	ds_read_b128 v[224:227], v191 offset:23552
	global_load_lds_dwordx4 v[176:177], off
	s_add_i32 m0, s44, 0x2000
	s_add_u32 s44, s46, 0xb0000
	v_lshl_add_u64 v[178:179], s[46:47], 0, v[166:167]
	s_addc_u32 s45, s47, 0
	s_add_i32 s74, s62, s35
	global_load_lds_dwordx4 v[178:179], off
	v_lshl_add_u64 v[180:181], s[44:45], 0, v[162:163]
	s_mov_b32 m0, s74
	v_lshl_add_u64 v[182:183], s[48:49], 0, v[164:165]
	global_load_lds_dwordx4 v[180:181], off
	v_lshl_add_u64 v[180:181], s[44:45], 0, v[166:167]
	s_add_i32 m0, s74, 0x2000
	s_nop 0
	global_load_lds_dwordx4 v[180:181], off
	v_lshl_add_u64 v[180:181], s[48:49], 0, v[160:161]
	s_mov_b32 m0, s37
	s_nop 0
	global_load_lds_dwordx4 v[180:181], off
	s_mov_b32 m0, s39
	s_nop 0
	global_load_lds_dwordx4 v[182:183], off
	s_waitcnt vmcnt(8)
	s_waitcnt lgkmcnt(0)
	s_barrier
	s_setprio 1
	s_waitcnt lgkmcnt(0)
	v_mfma_scale_f32_16x16x128_f8f6f4 v[92:95], v[24:31], v[196:203], 0, v192, v192 op_sel_hi:[0,0,0]
	v_mfma_scale_f32_16x16x128_f8f6f4 v[88:91], v[16:23], v[196:203], 0, v192, v192 op_sel_hi:[0,0,0]
	v_mfma_scale_f32_16x16x128_f8f6f4 v[76:79], v[24:31], v[204:211], 0, v192, v192 op_sel_hi:[0,0,0]
	v_mfma_scale_f32_16x16x128_f8f6f4 v[72:75], v[16:23], v[204:211], 0, v192, v192 op_sel_hi:[0,0,0]
	v_mfma_scale_f32_16x16x128_f8f6f4 v[60:63], v[24:31], v[212:219], 0, v192, v192 op_sel_hi:[0,0,0]
	v_mfma_scale_f32_16x16x128_f8f6f4 v[56:59], v[16:23], v[212:219], 0, v192, v192 op_sel_hi:[0,0,0]
	v_mfma_scale_f32_16x16x128_f8f6f4 v[44:47], v[24:31], v[220:227], 0, v192, v192 op_sel_hi:[0,0,0]
	v_mfma_scale_f32_16x16x128_f8f6f4 v[40:43], v[16:23], v[220:227], 0, v192, v192 op_sel_hi:[0,0,0]
	s_setprio 0
	s_setprio 1
	v_mfma_scale_f32_16x16x128_f8f6f4 v[84:87], v[8:15], v[196:203], 0, v192, v192 op_sel_hi:[0,0,0]
	v_mfma_scale_f32_16x16x128_f8f6f4 v[80:83], v[0:7], v[196:203], 0, v192, v192 op_sel_hi:[0,0,0]
	v_mfma_scale_f32_16x16x128_f8f6f4 v[68:71], v[8:15], v[204:211], 0, v192, v192 op_sel_hi:[0,0,0]
	v_mfma_scale_f32_16x16x128_f8f6f4 v[64:67], v[0:7], v[204:211], 0, v192, v192 op_sel_hi:[0,0,0]
	v_mfma_scale_f32_16x16x128_f8f6f4 v[52:55], v[8:15], v[212:219], 0, v192, v192 op_sel_hi:[0,0,0]
	v_mfma_scale_f32_16x16x128_f8f6f4 v[48:51], v[0:7], v[212:219], 0, v192, v192 op_sel_hi:[0,0,0]
	v_mfma_scale_f32_16x16x128_f8f6f4 v[36:39], v[8:15], v[220:227], 0, v192, v192 op_sel_hi:[0,0,0]
	v_mfma_scale_f32_16x16x128_f8f6f4 v[32:35], v[0:7], v[220:227], 0, v192, v192 op_sel_hi:[0,0,0]
	s_setprio 0
	s_barrier
; #define PG8_STAGE(bufoff, gbase, voff) do { _Pragma("unroll") for (int _i = 0; _i < 2; ++_i) \
;         __builtin_amdgcn_global_load_lds((const unsigned*)((const char*)(gbase) + (voff)[_i]), (LAS unsigned*)(lds + (bufoff) + ldsw + _i * 8192), 16, 0, 0); } while (0)
; #define PG8_LDA(dst, b, h) do { _Pragma("unroll") for (int m = 0; m < 4; ++m) _Pragma("unroll") for (int k = 0; k < 2; ++k) dst[m][k] = *(const LAS bf16x8*)(lds + PG8_SA(b, h) + aoff + m * 2048 + k * 1024); } while (0)
; #define PG8_LDB(dst, b, h) do { _Pragma("unroll") for (int n = 0; n < 2; ++n) _Pragma("unroll") for (int k = 0; k < 2; ++k) dst[n][k] = *(const LAS bf16x8*)(lds + PG8_SB(b, h) + boff + n * 2048 + k * 1024); } while (0)
; #define PG8_WAIT_V(n) asm volatile("s_waitcnt vmcnt(" #n ")" ::: "memory")
; #define PG8_WAIT_L(n) asm volatile("s_waitcnt lgkmcnt(" #n ")" ::: "memory")
; #define PG8_BAR __builtin_amdgcn_s_barrier()
; #define PG8_SCHED __builtin_amdgcn_sched_barrier(0)
;     ...
;             PG8_LDB(B0, 1, 0); PG8_LDB(B1, 1, 1); PG8_SCHED; PG8_LDA(At, 1, 0); PG8_STAGE(PG8_SA(0, 1), a2 + hstep, voffA);
;             PG8_WAIT_V(8); PG8_WAIT_L(0); PG8_BAR; PG8_MMA(0, 0, At, B0); PG8_MMA(0, 1, At, B1); PG8_BAR; PG8_SCHED;
;             PG8_LDA(At, 1, 1); PG8_STAGE(PG8_SB(1, 0), b3, voffB); PG8_STAGE(PG8_SB(1, 1), b3 + hstep, voffB); PG8_STAGE(PG8_SA(1, 0), a3, voffA);
;             PG8_WAIT_V(8); PG8_WAIT_L(0); PG8_BAR; PG8_MMA(1, 0, At, B0); PG8_MMA(1, 1, At, B1); PG8_BAR; PG8_SCHED;
;         }
	s_add_i32 s74, 0, 0x18000
	s_add_i32 s75, 0, 0x1c000
	v_add_u32_e32 v12, s74, v187
	v_add_u32_e32 v28, s75, v187
	ds_read_b128 v[0:3], v12
	ds_read_b128 v[4:7], v12 offset:1024
	ds_read_b128 v[8:11], v12 offset:2048
	ds_read_b128 v[12:15], v12 offset:3072
	ds_read_b128 v[16:19], v28
	ds_read_b128 v[20:23], v28 offset:1024
	ds_read_b128 v[24:27], v28 offset:2048
	ds_read_b128 v[28:31], v28 offset:3072
	s_add_u32 s44, s48, 0xb0000
	s_addc_u32 s45, s49, 0
	s_mov_b32 m0, s50
	v_lshl_add_u64 v[184:185], s[44:45], 0, v[160:161]
	ds_read_b128 v[196:199], v191 offset:32768
	ds_read_b128 v[200:203], v191 offset:33792
	ds_read_b128 v[204:207], v191 offset:34816
	ds_read_b128 v[208:211], v191 offset:35840
	ds_read_b128 v[212:215], v191 offset:36864
	ds_read_b128 v[216:219], v191 offset:37888
	ds_read_b128 v[220:223], v191 offset:38912
	ds_read_b128 v[224:227], v191 offset:39936
	global_load_lds_dwordx4 v[184:185], off
	v_lshl_add_u64 v[184:185], s[44:45], 0, v[164:165]
	s_mov_b32 m0, s51
	s_nop 0
	global_load_lds_dwordx4 v[184:185], off
	s_waitcnt vmcnt(8)
	s_waitcnt lgkmcnt(0)
	s_barrier
	s_setprio 1
	s_waitcnt lgkmcnt(0)
	v_mfma_scale_f32_16x16x128_f8f6f4 v[156:159], v[0:7], v[196:203], v[156:159], v192, v192 op_sel_hi:[0,0,0]
	v_mfma_scale_f32_16x16x128_f8f6f4 v[152:155], v[8:15], v[196:203], v[152:155], v192, v192 op_sel_hi:[0,0,0]
	v_mfma_scale_f32_16x16x128_f8f6f4 v[140:143], v[0:7], v[204:211], v[140:143], v192, v192 op_sel_hi:[0,0,0]
	v_mfma_scale_f32_16x16x128_f8f6f4 v[136:139], v[8:15], v[204:211], v[136:139], v192, v192 op_sel_hi:[0,0,0]
	v_mfma_scale_f32_16x16x128_f8f6f4 v[124:127], v[0:7], v[212:219], v[124:127], v192, v192 op_sel_hi:[0,0,0]
	v_mfma_scale_f32_16x16x128_f8f6f4 v[120:123], v[8:15], v[212:219], v[120:123], v192, v192 op_sel_hi:[0,0,0]
	v_mfma_scale_f32_16x16x128_f8f6f4 v[108:111], v[0:7], v[220:227], v[108:111], v192, v192 op_sel_hi:[0,0,0]
	v_mfma_scale_f32_16x16x128_f8f6f4 v[104:107], v[8:15], v[220:227], v[104:107], v192, v192 op_sel_hi:[0,0,0]
	s_setprio 0
	s_setprio 1
	v_mfma_scale_f32_16x16x128_f8f6f4 v[148:151], v[16:23], v[196:203], v[148:151], v192, v192 op_sel_hi:[0,0,0]
	v_mfma_scale_f32_16x16x128_f8f6f4 v[144:147], v[24:31], v[196:203], v[144:147], v192, v192 op_sel_hi:[0,0,0]
	v_mfma_scale_f32_16x16x128_f8f6f4 v[132:135], v[16:23], v[204:211], v[132:135], v192, v192 op_sel_hi:[0,0,0]
	v_mfma_scale_f32_16x16x128_f8f6f4 v[128:131], v[24:31], v[204:211], v[128:131], v192, v192 op_sel_hi:[0,0,0]
	v_mfma_scale_f32_16x16x128_f8f6f4 v[116:119], v[16:23], v[212:219], v[116:119], v192, v192 op_sel_hi:[0,0,0]
	v_mfma_scale_f32_16x16x128_f8f6f4 v[112:115], v[24:31], v[212:219], v[112:115], v192, v192 op_sel_hi:[0,0,0]
	v_mfma_scale_f32_16x16x128_f8f6f4 v[100:103], v[16:23], v[220:227], v[100:103], v192, v192 op_sel_hi:[0,0,0]
	v_mfma_scale_f32_16x16x128_f8f6f4 v[96:99], v[24:31], v[220:227], v[96:99], v192, v192 op_sel_hi:[0,0,0]
	s_setprio 0
	s_barrier
	s_add_i32 s44, s74, s35
	v_lshl_add_u64 v[176:177], v[176:177], 0, s[24:25]
	s_mov_b32 m0, s44
	ds_read_b128 v[196:199], v191 offset:49152
	ds_read_b128 v[200:203], v191 offset:50176
	ds_read_b128 v[204:207], v191 offset:51200
	ds_read_b128 v[208:211], v191 offset:52224
	ds_read_b128 v[212:215], v191 offset:53248
	ds_read_b128 v[216:219], v191 offset:54272
	ds_read_b128 v[220:223], v191 offset:55296
	ds_read_b128 v[224:227], v191 offset:56320
	global_load_lds_dwordx4 v[176:177], off
	s_add_i32 m0, s44, 0x2000
	s_add_u32 s44, s46, 0xb0080
	v_lshl_add_u64 v[176:177], v[178:179], 0, s[24:25]
	s_addc_u32 s45, s47, 0
	s_add_i32 s46, s75, s35
	global_load_lds_dwordx4 v[176:177], off
	v_lshl_add_u64 v[176:177], s[44:45], 0, v[162:163]
	s_mov_b32 m0, s46
	s_nop 0
	global_load_lds_dwordx4 v[176:177], off
	v_lshl_add_u64 v[176:177], s[44:45], 0, v[166:167]
	s_add_i32 m0, s46, 0x2000
	s_nop 0
	global_load_lds_dwordx4 v[176:177], off
	v_lshl_add_u64 v[176:177], v[180:181], 0, s[24:25]
	s_mov_b32 m0, s55
	s_nop 0
	global_load_lds_dwordx4 v[176:177], off
	v_lshl_add_u64 v[176:177], v[182:183], 0, s[24:25]
	s_mov_b32 m0, s58
	s_nop 0
	global_load_lds_dwordx4 v[176:177], off
	s_waitcnt vmcnt(8)
	s_waitcnt lgkmcnt(0)
	s_barrier
	s_setprio 1
	s_waitcnt lgkmcnt(0)
	v_mfma_scale_f32_16x16x128_f8f6f4 v[92:95], v[0:7], v[196:203], v[92:95], v192, v192 op_sel_hi:[0,0,0]
	v_mfma_scale_f32_16x16x128_f8f6f4 v[88:91], v[8:15], v[196:203], v[88:91], v192, v192 op_sel_hi:[0,0,0]
	v_mfma_scale_f32_16x16x128_f8f6f4 v[76:79], v[0:7], v[204:211], v[76:79], v192, v192 op_sel_hi:[0,0,0]
	v_mfma_scale_f32_16x16x128_f8f6f4 v[72:75], v[8:15], v[204:211], v[72:75], v192, v192 op_sel_hi:[0,0,0]
	v_mfma_scale_f32_16x16x128_f8f6f4 v[60:63], v[0:7], v[212:219], v[60:63], v192, v192 op_sel_hi:[0,0,0]
	v_mfma_scale_f32_16x16x128_f8f6f4 v[56:59], v[8:15], v[212:219], v[56:59], v192, v192 op_sel_hi:[0,0,0]
	v_mfma_scale_f32_16x16x128_f8f6f4 v[44:47], v[0:7], v[220:227], v[44:47], v192, v192 op_sel_hi:[0,0,0]
	v_mfma_scale_f32_16x16x128_f8f6f4 v[40:43], v[8:15], v[220:227], v[40:43], v192, v192 op_sel_hi:[0,0,0]
	s_setprio 0
	s_setprio 1
	v_mfma_scale_f32_16x16x128_f8f6f4 v[84:87], v[16:23], v[196:203], v[84:87], v192, v192 op_sel_hi:[0,0,0]
	v_mfma_scale_f32_16x16x128_f8f6f4 v[80:83], v[24:31], v[196:203], v[80:83], v192, v192 op_sel_hi:[0,0,0]
	v_mfma_scale_f32_16x16x128_f8f6f4 v[68:71], v[16:23], v[204:211], v[68:71], v192, v192 op_sel_hi:[0,0,0]
	v_mfma_scale_f32_16x16x128_f8f6f4 v[64:67], v[24:31], v[204:211], v[64:67], v192, v192 op_sel_hi:[0,0,0]
	v_mfma_scale_f32_16x16x128_f8f6f4 v[52:55], v[16:23], v[212:219], v[52:55], v192, v192 op_sel_hi:[0,0,0]
	v_mfma_scale_f32_16x16x128_f8f6f4 v[48:51], v[24:31], v[212:219], v[48:51], v192, v192 op_sel_hi:[0,0,0]
	v_mfma_scale_f32_16x16x128_f8f6f4 v[36:39], v[16:23], v[220:227], v[36:39], v192, v192 op_sel_hi:[0,0,0]
	v_mfma_scale_f32_16x16x128_f8f6f4 v[32:35], v[24:31], v[220:227], v[32:35], v192, v192 op_sel_hi:[0,0,0]
	s_setprio 0
	s_barrier
	s_add_i32 s73, s73, 2
	s_add_u32 s71, s71, 0x100
	s_addc_u32 s72, s72, 0
	s_cmp_gt_u32 s73, 41
	s_mov_b64 s[44:45], s[6:7]
	s_cbranch_scc0 .LBB0_3858

; #define PG8_STAGE(bufoff, gbase, voff) do { _Pragma("unroll") for (int _i = 0; _i < 2; ++_i) \
;         __builtin_amdgcn_global_load_lds((const unsigned*)((const char*)(gbase) + (voff)[_i]), (LAS unsigned*)(lds + (bufoff) + ldsw + _i * 8192), 16, 0, 0); } while (0)
; #define PG8_LDA(dst, b, h) do { _Pragma("unroll") for (int m = 0; m < 4; ++m) _Pragma("unroll") for (int k = 0; k < 2; ++k) dst[m][k] = *(const LAS bf16x8*)(lds + PG8_SA(b, h) + aoff + m * 2048 + k * 1024); } while (0)
; #define PG8_LDB(dst, b, h) do { _Pragma("unroll") for (int n = 0; n < 2; ++n) _Pragma("unroll") for (int k = 0; k < 2; ++k) dst[n][k] = *(const LAS bf16x8*)(lds + PG8_SB(b, h) + boff + n * 2048 + k * 1024); } while (0)
; #define PG8_SCHED __builtin_amdgcn_sched_barrier(0)
;     __device__ __forceinline__ bool next(int i, Unit& u) const {
;         const long L = (long)i * G + c; if (L >= nwg) return false;
;         int wgid = (int)L; { const int q = nwg / NXCD, r = nwg % NXCD, xcd = wgid % NXCD, off = wgid / NXCD; wgid = (xcd < r ? xcd * (q + 1) : r * (q + 1) + (xcd - r) * q) + off; }
;         const int nig = WGM * nN, gid = wgid / nig, fm = gid * WGM, gsz = (nM - fm) < WGM ? (nM - fm) : WGM;
;         u.pm = fm + ((wgid % nig) % gsz); u.pn = (wgid % nig) / gsz; u.e = 0; u.kt0 = 0; u.nkt = nt; u.buf = 0;
;     ...
;     for (;;) {
;         const bool has_next = S.next(ui + 1, nxt);
;         const char* nA = has_next ? (const char*)g.A + (size_t)nxt.pm * tstep + (size_t)nxt.kt0 * kstep : cA; const char* nB = has_next ? (const char*)g.Bt + (size_t)nxt.e * g.estride + (size_t)nxt.pn * tstep + (size_t)nxt.kt0 * kstep : cB;
;         const int nt = cur.nkt;
;         for (int t = 0; t < nt; t += 2) {
;             const bool last = (t == nt - 2);
;             const char* a1 = cA + (size_t)(t + 1) * kstep;
;             const char* a2 = last ? nA : cA + (size_t)(t + 2) * kstep; const char* b2 = last ? nB : cB + (size_t)(t + 2) * kstep;
;             const char* a3 = a2 + kstep; const char* b3 = b2 + kstep;
;             PG8_LDB(B0, 0, 0); PG8_LDB(B1, 0, 1); PG8_SCHED; PG8_LDA(At, 0, 0); PG8_STAGE(PG8_SA(1, 1), a1 + hstep, voffA);
.LBB0_3948:
	ds_read_b128 v[152:155], v183
	ds_read_b128 v[156:159], v183 offset:1024
	ds_read_b128 v[160:163], v183 offset:2048
	ds_read_b128 v[164:167], v183 offset:3072
	ds_read_b128 v[168:171], v184
	ds_read_b128 v[172:175], v184 offset:1024
	ds_read_b128 v[176:179], v184 offset:2048
	ds_read_b128 v[190:193], v184 offset:3072
	ds_read_b128 v[194:197], v185
	ds_read_b128 v[198:201], v185 offset:1024
	ds_read_b128 v[202:205], v185 offset:2048
	ds_read_b128 v[206:209], v185 offset:3072
	ds_read_b128 v[210:213], v185 offset:4096
	ds_read_b128 v[214:217], v185 offset:5120
	ds_read_b128 v[218:221], v185 offset:6144
	ds_read_b128 v[222:225], v185 offset:7168
	s_add_i32 s59, s59, 1
	s_mul_i32 s4, s59, s63
	s_mul_hi_u32 s5, s59, s33
	s_add_i32 s5, s5, s4
	s_mul_i32 s4, s59, s33
	s_add_u32 s40, s4, s22
	s_addc_u32 s41, s5, s64
	v_cmp_gt_i64_e32 vcc, s[40:41], v[150:151]
	v_cmp_lt_i64_e64 s[4:5], s[40:41], v[148:149]
	s_cbranch_vccnz .LBB0_3954
	s_ashr_i32 s7, s40, 31
	s_lshr_b32 s7, s7, 29
	s_add_i32 s7, s40, s7
	s_and_b32 s36, s7, -8
	s_sub_i32 s38, s40, s36
	s_cmp_gt_i32 s38, -1
	s_mov_b64 s[36:37], -1
	s_cbranch_scc0 .LBB0_3951
	s_lshl_b32 s39, s38, 5
	s_mov_b64 s[36:37], 0

; #define PG8_STAGE(bufoff, gbase, voff) do { _Pragma("unroll") for (int _i = 0; _i < 2; ++_i) \
;         __builtin_amdgcn_global_load_lds((const unsigned*)((const char*)(gbase) + (voff)[_i]), (LAS unsigned*)(lds + (bufoff) + ldsw + _i * 8192), 16, 0, 0); } while (0)
; #define PG8_LDA(dst, b, h) do { _Pragma("unroll") for (int m = 0; m < 4; ++m) _Pragma("unroll") for (int k = 0; k < 2; ++k) dst[m][k] = *(const LAS bf16x8*)(lds + PG8_SA(b, h) + aoff + m * 2048 + k * 1024); } while (0)
; #define PG8_LDB(dst, b, h) do { _Pragma("unroll") for (int n = 0; n < 2; ++n) _Pragma("unroll") for (int k = 0; k < 2; ++k) dst[n][k] = *(const LAS bf16x8*)(lds + PG8_SB(b, h) + boff + n * 2048 + k * 1024); } while (0)
; #define PG8_WAIT_V(n) asm volatile("s_waitcnt vmcnt(" #n ")" ::: "memory")
; #define PG8_WAIT_L(n) asm volatile("s_waitcnt lgkmcnt(" #n ")" ::: "memory")
; #define PG8_BAR __builtin_amdgcn_s_barrier()
; #define PG8_SCHED __builtin_amdgcn_sched_barrier(0)
;     ...
;         const char* nA = has_next ? (const char*)g.A + (size_t)nxt.pm * tstep + (size_t)nxt.kt0 * kstep : cA; const char* nB = has_next ? (const char*)g.Bt + (size_t)nxt.e * g.estride + (size_t)nxt.pn * tstep + (size_t)nxt.kt0 * kstep : cB;
;         const int nt = cur.nkt;
;         for (int t = 0; t < nt; t += 2) {
;             const bool last = (t == nt - 2);
;             const char* a1 = cA + (size_t)(t + 1) * kstep;
;             const char* a2 = last ? nA : cA + (size_t)(t + 2) * kstep; const char* b2 = last ? nB : cB + (size_t)(t + 2) * kstep;
;             const char* a3 = a2 + kstep; const char* b3 = b2 + kstep;
;             PG8_LDB(B0, 0, 0); PG8_LDB(B1, 0, 1); PG8_SCHED; PG8_LDA(At, 0, 0); PG8_STAGE(PG8_SA(1, 1), a1 + hstep, voffA);
;             PG8_WAIT_V(8); PG8_WAIT_L(0); PG8_BAR; PG8_MMA(0, 0, At, B0); PG8_MMA(0, 1, At, B1); PG8_BAR; PG8_SCHED;
;             PG8_LDA(At, 0, 1); PG8_STAGE(PG8_SB(0, 0), b2, voffB); PG8_STAGE(PG8_SB(0, 1), b2 + hstep, voffB); PG8_STAGE(PG8_SA(0, 0), a2, voffA);
;             PG8_WAIT_V(8); PG8_WAIT_L(0); PG8_BAR; PG8_MMA(1, 0, At, B0); PG8_MMA(1, 1, At, B1); PG8_BAR; PG8_SCHED;
.LBB0_3954:
	s_ashr_i32 s39, s38, 31
	s_lshl_b64 s[40:41], s[38:39], 19
	s_add_u32 s40, s23, s40
	s_addc_u32 s41, s27, s41
	s_and_b64 s[42:43], s[4:5], exec
	s_cselect_b32 s7, s41, s47
	s_cselect_b32 s39, s40, s46
	s_ashr_i32 s37, s36, 31
	s_lshl_b64 s[42:43], s[36:37], 19
	s_add_u32 s42, s29, s42
	s_addc_u32 s43, s31, s43
	s_and_b64 s[50:51], s[4:5], exec
	s_cselect_b32 s37, s43, s49
	s_cselect_b32 s45, s42, s48
	s_add_u32 s46, s46, 0x40080
	s_addc_u32 s47, s47, 0
	s_add_u32 s73, s48, 0x100
	s_addc_u32 s74, s49, 0
	s_mov_b32 s75, -2
	s_waitcnt lgkmcnt(0)
	s_add_u32 s48, s46, 0xfffc0080
	s_addc_u32 s49, s47, -1
	s_cmp_eq_u32 s75, 12
	s_cselect_b32 s51, s7, s49
	s_cselect_b32 s50, s39, s48
	s_cselect_b32 s49, s37, s74
	s_cselect_b32 s48, s45, s73
	v_lshl_add_u64 v[226:227], s[46:47], 0, v[144:145]
	s_add_i32 m0, s35, 0xc000
	global_load_lds_dwordx4 v[226:227], off
	v_lshl_add_u64 v[226:227], s[46:47], 0, v[146:147]
	s_add_i32 m0, s35, 0xe000
	s_nop 0
	global_load_lds_dwordx4 v[226:227], off
	s_waitcnt vmcnt(8)
	s_waitcnt lgkmcnt(0)
	s_barrier
	s_setprio 1
	s_waitcnt lgkmcnt(0)
	v_mfma_i32_16x16x64_i8 v[124:127], v[152:155], v[194:197], 0
	v_mfma_i32_16x16x64_i8 v[120:123], v[160:163], v[194:197], 0
	v_mfma_i32_16x16x64_i8 v[116:119], v[152:155], v[202:205], 0
	v_mfma_i32_16x16x64_i8 v[112:115], v[160:163], v[202:205], 0
	v_mfma_i32_16x16x64_i8 v[108:111], v[152:155], v[210:213], 0
	v_mfma_i32_16x16x64_i8 v[104:107], v[160:163], v[210:213], 0
	v_mfma_i32_16x16x64_i8 v[100:103], v[152:155], v[218:221], 0
	v_mfma_i32_16x16x64_i8 v[96:99], v[160:163], v[218:221], 0
	v_mfma_i32_16x16x64_i8 v[124:127], v[156:159], v[198:201], v[124:127]
	v_mfma_i32_16x16x64_i8 v[120:123], v[164:167], v[198:201], v[120:123]
	v_mfma_i32_16x16x64_i8 v[116:119], v[156:159], v[206:209], v[116:119]
	v_mfma_i32_16x16x64_i8 v[112:115], v[164:167], v[206:209], v[112:115]
	v_mfma_i32_16x16x64_i8 v[108:111], v[156:159], v[214:217], v[108:111]
	v_mfma_i32_16x16x64_i8 v[104:107], v[164:167], v[214:217], v[104:107]
	v_mfma_i32_16x16x64_i8 v[100:103], v[156:159], v[222:225], v[100:103]
	v_mfma_i32_16x16x64_i8 v[96:99], v[164:167], v[222:225], v[96:99]
	s_setprio 0
	s_setprio 1
	v_mfma_i32_16x16x64_i8 v[60:63], v[168:171], v[194:197], 0
	v_mfma_i32_16x16x64_i8 v[56:59], v[176:179], v[194:197], 0
	v_mfma_i32_16x16x64_i8 v[52:55], v[168:171], v[202:205], 0
	v_mfma_i32_16x16x64_i8 v[48:51], v[176:179], v[202:205], 0
	v_mfma_i32_16x16x64_i8 v[44:47], v[168:171], v[210:213], 0
	v_mfma_i32_16x16x64_i8 v[40:43], v[176:179], v[210:213], 0
	v_mfma_i32_16x16x64_i8 v[36:39], v[168:171], v[218:221], 0
	v_mfma_i32_16x16x64_i8 v[32:35], v[176:179], v[218:221], 0
	v_mfma_i32_16x16x64_i8 v[60:63], v[172:175], v[198:201], v[60:63]
	v_mfma_i32_16x16x64_i8 v[56:59], v[190:193], v[198:201], v[56:59]
	v_mfma_i32_16x16x64_i8 v[52:55], v[172:175], v[206:209], v[52:55]
	v_mfma_i32_16x16x64_i8 v[48:51], v[190:193], v[206:209], v[48:51]
	v_mfma_i32_16x16x64_i8 v[44:47], v[172:175], v[214:217], v[44:47]
	v_mfma_i32_16x16x64_i8 v[40:43], v[190:193], v[214:217], v[40:43]
	v_mfma_i32_16x16x64_i8 v[36:39], v[172:175], v[222:225], v[36:39]
	v_mfma_i32_16x16x64_i8 v[32:35], v[190:193], v[222:225], v[32:35]
	s_setprio 0
	s_barrier
	s_add_i32 s76, s65, s34
	v_lshl_add_u64 v[226:227], s[48:49], 0, v[130:131]
	s_mov_b32 m0, s76
	ds_read_b128 v[194:197], v185 offset:16384
	ds_read_b128 v[198:201], v185 offset:17408
	ds_read_b128 v[202:205], v185 offset:18432
	ds_read_b128 v[206:209], v185 offset:19456
	ds_read_b128 v[210:213], v185 offset:20480
	ds_read_b128 v[214:217], v185 offset:21504
	ds_read_b128 v[218:221], v185 offset:22528
	ds_read_b128 v[222:225], v185 offset:23552
	global_load_lds_dwordx4 v[226:227], off
	s_add_i32 m0, s76, 0x2000
	s_add_u32 s76, s48, 0x40000
	v_lshl_add_u64 v[228:229], s[48:49], 0, v[134:135]
	s_addc_u32 s77, s49, 0
	s_add_i32 s78, s66, s34
	global_load_lds_dwordx4 v[228:229], off
	v_lshl_add_u64 v[230:231], s[76:77], 0, v[130:131]
	s_mov_b32 m0, s78
	v_lshl_add_u64 v[232:233], s[50:51], 0, v[132:133]
	global_load_lds_dwordx4 v[230:231], off
	v_lshl_add_u64 v[230:231], s[76:77], 0, v[134:135]
	s_add_i32 m0, s78, 0x2000
	s_nop 0
	global_load_lds_dwordx4 v[230:231], off
	v_lshl_add_u64 v[230:231], s[50:51], 0, v[128:129]
	s_mov_b32 m0, s35
	s_nop 0
	global_load_lds_dwordx4 v[230:231], off
	s_mov_b32 m0, s54
	s_nop 0
	global_load_lds_dwordx4 v[232:233], off
	s_waitcnt vmcnt(8)
	s_waitcnt lgkmcnt(0)
	s_barrier
	s_setprio 1
	s_waitcnt lgkmcnt(0)
	v_mfma_i32_16x16x64_i8 v[92:95], v[152:155], v[194:197], 0
	v_mfma_i32_16x16x64_i8 v[88:91], v[160:163], v[194:197], 0
	v_mfma_i32_16x16x64_i8 v[84:87], v[152:155], v[202:205], 0
	v_mfma_i32_16x16x64_i8 v[80:83], v[160:163], v[202:205], 0
	v_mfma_i32_16x16x64_i8 v[76:79], v[152:155], v[210:213], 0
	v_mfma_i32_16x16x64_i8 v[72:75], v[160:163], v[210:213], 0
	v_mfma_i32_16x16x64_i8 v[68:71], v[152:155], v[218:221], 0
	v_mfma_i32_16x16x64_i8 v[64:67], v[160:163], v[218:221], 0
	v_mfma_i32_16x16x64_i8 v[92:95], v[156:159], v[198:201], v[92:95]
	v_mfma_i32_16x16x64_i8 v[88:91], v[164:167], v[198:201], v[88:91]
	v_mfma_i32_16x16x64_i8 v[84:87], v[156:159], v[206:209], v[84:87]
	v_mfma_i32_16x16x64_i8 v[80:83], v[164:167], v[206:209], v[80:83]
	v_mfma_i32_16x16x64_i8 v[76:79], v[156:159], v[214:217], v[76:79]
	v_mfma_i32_16x16x64_i8 v[72:75], v[164:167], v[214:217], v[72:75]
	v_mfma_i32_16x16x64_i8 v[68:71], v[156:159], v[222:225], v[68:71]
	v_mfma_i32_16x16x64_i8 v[64:67], v[164:167], v[222:225], v[64:67]
	s_setprio 0
	s_setprio 1
	v_mfma_i32_16x16x64_i8 v[28:31], v[168:171], v[194:197], 0
	v_mfma_i32_16x16x64_i8 v[24:27], v[176:179], v[194:197], 0
	v_mfma_i32_16x16x64_i8 v[20:23], v[168:171], v[202:205], 0
	v_mfma_i32_16x16x64_i8 v[16:19], v[176:179], v[202:205], 0
	v_mfma_i32_16x16x64_i8 v[12:15], v[168:171], v[210:213], 0
	v_mfma_i32_16x16x64_i8 v[8:11], v[176:179], v[210:213], 0
	v_mfma_i32_16x16x64_i8 v[4:7], v[168:171], v[218:221], 0
	v_mfma_i32_16x16x64_i8 v[0:3], v[176:179], v[218:221], 0
	v_mfma_i32_16x16x64_i8 v[28:31], v[172:175], v[198:201], v[28:31]
	v_mfma_i32_16x16x64_i8 v[24:27], v[190:193], v[198:201], v[24:27]
	v_mfma_i32_16x16x64_i8 v[20:23], v[172:175], v[206:209], v[20:23]
	v_mfma_i32_16x16x64_i8 v[16:19], v[190:193], v[206:209], v[16:19]
	v_mfma_i32_16x16x64_i8 v[12:15], v[172:175], v[214:217], v[12:15]
	v_mfma_i32_16x16x64_i8 v[8:11], v[190:193], v[214:217], v[8:11]
	v_mfma_i32_16x16x64_i8 v[4:7], v[172:175], v[222:225], v[4:7]
	v_mfma_i32_16x16x64_i8 v[0:3], v[190:193], v[222:225], v[0:3]
	s_setprio 0
	s_barrier
; #define PG8_STAGE(bufoff, gbase, voff) do { _Pragma("unroll") for (int _i = 0; _i < 2; ++_i) \
;         __builtin_amdgcn_global_load_lds((const unsigned*)((const char*)(gbase) + (voff)[_i]), (LAS unsigned*)(lds + (bufoff) + ldsw + _i * 8192), 16, 0, 0); } while (0)
; #define PG8_LDA(dst, b, h) do { _Pragma("unroll") for (int m = 0; m < 4; ++m) _Pragma("unroll") for (int k = 0; k < 2; ++k) dst[m][k] = *(const LAS bf16x8*)(lds + PG8_SA(b, h) + aoff + m * 2048 + k * 1024); } while (0)
; #define PG8_LDB(dst, b, h) do { _Pragma("unroll") for (int n = 0; n < 2; ++n) _Pragma("unroll") for (int k = 0; k < 2; ++k) dst[n][k] = *(const LAS bf16x8*)(lds + PG8_SB(b, h) + boff + n * 2048 + k * 1024); } while (0)
; #define PG8_WAIT_V(n) asm volatile("s_waitcnt vmcnt(" #n ")" ::: "memory")
; #define PG8_WAIT_L(n) asm volatile("s_waitcnt lgkmcnt(" #n ")" ::: "memory")
; #define PG8_BAR __builtin_amdgcn_s_barrier()
; #define PG8_SCHED __builtin_amdgcn_sched_barrier(0)
;     ...
;             PG8_LDB(B0, 1, 0); PG8_LDB(B1, 1, 1); PG8_SCHED; PG8_LDA(At, 1, 0); PG8_STAGE(PG8_SA(0, 1), a2 + hstep, voffA);
;             PG8_WAIT_V(8); PG8_WAIT_L(0); PG8_BAR; PG8_MMA(0, 0, At, B0); PG8_MMA(0, 1, At, B1); PG8_BAR; PG8_SCHED;
;             PG8_LDA(At, 1, 1); PG8_STAGE(PG8_SB(1, 0), b3, voffB); PG8_STAGE(PG8_SB(1, 1), b3 + hstep, voffB); PG8_STAGE(PG8_SA(1, 0), a3, voffA);
;             PG8_WAIT_V(8); PG8_WAIT_L(0); PG8_BAR; PG8_MMA(1, 0, At, B0); PG8_MMA(1, 1, At, B1); PG8_BAR; PG8_SCHED;
;         }
	s_add_i32 s76, 0, 0x18000
	v_add_u32_e32 v136, s76, v181
	s_add_i32 s77, 0, 0x1c000
	ds_read_b128 v[152:155], v136
	ds_read_b128 v[156:159], v136 offset:1024
	ds_read_b128 v[160:163], v136 offset:2048
	ds_read_b128 v[164:167], v136 offset:3072
	v_add_u32_e32 v136, s77, v181
	ds_read_b128 v[168:171], v136
	ds_read_b128 v[172:175], v136 offset:1024
	ds_read_b128 v[176:179], v136 offset:2048
	ds_read_b128 v[190:193], v136 offset:3072
	s_add_u32 s50, s50, 0x40000
	s_addc_u32 s51, s51, 0
	s_mov_b32 m0, s55
	v_lshl_add_u64 v[234:235], s[50:51], 0, v[128:129]
	ds_read_b128 v[194:197], v185 offset:32768
	ds_read_b128 v[198:201], v185 offset:33792
	ds_read_b128 v[202:205], v185 offset:34816
	ds_read_b128 v[206:209], v185 offset:35840
	ds_read_b128 v[210:213], v185 offset:36864
	ds_read_b128 v[214:217], v185 offset:37888
	ds_read_b128 v[218:221], v185 offset:38912
	ds_read_b128 v[222:225], v185 offset:39936
	global_load_lds_dwordx4 v[234:235], off
	v_lshl_add_u64 v[234:235], s[50:51], 0, v[132:133]
	s_mov_b32 m0, s58
	s_nop 0
	global_load_lds_dwordx4 v[234:235], off
	s_waitcnt vmcnt(8)
	s_waitcnt lgkmcnt(0)
	s_barrier
	s_setprio 1
	s_waitcnt lgkmcnt(0)
	v_mfma_i32_16x16x64_i8 v[124:127], v[152:155], v[194:197], v[124:127]
	v_mfma_i32_16x16x64_i8 v[120:123], v[160:163], v[194:197], v[120:123]
	v_mfma_i32_16x16x64_i8 v[116:119], v[152:155], v[202:205], v[116:119]
	v_mfma_i32_16x16x64_i8 v[112:115], v[160:163], v[202:205], v[112:115]
	v_mfma_i32_16x16x64_i8 v[108:111], v[152:155], v[210:213], v[108:111]
	v_mfma_i32_16x16x64_i8 v[104:107], v[160:163], v[210:213], v[104:107]
	v_mfma_i32_16x16x64_i8 v[100:103], v[152:155], v[218:221], v[100:103]
	v_mfma_i32_16x16x64_i8 v[96:99], v[160:163], v[218:221], v[96:99]
	v_mfma_i32_16x16x64_i8 v[124:127], v[156:159], v[198:201], v[124:127]
	v_mfma_i32_16x16x64_i8 v[120:123], v[164:167], v[198:201], v[120:123]
	v_mfma_i32_16x16x64_i8 v[116:119], v[156:159], v[206:209], v[116:119]
	v_mfma_i32_16x16x64_i8 v[112:115], v[164:167], v[206:209], v[112:115]
	v_mfma_i32_16x16x64_i8 v[108:111], v[156:159], v[214:217], v[108:111]
	v_mfma_i32_16x16x64_i8 v[104:107], v[164:167], v[214:217], v[104:107]
	v_mfma_i32_16x16x64_i8 v[100:103], v[156:159], v[222:225], v[100:103]
	v_mfma_i32_16x16x64_i8 v[96:99], v[164:167], v[222:225], v[96:99]
	s_setprio 0
	s_setprio 1
	v_mfma_i32_16x16x64_i8 v[60:63], v[168:171], v[194:197], v[60:63]
	v_mfma_i32_16x16x64_i8 v[56:59], v[176:179], v[194:197], v[56:59]
	v_mfma_i32_16x16x64_i8 v[52:55], v[168:171], v[202:205], v[52:55]
	v_mfma_i32_16x16x64_i8 v[48:51], v[176:179], v[202:205], v[48:51]
	v_mfma_i32_16x16x64_i8 v[44:47], v[168:171], v[210:213], v[44:47]
	v_mfma_i32_16x16x64_i8 v[40:43], v[176:179], v[210:213], v[40:43]
	v_mfma_i32_16x16x64_i8 v[36:39], v[168:171], v[218:221], v[36:39]
	v_mfma_i32_16x16x64_i8 v[32:35], v[176:179], v[218:221], v[32:35]
	v_mfma_i32_16x16x64_i8 v[60:63], v[172:175], v[198:201], v[60:63]
	v_mfma_i32_16x16x64_i8 v[56:59], v[190:193], v[198:201], v[56:59]
	v_mfma_i32_16x16x64_i8 v[52:55], v[172:175], v[206:209], v[52:55]
	v_mfma_i32_16x16x64_i8 v[48:51], v[190:193], v[206:209], v[48:51]
	v_mfma_i32_16x16x64_i8 v[44:47], v[172:175], v[214:217], v[44:47]
	v_mfma_i32_16x16x64_i8 v[40:43], v[190:193], v[214:217], v[40:43]
	v_mfma_i32_16x16x64_i8 v[36:39], v[172:175], v[222:225], v[36:39]
	v_mfma_i32_16x16x64_i8 v[32:35], v[190:193], v[222:225], v[32:35]
	s_setprio 0
	s_barrier
	s_add_i32 s50, s76, s34
	v_lshl_add_u64 v[226:227], v[226:227], 0, s[18:19]
	s_mov_b32 m0, s50
	ds_read_b128 v[194:197], v185 offset:49152
	ds_read_b128 v[198:201], v185 offset:50176
	ds_read_b128 v[202:205], v185 offset:51200
	ds_read_b128 v[206:209], v185 offset:52224
	ds_read_b128 v[210:213], v185 offset:53248
	ds_read_b128 v[214:217], v185 offset:54272
	ds_read_b128 v[218:221], v185 offset:55296
	ds_read_b128 v[222:225], v185 offset:56320
	global_load_lds_dwordx4 v[226:227], off
	s_add_i32 m0, s50, 0x2000
	s_add_u32 s48, s48, 0x40080
	v_lshl_add_u64 v[226:227], v[228:229], 0, s[18:19]
	s_addc_u32 s49, s49, 0
	s_add_i32 s50, s77, s34
	global_load_lds_dwordx4 v[226:227], off
	v_lshl_add_u64 v[226:227], s[48:49], 0, v[130:131]
	s_mov_b32 m0, s50
	s_nop 0
	global_load_lds_dwordx4 v[226:227], off
	v_lshl_add_u64 v[226:227], s[48:49], 0, v[134:135]
	s_add_i32 m0, s50, 0x2000
	s_nop 0
	global_load_lds_dwordx4 v[226:227], off
	v_lshl_add_u64 v[226:227], v[230:231], 0, s[18:19]
	s_mov_b32 m0, s61
	s_nop 0
	global_load_lds_dwordx4 v[226:227], off
	v_lshl_add_u64 v[226:227], v[232:233], 0, s[18:19]
	s_mov_b32 m0, s62
	s_nop 0
	global_load_lds_dwordx4 v[226:227], off
	s_waitcnt vmcnt(8)
	s_waitcnt lgkmcnt(0)
	s_barrier
	s_setprio 1
	s_waitcnt lgkmcnt(0)
	v_mfma_i32_16x16x64_i8 v[92:95], v[152:155], v[194:197], v[92:95]
	v_mfma_i32_16x16x64_i8 v[88:91], v[160:163], v[194:197], v[88:91]
	v_mfma_i32_16x16x64_i8 v[84:87], v[152:155], v[202:205], v[84:87]
	v_mfma_i32_16x16x64_i8 v[80:83], v[160:163], v[202:205], v[80:83]
	v_mfma_i32_16x16x64_i8 v[76:79], v[152:155], v[210:213], v[76:79]
	v_mfma_i32_16x16x64_i8 v[72:75], v[160:163], v[210:213], v[72:75]
	v_mfma_i32_16x16x64_i8 v[68:71], v[152:155], v[218:221], v[68:71]
	v_mfma_i32_16x16x64_i8 v[64:67], v[160:163], v[218:221], v[64:67]
	v_mfma_i32_16x16x64_i8 v[92:95], v[156:159], v[198:201], v[92:95]
	v_mfma_i32_16x16x64_i8 v[88:91], v[164:167], v[198:201], v[88:91]
	v_mfma_i32_16x16x64_i8 v[84:87], v[156:159], v[206:209], v[84:87]
	v_mfma_i32_16x16x64_i8 v[80:83], v[164:167], v[206:209], v[80:83]
	v_mfma_i32_16x16x64_i8 v[76:79], v[156:159], v[214:217], v[76:79]
	v_mfma_i32_16x16x64_i8 v[72:75], v[164:167], v[214:217], v[72:75]
	v_mfma_i32_16x16x64_i8 v[68:71], v[156:159], v[222:225], v[68:71]
	v_mfma_i32_16x16x64_i8 v[64:67], v[164:167], v[222:225], v[64:67]
	s_setprio 0
	s_setprio 1
	v_mfma_i32_16x16x64_i8 v[28:31], v[168:171], v[194:197], v[28:31]
	v_mfma_i32_16x16x64_i8 v[24:27], v[176:179], v[194:197], v[24:27]
	v_mfma_i32_16x16x64_i8 v[20:23], v[168:171], v[202:205], v[20:23]
	v_mfma_i32_16x16x64_i8 v[16:19], v[176:179], v[202:205], v[16:19]
	v_mfma_i32_16x16x64_i8 v[12:15], v[168:171], v[210:213], v[12:15]
	v_mfma_i32_16x16x64_i8 v[8:11], v[176:179], v[210:213], v[8:11]
	v_mfma_i32_16x16x64_i8 v[4:7], v[168:171], v[218:221], v[4:7]
	v_mfma_i32_16x16x64_i8 v[0:3], v[176:179], v[218:221], v[0:3]
	v_mfma_i32_16x16x64_i8 v[28:31], v[172:175], v[198:201], v[28:31]
	v_mfma_i32_16x16x64_i8 v[24:27], v[190:193], v[198:201], v[24:27]
	v_mfma_i32_16x16x64_i8 v[20:23], v[172:175], v[206:209], v[20:23]
	v_mfma_i32_16x16x64_i8 v[16:19], v[190:193], v[206:209], v[16:19]
	v_mfma_i32_16x16x64_i8 v[12:15], v[172:175], v[214:217], v[12:15]
	v_mfma_i32_16x16x64_i8 v[8:11], v[190:193], v[214:217], v[8:11]
	v_mfma_i32_16x16x64_i8 v[4:7], v[172:175], v[222:225], v[4:7]
	v_mfma_i32_16x16x64_i8 v[0:3], v[190:193], v[222:225], v[0:3]
	s_setprio 0
	s_barrier
	s_add_i32 s75, s75, 2
	s_add_u32 s46, s46, 0x100
	s_addc_u32 s47, s47, 0
	s_add_u32 s73, s73, 0x100
	s_addc_u32 s74, s74, 0
	s_cmp_gt_u32 s75, 13
	s_cbranch_scc0 .LBB0_3955

; #define PG8_STAGE(bufoff, gbase, voff) do { _Pragma("unroll") for (int _i = 0; _i < 2; ++_i) \
;         __builtin_amdgcn_global_load_lds((const unsigned*)((const char*)(gbase) + (voff)[_i]), (LAS unsigned*)(lds + (bufoff) + ldsw + _i * 8192), 16, 0, 0); } while (0)
; #define PG8_LDA(dst, b, h) do { _Pragma("unroll") for (int m = 0; m < 4; ++m) _Pragma("unroll") for (int k = 0; k < 2; ++k) dst[m][k] = *(const LAS bf16x8*)(lds + PG8_SA(b, h) + aoff + m * 2048 + k * 1024); } while (0)
; #define PG8_LDB(dst, b, h) do { _Pragma("unroll") for (int n = 0; n < 2; ++n) _Pragma("unroll") for (int k = 0; k < 2; ++k) dst[n][k] = *(const LAS bf16x8*)(lds + PG8_SB(b, h) + boff + n * 2048 + k * 1024); } while (0)
; #define PG8_SCHED __builtin_amdgcn_sched_barrier(0)
;     __device__ __forceinline__ bool next(int i, Unit& u) const {
;         const long L = (long)i * G + c; if (L >= nwg) return false;
;         int wgid = (int)L; { const int q = nwg / NXCD, r = nwg % NXCD, xcd = wgid % NXCD, off = wgid / NXCD; wgid = (xcd < r ? xcd * (q + 1) : r * (q + 1) + (xcd - r) * q) + off; }
;         const int nig = WGM * nN, gid = wgid / nig, fm = gid * WGM, gsz = (nM - fm) < WGM ? (nM - fm) : WGM;
;         u.pm = fm + ((wgid % nig) % gsz); u.pn = (wgid % nig) / gsz; u.e = 0; u.kt0 = 0; u.nkt = nt; u.buf = 0;
;     ...
;     for (;;) {
;         const bool has_next = S.next(ui + 1, nxt);
;         const char* nA = has_next ? (const char*)g.A + (size_t)nxt.pm * tstep + (size_t)nxt.kt0 * kstep : cA; const char* nB = has_next ? (const char*)g.Bt + (size_t)nxt.e * g.estride + (size_t)nxt.pn * tstep + (size_t)nxt.kt0 * kstep : cB;
;         const int nt = cur.nkt;
;         for (int t = 0; t < nt; t += 2) {
;             const bool last = (t == nt - 2);
;             const char* a1 = cA + (size_t)(t + 1) * kstep;
;             const char* a2 = last ? nA : cA + (size_t)(t + 2) * kstep; const char* b2 = last ? nB : cB + (size_t)(t + 2) * kstep;
;             const char* a3 = a2 + kstep; const char* b3 = b2 + kstep;
;             PG8_LDB(B0, 0, 0); PG8_LDB(B1, 0, 1); PG8_SCHED; PG8_LDA(At, 0, 0); PG8_STAGE(PG8_SA(1, 1), a1 + hstep, voffA);
.LBB0_4105:
	ds_read_b128 v[24:27], v106
	ds_read_b128 v[28:31], v106 offset:1024
	ds_read_b128 v[32:35], v106 offset:2048
	ds_read_b128 v[36:39], v106 offset:3072
	ds_read_b128 v[110:113], v107
	ds_read_b128 v[114:117], v107 offset:1024
	ds_read_b128 v[118:121], v107 offset:2048
	ds_read_b128 v[122:125], v107 offset:3072
	ds_read_b128 v[126:129], v107 offset:4096
	ds_read_b128 v[130:133], v107 offset:5120
	ds_read_b128 v[134:137], v107 offset:6144
	ds_read_b128 v[138:141], v107 offset:7168
	s_add_i32 s48, s48, 1
	s_mul_i32 s3, s48, s58
	s_mul_hi_u32 s20, s48, s23
	s_add_i32 s20, s20, s3
	s_mul_i32 s3, s48, s23
	s_add_u32 s28, s3, s22
	s_addc_u32 s29, s20, s17
	v_cmp_gt_i64_e64 s[30:31], s[28:29], 63
	v_cmp_lt_i64_e64 s[20:21], s[28:29], 64
	s_and_b64 vcc, exec, s[30:31]
	s_cbranch_vccnz .LBB0_4111
	s_ashr_i32 s3, s28, 31
	s_lshr_b32 s3, s3, 29
	s_add_i32 s3, s28, s3
	s_and_b32 s24, s3, -8
	s_sub_i32 s26, s28, s24
	s_cmp_gt_i32 s26, -1
	s_mov_b64 s[24:25], -1
	s_cbranch_scc0 .LBB0_4108
	s_lshl_b32 s27, s26, 3
	s_mov_b64 s[24:25], 0

; #define PG8_STAGE(bufoff, gbase, voff) do { _Pragma("unroll") for (int _i = 0; _i < 2; ++_i) \
;         __builtin_amdgcn_global_load_lds((const unsigned*)((const char*)(gbase) + (voff)[_i]), (LAS unsigned*)(lds + (bufoff) + ldsw + _i * 8192), 16, 0, 0); } while (0)
; #define PG8_LDA(dst, b, h) do { _Pragma("unroll") for (int m = 0; m < 4; ++m) _Pragma("unroll") for (int k = 0; k < 2; ++k) dst[m][k] = *(const LAS bf16x8*)(lds + PG8_SA(b, h) + aoff + m * 2048 + k * 1024); } while (0)
; #define PG8_LDB(dst, b, h) do { _Pragma("unroll") for (int n = 0; n < 2; ++n) _Pragma("unroll") for (int k = 0; k < 2; ++k) dst[n][k] = *(const LAS bf16x8*)(lds + PG8_SB(b, h) + boff + n * 2048 + k * 1024); } while (0)
; #define PG8_WAIT_V(n) asm volatile("s_waitcnt vmcnt(" #n ")" ::: "memory")
; #define PG8_WAIT_L(n) asm volatile("s_waitcnt lgkmcnt(" #n ")" ::: "memory")
; #define PG8_BAR __builtin_amdgcn_s_barrier()
; #define PG8_SCHED __builtin_amdgcn_sched_barrier(0)
;     ...
;         const char* nA = has_next ? (const char*)g.A + (size_t)nxt.pm * tstep + (size_t)nxt.kt0 * kstep : cA; const char* nB = has_next ? (const char*)g.Bt + (size_t)nxt.e * g.estride + (size_t)nxt.pn * tstep + (size_t)nxt.kt0 * kstep : cB;
;         const int nt = cur.nkt;
;         for (int t = 0; t < nt; t += 2) {
;             const bool last = (t == nt - 2);
;             const char* a1 = cA + (size_t)(t + 1) * kstep;
;             const char* a2 = last ? nA : cA + (size_t)(t + 2) * kstep; const char* b2 = last ? nB : cB + (size_t)(t + 2) * kstep;
;             const char* a3 = a2 + kstep; const char* b3 = b2 + kstep;
;             PG8_LDB(B0, 0, 0); PG8_LDB(B1, 0, 1); PG8_SCHED; PG8_LDA(At, 0, 0); PG8_STAGE(PG8_SA(1, 1), a1 + hstep, voffA);
;             PG8_WAIT_V(8); PG8_WAIT_L(0); PG8_BAR; PG8_MMA(0, 0, At, B0); PG8_MMA(0, 1, At, B1); PG8_BAR; PG8_SCHED;
;             PG8_LDA(At, 0, 1); PG8_STAGE(PG8_SB(0, 0), b2, voffB); PG8_STAGE(PG8_SB(0, 1), b2 + hstep, voffB); PG8_STAGE(PG8_SA(0, 0), a2, voffA);
;             PG8_WAIT_V(8); PG8_WAIT_L(0); PG8_BAR; PG8_MMA(1, 0, At, B0); PG8_MMA(1, 1, At, B1); PG8_BAR; PG8_SCHED;
.LBB0_4111:
	s_ashr_i32 s27, s26, 31
	s_lshl_b64 s[28:29], s[26:27], 19
	s_add_u32 s28, s19, s28
	s_addc_u32 s29, s34, s29
	s_and_b64 s[30:31], s[20:21], exec
	s_cselect_b32 s3, s29, s37
	s_cselect_b32 s27, s28, s36
	s_ashr_i32 s25, s24, 31
	s_lshl_b64 s[30:31], s[24:25], 19
	s_add_u32 s30, s4, s30
	s_addc_u32 s31, s5, s31
	s_and_b64 s[40:41], s[20:21], exec
	s_cselect_b32 s25, s31, s39
	s_cselect_b32 s62, s30, s38
	s_add_u32 s36, s36, 0x40080
	s_addc_u32 s37, s37, 0
	s_add_u32 s63, s38, 0x100
	s_addc_u32 s64, s39, 0
	s_mov_b32 s65, -2
	s_add_u32 s38, s36, 0xfffc0080
	s_addc_u32 s39, s37, -1
	s_cmp_eq_u32 s65, 12
	s_cselect_b32 s41, s3, s39
	s_cselect_b32 s40, s27, s38
	s_cselect_b32 s39, s25, s64
	s_cselect_b32 s38, s62, s63
	v_lshl_add_u64 v[102:103], s[36:37], 0, v[98:99]
	s_add_i32 m0, s42, 0xc000
	global_load_lds_dwordx4 v[102:103], off
	v_lshl_add_u64 v[102:103], s[36:37], 0, v[100:101]
	s_add_i32 m0, s42, 0xe000
	s_nop 0
	global_load_lds_dwordx4 v[102:103], off
	s_waitcnt vmcnt(8)
	s_waitcnt lgkmcnt(0)
	s_barrier
	s_setprio 1
	s_waitcnt lgkmcnt(0)
	v_mfma_i32_16x16x64_i8 v[76:79], v[24:27], v[110:113], 0
	v_mfma_i32_16x16x64_i8 v[72:75], v[32:35], v[110:113], 0
	v_mfma_i32_16x16x64_i8 v[68:71], v[24:27], v[118:121], 0
	v_mfma_i32_16x16x64_i8 v[64:67], v[32:35], v[118:121], 0
	v_mfma_i32_16x16x64_i8 v[60:63], v[24:27], v[126:129], 0
	v_mfma_i32_16x16x64_i8 v[56:59], v[32:35], v[126:129], 0
	v_mfma_i32_16x16x64_i8 v[52:55], v[24:27], v[134:137], 0
	v_mfma_i32_16x16x64_i8 v[48:51], v[32:35], v[134:137], 0
	v_mfma_i32_16x16x64_i8 v[76:79], v[28:31], v[114:117], v[76:79]
	v_mfma_i32_16x16x64_i8 v[72:75], v[36:39], v[114:117], v[72:75]
	v_mfma_i32_16x16x64_i8 v[68:71], v[28:31], v[122:125], v[68:71]
	v_mfma_i32_16x16x64_i8 v[64:67], v[36:39], v[122:125], v[64:67]
	v_mfma_i32_16x16x64_i8 v[60:63], v[28:31], v[130:133], v[60:63]
	v_mfma_i32_16x16x64_i8 v[56:59], v[36:39], v[130:133], v[56:59]
	v_mfma_i32_16x16x64_i8 v[52:55], v[28:31], v[138:141], v[52:55]
	v_mfma_i32_16x16x64_i8 v[48:51], v[36:39], v[138:141], v[48:51]
	s_setprio 0
	s_setprio 1
	s_setprio 0
	s_barrier
	s_add_i32 s66, s59, s35
	v_lshl_add_u64 v[102:103], s[38:39], 0, v[82:83]
	s_mov_b32 m0, s66
	ds_read_b128 v[110:113], v107 offset:16384
	ds_read_b128 v[114:117], v107 offset:17408
	ds_read_b128 v[118:121], v107 offset:18432
	ds_read_b128 v[122:125], v107 offset:19456
	ds_read_b128 v[126:129], v107 offset:20480
	ds_read_b128 v[130:133], v107 offset:21504
	ds_read_b128 v[134:137], v107 offset:22528
	ds_read_b128 v[138:141], v107 offset:23552
	global_load_lds_dwordx4 v[102:103], off
	s_add_i32 m0, s66, 0x2000
	s_add_u32 s66, s38, 0x40000
	v_lshl_add_u64 v[142:143], s[38:39], 0, v[86:87]
	s_addc_u32 s67, s39, 0
	global_load_lds_dwordx4 v[142:143], off
	v_lshl_add_u64 v[144:145], s[66:67], 0, v[82:83]
	s_mov_b32 m0, s43
	v_lshl_add_u64 v[146:147], s[40:41], 0, v[84:85]
	global_load_lds_dwordx4 v[144:145], off
	v_lshl_add_u64 v[144:145], s[66:67], 0, v[86:87]
	s_mov_b32 m0, s44
	s_nop 0
	global_load_lds_dwordx4 v[144:145], off
	v_lshl_add_u64 v[144:145], s[40:41], 0, v[80:81]
	s_mov_b32 m0, s42
	s_nop 0
	global_load_lds_dwordx4 v[144:145], off
	s_mov_b32 m0, s45
	s_nop 0
	global_load_lds_dwordx4 v[146:147], off
	s_waitcnt vmcnt(8)
	s_waitcnt lgkmcnt(0)
	s_barrier
	s_setprio 1
	s_waitcnt lgkmcnt(0)
	v_mfma_i32_16x16x64_i8 v[44:47], v[24:27], v[110:113], 0
	v_mfma_i32_16x16x64_i8 v[40:43], v[32:35], v[110:113], 0
	v_mfma_i32_16x16x64_i8 v[20:23], v[24:27], v[118:121], 0
	v_mfma_i32_16x16x64_i8 v[16:19], v[32:35], v[118:121], 0
	v_mfma_i32_16x16x64_i8 v[12:15], v[24:27], v[126:129], 0
	v_mfma_i32_16x16x64_i8 v[8:11], v[32:35], v[126:129], 0
	v_mfma_i32_16x16x64_i8 v[4:7], v[24:27], v[134:137], 0
	v_mfma_i32_16x16x64_i8 v[0:3], v[32:35], v[134:137], 0
	v_mfma_i32_16x16x64_i8 v[44:47], v[28:31], v[114:117], v[44:47]
	v_mfma_i32_16x16x64_i8 v[40:43], v[36:39], v[114:117], v[40:43]
	v_mfma_i32_16x16x64_i8 v[20:23], v[28:31], v[122:125], v[20:23]
	v_mfma_i32_16x16x64_i8 v[16:19], v[36:39], v[122:125], v[16:19]
	v_mfma_i32_16x16x64_i8 v[12:15], v[28:31], v[130:133], v[12:15]
	v_mfma_i32_16x16x64_i8 v[8:11], v[36:39], v[130:133], v[8:11]
	v_mfma_i32_16x16x64_i8 v[4:7], v[28:31], v[138:141], v[4:7]
	v_mfma_i32_16x16x64_i8 v[0:3], v[36:39], v[138:141], v[0:3]
	s_setprio 0
	s_setprio 1
	s_setprio 0
	s_barrier
; #define PG8_STAGE(bufoff, gbase, voff) do { _Pragma("unroll") for (int _i = 0; _i < 2; ++_i) \
;         __builtin_amdgcn_global_load_lds((const unsigned*)((const char*)(gbase) + (voff)[_i]), (LAS unsigned*)(lds + (bufoff) + ldsw + _i * 8192), 16, 0, 0); } while (0)
; #define PG8_LDA(dst, b, h) do { _Pragma("unroll") for (int m = 0; m < 4; ++m) _Pragma("unroll") for (int k = 0; k < 2; ++k) dst[m][k] = *(const LAS bf16x8*)(lds + PG8_SA(b, h) + aoff + m * 2048 + k * 1024); } while (0)
; #define PG8_LDB(dst, b, h) do { _Pragma("unroll") for (int n = 0; n < 2; ++n) _Pragma("unroll") for (int k = 0; k < 2; ++k) dst[n][k] = *(const LAS bf16x8*)(lds + PG8_SB(b, h) + boff + n * 2048 + k * 1024); } while (0)
; #define PG8_WAIT_V(n) asm volatile("s_waitcnt vmcnt(" #n ")" ::: "memory")
; #define PG8_WAIT_L(n) asm volatile("s_waitcnt lgkmcnt(" #n ")" ::: "memory")
; #define PG8_BAR __builtin_amdgcn_s_barrier()
; #define PG8_SCHED __builtin_amdgcn_sched_barrier(0)
;     ...
;             PG8_LDB(B0, 1, 0); PG8_LDB(B1, 1, 1); PG8_SCHED; PG8_LDA(At, 1, 0); PG8_STAGE(PG8_SA(0, 1), a2 + hstep, voffA);
;             PG8_WAIT_V(8); PG8_WAIT_L(0); PG8_BAR; PG8_MMA(0, 0, At, B0); PG8_MMA(0, 1, At, B1); PG8_BAR; PG8_SCHED;
;             PG8_LDA(At, 1, 1); PG8_STAGE(PG8_SB(1, 0), b3, voffB); PG8_STAGE(PG8_SB(1, 1), b3 + hstep, voffB); PG8_STAGE(PG8_SA(1, 0), a3, voffA);
;             PG8_WAIT_V(8); PG8_WAIT_L(0); PG8_BAR; PG8_MMA(1, 0, At, B0); PG8_MMA(1, 1, At, B1); PG8_BAR; PG8_SCHED;
;         }
	s_add_i32 s66, 0, 0x18000
	v_add_u32_e32 v36, s66, v105
	ds_read_b128 v[24:27], v36
	ds_read_b128 v[28:31], v36 offset:1024
	ds_read_b128 v[32:35], v36 offset:2048
	ds_read_b128 v[36:39], v36 offset:3072
	s_add_u32 s40, s40, 0x40000
	s_addc_u32 s41, s41, 0
	s_mov_b32 m0, s46
	v_lshl_add_u64 v[148:149], s[40:41], 0, v[80:81]
	ds_read_b128 v[110:113], v107 offset:32768
	ds_read_b128 v[114:117], v107 offset:33792
	ds_read_b128 v[118:121], v107 offset:34816
	ds_read_b128 v[122:125], v107 offset:35840
	ds_read_b128 v[126:129], v107 offset:36864
	ds_read_b128 v[130:133], v107 offset:37888
	ds_read_b128 v[134:137], v107 offset:38912
	ds_read_b128 v[138:141], v107 offset:39936
	global_load_lds_dwordx4 v[148:149], off
	v_lshl_add_u64 v[148:149], s[40:41], 0, v[84:85]
	s_mov_b32 m0, s47
	s_nop 0
	global_load_lds_dwordx4 v[148:149], off
	s_waitcnt vmcnt(8)
	s_waitcnt lgkmcnt(0)
	s_barrier
	s_setprio 1
	s_waitcnt lgkmcnt(0)
	v_mfma_i32_16x16x64_i8 v[76:79], v[24:27], v[110:113], v[76:79]
	v_mfma_i32_16x16x64_i8 v[72:75], v[32:35], v[110:113], v[72:75]
	v_mfma_i32_16x16x64_i8 v[68:71], v[24:27], v[118:121], v[68:71]
	v_mfma_i32_16x16x64_i8 v[64:67], v[32:35], v[118:121], v[64:67]
	v_mfma_i32_16x16x64_i8 v[60:63], v[24:27], v[126:129], v[60:63]
	v_mfma_i32_16x16x64_i8 v[56:59], v[32:35], v[126:129], v[56:59]
	v_mfma_i32_16x16x64_i8 v[52:55], v[24:27], v[134:137], v[52:55]
	v_mfma_i32_16x16x64_i8 v[48:51], v[32:35], v[134:137], v[48:51]
	v_mfma_i32_16x16x64_i8 v[76:79], v[28:31], v[114:117], v[76:79]
	v_mfma_i32_16x16x64_i8 v[72:75], v[36:39], v[114:117], v[72:75]
	v_mfma_i32_16x16x64_i8 v[68:71], v[28:31], v[122:125], v[68:71]
	v_mfma_i32_16x16x64_i8 v[64:67], v[36:39], v[122:125], v[64:67]
	v_mfma_i32_16x16x64_i8 v[60:63], v[28:31], v[130:133], v[60:63]
	v_mfma_i32_16x16x64_i8 v[56:59], v[36:39], v[130:133], v[56:59]
	v_mfma_i32_16x16x64_i8 v[52:55], v[28:31], v[138:141], v[52:55]
	v_mfma_i32_16x16x64_i8 v[48:51], v[36:39], v[138:141], v[48:51]
	s_setprio 0
	s_setprio 1
	s_setprio 0
	s_barrier
	s_add_i32 s40, s66, s35
	v_lshl_add_u64 v[102:103], v[102:103], 0, s[8:9]
	s_mov_b32 m0, s40
	ds_read_b128 v[110:113], v107 offset:49152
	ds_read_b128 v[114:117], v107 offset:50176
	ds_read_b128 v[118:121], v107 offset:51200
	ds_read_b128 v[122:125], v107 offset:52224
	ds_read_b128 v[126:129], v107 offset:53248
	ds_read_b128 v[130:133], v107 offset:54272
	ds_read_b128 v[134:137], v107 offset:55296
	ds_read_b128 v[138:141], v107 offset:56320
	global_load_lds_dwordx4 v[102:103], off
	s_add_i32 m0, s40, 0x2000
	s_add_u32 s38, s38, 0x40080
	v_lshl_add_u64 v[102:103], v[142:143], 0, s[8:9]
	s_addc_u32 s39, s39, 0
	global_load_lds_dwordx4 v[102:103], off
	v_lshl_add_u64 v[102:103], s[38:39], 0, v[82:83]
	s_mov_b32 m0, s51
	s_nop 0
	global_load_lds_dwordx4 v[102:103], off
	v_lshl_add_u64 v[102:103], s[38:39], 0, v[86:87]
	s_mov_b32 m0, s55
	s_nop 0
	global_load_lds_dwordx4 v[102:103], off
	v_lshl_add_u64 v[102:103], v[144:145], 0, s[8:9]
	s_mov_b32 m0, s49
	s_nop 0
	global_load_lds_dwordx4 v[102:103], off
	v_lshl_add_u64 v[102:103], v[146:147], 0, s[8:9]
	s_mov_b32 m0, s50
	s_nop 0
	global_load_lds_dwordx4 v[102:103], off
	s_waitcnt vmcnt(8)
	s_waitcnt lgkmcnt(0)
	s_barrier
	s_setprio 1
	s_waitcnt lgkmcnt(0)
	v_mfma_i32_16x16x64_i8 v[44:47], v[24:27], v[110:113], v[44:47]
	v_mfma_i32_16x16x64_i8 v[40:43], v[32:35], v[110:113], v[40:43]
	v_mfma_i32_16x16x64_i8 v[20:23], v[24:27], v[118:121], v[20:23]
	v_mfma_i32_16x16x64_i8 v[16:19], v[32:35], v[118:121], v[16:19]
	v_mfma_i32_16x16x64_i8 v[12:15], v[24:27], v[126:129], v[12:15]
	v_mfma_i32_16x16x64_i8 v[8:11], v[32:35], v[126:129], v[8:11]
	v_mfma_i32_16x16x64_i8 v[4:7], v[24:27], v[134:137], v[4:7]
	v_mfma_i32_16x16x64_i8 v[0:3], v[32:35], v[134:137], v[0:3]
	v_mfma_i32_16x16x64_i8 v[44:47], v[28:31], v[114:117], v[44:47]
	v_mfma_i32_16x16x64_i8 v[40:43], v[36:39], v[114:117], v[40:43]
	v_mfma_i32_16x16x64_i8 v[20:23], v[28:31], v[122:125], v[20:23]
	v_mfma_i32_16x16x64_i8 v[16:19], v[36:39], v[122:125], v[16:19]
	v_mfma_i32_16x16x64_i8 v[12:15], v[28:31], v[130:133], v[12:15]
	v_mfma_i32_16x16x64_i8 v[8:11], v[36:39], v[130:133], v[8:11]
	v_mfma_i32_16x16x64_i8 v[4:7], v[28:31], v[138:141], v[4:7]
	v_mfma_i32_16x16x64_i8 v[0:3], v[36:39], v[138:141], v[0:3]
	s_setprio 0
	s_setprio 1
	s_setprio 0
	s_barrier
	s_add_i32 s65, s65, 2
	s_add_u32 s36, s36, 0x100
	s_addc_u32 s37, s37, 0
	s_add_u32 s63, s63, 0x100
	s_addc_u32 s64, s64, 0
	s_cmp_gt_u32 s65, 13
	s_cbranch_scc0 .LBB0_4112

; #define PG8_STAGE(bufoff, gbase, voff) do { _Pragma("unroll") for (int _i = 0; _i < 2; ++_i) \
;         __builtin_amdgcn_global_load_lds((const unsigned*)((const char*)(gbase) + (voff)[_i]), (LAS unsigned*)(lds + (bufoff) + ldsw + _i * 8192), 16, 0, 0); } while (0)
; #define PG8_LDA(dst, b, h) do { _Pragma("unroll") for (int m = 0; m < 4; ++m) _Pragma("unroll") for (int k = 0; k < 2; ++k) dst[m][k] = *(const LAS bf16x8*)(lds + PG8_SA(b, h) + aoff + m * 2048 + k * 1024); } while (0)
; #define PG8_LDB(dst, b, h) do { _Pragma("unroll") for (int n = 0; n < 2; ++n) _Pragma("unroll") for (int k = 0; k < 2; ++k) dst[n][k] = *(const LAS bf16x8*)(lds + PG8_SB(b, h) + boff + n * 2048 + k * 1024); } while (0)
; #define PG8_SCHED __builtin_amdgcn_sched_barrier(0)
;     __device__ __forceinline__ bool next(int i, Unit& u) const {
;         const long L = (long)i * G + c; if (L >= nwg) return false;
;         int wgid = (int)L; { const int q = nwg / NXCD, r = nwg % NXCD, xcd = wgid % NXCD, off = wgid / NXCD; wgid = (xcd < r ? xcd * (q + 1) : r * (q + 1) + (xcd - r) * q) + off; }
;         const int nig = WGM * nN, gid = wgid / nig, fm = gid * WGM, gsz = (nM - fm) < WGM ? (nM - fm) : WGM;
;         u.pm = fm + ((wgid % nig) % gsz); u.pn = (wgid % nig) / gsz; u.e = 0; u.kt0 = 0; u.nkt = nt; u.buf = 0;
;         if (ts) { int e = 0;
; #pragma unroll
;             for (int j = 1; j < 8; ++j) e += (u.pm >= ts[j]) ? 1 : 0;
;             u.e = e; }
;     ...
;     for (;;) {
;         const bool has_next = S.next(ui + 1, nxt);
;         const char* nA = has_next ? (const char*)g.A + (size_t)nxt.pm * tstep + (size_t)nxt.kt0 * kstep : cA; const char* nB = has_next ? (const char*)g.Bt + (size_t)nxt.e * g.estride + (size_t)nxt.pn * tstep + (size_t)nxt.kt0 * kstep : cB;
;         const int nt = cur.nkt;
;         for (int t = 0; t < nt; t += 2) {
;             const bool last = (t == nt - 2);
;             const char* a1 = cA + (size_t)(t + 1) * kstep;
;             const char* a2 = last ? nA : cA + (size_t)(t + 2) * kstep; const char* b2 = last ? nB : cB + (size_t)(t + 2) * kstep;
;             const char* a3 = a2 + kstep; const char* b3 = b2 + kstep;
;             PG8_LDB(B0, 0, 0); PG8_LDB(B1, 0, 1); PG8_SCHED; PG8_LDA(At, 0, 0); PG8_STAGE(PG8_SA(1, 1), a1 + hstep, voffA);
.LBB0_4733:
	ds_read_b128 v[156:159], v151
	ds_read_b128 v[160:163], v151 offset:1024
	ds_read_b128 v[164:167], v151 offset:2048
	ds_read_b128 v[168:171], v151 offset:3072
	ds_read_b128 v[172:175], v152
	ds_read_b128 v[176:179], v152 offset:1024
	ds_read_b128 v[180:183], v152 offset:2048
	ds_read_b128 v[184:187], v152 offset:3072
	ds_read_b128 v[188:191], v153
	ds_read_b128 v[192:195], v153 offset:1024
	ds_read_b128 v[196:199], v153 offset:2048
	ds_read_b128 v[200:203], v153 offset:3072
	ds_read_b128 v[204:207], v153 offset:4096
	ds_read_b128 v[208:211], v153 offset:5120
	ds_read_b128 v[212:215], v153 offset:6144
	ds_read_b128 v[216:219], v153 offset:7168
	s_add_i32 s55, s55, 1
	s_mul_i32 s2, s55, s60
	s_mul_hi_u32 s3, s55, s33
	s_add_i32 s3, s3, s2
	s_mul_i32 s2, s55, s33
	s_add_u32 s2, s2, s22
	s_addc_u32 s3, s3, s48
	v_cmp_ge_i64_e32 vcc, s[2:3], v[130:131]
	v_cmp_lt_i64_e64 s[4:5], s[2:3], v[130:131]
	s_cbranch_vccnz .LBB0_4735
	s_ashr_i32 s3, s2, 31
	s_lshr_b32 s3, s3, 29
	s_add_i32 s3, s2, s3
	s_ashr_i32 s36, s3, 3
	s_and_b32 s3, s3, -8
	s_sub_i32 s2, s2, s3
	s_cmp_lt_i32 s2, 0
	s_cselect_b32 s3, s49, s35
	s_mul_i32 s2, s3, s2
	s_add_i32 s2, s2, s36
	s_mul_hi_i32 s3, s2, 0x92492493
	s_add_i32 s3, s3, s2
	s_lshr_b32 s36, s3, 31
	s_ashr_i32 s3, s3, 8
	s_add_i32 s3, s3, s36
	s_lshl_b32 s37, s3, 3
	s_sub_i32 s36, s23, s37
	s_min_i32 s38, s36, 8
	s_abs_i32 s36, s38
	v_cvt_f32_u32_e32 v9, s36
	s_sub_i32 s40, 0, s36
	s_mulk_i32 s3, 0x1c0
	s_sub_i32 s2, s2, s3
	v_rcp_iflag_f32_e32 v9, v9
	s_abs_i32 s3, s2
	s_xor_b32 s39, s2, s38
	s_ashr_i32 s39, s39, 31
	v_mul_f32_e32 v9, 0x4f7ffffe, v9
	v_cvt_u32_f32_e32 v9, v9
	s_nop 0
	v_readfirstlane_b32 s41, v9
	s_mul_i32 s40, s40, s41
	s_mul_hi_u32 s40, s41, s40
	s_add_i32 s41, s41, s40
	s_mul_hi_u32 s40, s3, s41
	s_mul_i32 s41, s40, s36
	s_sub_i32 s3, s3, s41
	s_add_i32 s65, s40, 1
	s_sub_i32 s41, s3, s36
	s_cmp_ge_u32 s3, s36
	s_cselect_b32 s40, s65, s40
	s_cselect_b32 s3, s41, s3
	s_add_i32 s41, s40, 1
	s_cmp_ge_u32 s3, s36
	s_cselect_b32 s3, s41, s40
	s_xor_b32 s3, s3, s39
	s_sub_i32 s36, s3, s39
	s_mul_i32 s3, s36, s38
	s_sub_i32 s2, s2, s3
	s_add_i32 s38, s2, s37
	v_cmp_ge_i32_e32 vcc, s38, v230
	s_nop 1
	v_cndmask_b32_e64 v2, 0, 1, vcc
	v_cmp_ge_i32_e32 vcc, s38, v231
	s_nop 1
	v_cndmask_b32_e64 v3, 0, 1, vcc
	v_cmp_ge_i32_e32 vcc, s38, v233
	s_nop 1
	v_cndmask_b32_e64 v5, 0, 1, vcc
	v_cmp_ge_i32_e32 vcc, s38, v235
	s_nop 1
	v_cndmask_b32_e64 v7, 0, 1, vcc
	v_cmp_ge_i32_e32 vcc, s38, v232
	s_nop 1
	v_addc_co_u32_e32 v2, vcc, v3, v2, vcc
	v_cmp_ge_i32_e32 vcc, s38, v234
	s_nop 1
	v_addc_co_u32_e32 v2, vcc, v2, v5, vcc
	v_cmp_ge_i32_e32 vcc, s38, v236
	s_nop 1
	v_addc_co_u32_e32 v155, vcc, v2, v7, vcc

; #define PG8_STAGE(bufoff, gbase, voff) do { _Pragma("unroll") for (int _i = 0; _i < 2; ++_i) \
;         __builtin_amdgcn_global_load_lds((const unsigned*)((const char*)(gbase) + (voff)[_i]), (LAS unsigned*)(lds + (bufoff) + ldsw + _i * 8192), 16, 0, 0); } while (0)
; #define PG8_LDA(dst, b, h) do { _Pragma("unroll") for (int m = 0; m < 4; ++m) _Pragma("unroll") for (int k = 0; k < 2; ++k) dst[m][k] = *(const LAS bf16x8*)(lds + PG8_SA(b, h) + aoff + m * 2048 + k * 1024); } while (0)
; #define PG8_LDB(dst, b, h) do { _Pragma("unroll") for (int n = 0; n < 2; ++n) _Pragma("unroll") for (int k = 0; k < 2; ++k) dst[n][k] = *(const LAS bf16x8*)(lds + PG8_SB(b, h) + boff + n * 2048 + k * 1024); } while (0)
; #define PG8_WAIT_V(n) asm volatile("s_waitcnt vmcnt(" #n ")" ::: "memory")
; #define PG8_WAIT_L(n) asm volatile("s_waitcnt lgkmcnt(" #n ")" ::: "memory")
; #define PG8_BAR __builtin_amdgcn_s_barrier()
; #define PG8_SCHED __builtin_amdgcn_sched_barrier(0)
;     ...
;         const char* nA = has_next ? (const char*)g.A + (size_t)nxt.pm * tstep + (size_t)nxt.kt0 * kstep : cA; const char* nB = has_next ? (const char*)g.Bt + (size_t)nxt.e * g.estride + (size_t)nxt.pn * tstep + (size_t)nxt.kt0 * kstep : cB;
;         const int nt = cur.nkt;
;         for (int t = 0; t < nt; t += 2) {
;             const bool last = (t == nt - 2);
;             const char* a1 = cA + (size_t)(t + 1) * kstep;
;             const char* a2 = last ? nA : cA + (size_t)(t + 2) * kstep; const char* b2 = last ? nB : cB + (size_t)(t + 2) * kstep;
;             const char* a3 = a2 + kstep; const char* b3 = b2 + kstep;
;             PG8_LDB(B0, 0, 0); PG8_LDB(B1, 0, 1); PG8_SCHED; PG8_LDA(At, 0, 0); PG8_STAGE(PG8_SA(1, 1), a1 + hstep, voffA);
;             PG8_WAIT_V(8); PG8_WAIT_L(0); PG8_BAR; PG8_MMA(0, 0, At, B0); PG8_MMA(0, 1, At, B1); PG8_BAR; PG8_SCHED;
;             PG8_LDA(At, 0, 1); PG8_STAGE(PG8_SB(0, 0), b2, voffB); PG8_STAGE(PG8_SB(0, 1), b2 + hstep, voffB); PG8_STAGE(PG8_SA(0, 0), a2, voffA);
;             PG8_WAIT_V(8); PG8_WAIT_L(0); PG8_BAR; PG8_MMA(1, 0, At, B0); PG8_MMA(1, 1, At, B1); PG8_BAR; PG8_SCHED;
.LBB0_4737:
	s_ashr_i32 s39, s38, 31
	s_lshl_b64 s[40:41], s[38:39], 19
	s_add_u32 s40, s29, s40
	s_addc_u32 s41, s31, s41
	s_and_b64 s[4:5], s[4:5], exec
	s_cselect_b32 s37, s41, s47
	s_cselect_b32 s39, s40, s46
	s_add_u32 s4, s46, 0x40080
	v_lshl_add_u64 v[144:145], v[0:1], 0, s[26:27]
	s_addc_u32 s5, s47, 0
	s_mov_b32 s65, -2
	s_add_u32 s46, s4, 0xfffc0080
	s_addc_u32 s47, s5, -1
	s_cmp_eq_u32 s65, 12
	s_cselect_b64 vcc, -1, 0
	s_cselect_b32 s47, s37, s47
	s_cselect_b32 s46, s39, s46
	v_cndmask_b32_e32 v147, v145, v143, vcc
	v_cndmask_b32_e32 v146, v144, v142, vcc
	v_lshl_add_u64 v[220:221], s[4:5], 0, v[138:139]
	s_add_i32 m0, s43, 0xc000
	global_load_lds_dwordx4 v[220:221], off
	v_lshl_add_u64 v[220:221], s[4:5], 0, v[140:141]
	s_add_i32 m0, s43, 0xe000
	s_nop 0
	global_load_lds_dwordx4 v[220:221], off
	s_waitcnt vmcnt(8)
	s_waitcnt lgkmcnt(0)
	s_barrier
	s_setprio 1
	s_waitcnt lgkmcnt(0)
	v_mfma_i32_16x16x64_i8 v[124:127], v[156:159], v[188:191], 0
	v_mfma_i32_16x16x64_i8 v[120:123], v[164:167], v[188:191], 0
	v_mfma_i32_16x16x64_i8 v[116:119], v[156:159], v[196:199], 0
	v_mfma_i32_16x16x64_i8 v[112:115], v[164:167], v[196:199], 0
	v_mfma_i32_16x16x64_i8 v[108:111], v[156:159], v[204:207], 0
	v_mfma_i32_16x16x64_i8 v[104:107], v[164:167], v[204:207], 0
	v_mfma_i32_16x16x64_i8 v[100:103], v[156:159], v[212:215], 0
	v_mfma_i32_16x16x64_i8 v[96:99], v[164:167], v[212:215], 0
	v_mfma_i32_16x16x64_i8 v[124:127], v[160:163], v[192:195], v[124:127]
	v_mfma_i32_16x16x64_i8 v[120:123], v[168:171], v[192:195], v[120:123]
	v_mfma_i32_16x16x64_i8 v[116:119], v[160:163], v[200:203], v[116:119]
	v_mfma_i32_16x16x64_i8 v[112:115], v[168:171], v[200:203], v[112:115]
	v_mfma_i32_16x16x64_i8 v[108:111], v[160:163], v[208:211], v[108:111]
	v_mfma_i32_16x16x64_i8 v[104:107], v[168:171], v[208:211], v[104:107]
	v_mfma_i32_16x16x64_i8 v[100:103], v[160:163], v[216:219], v[100:103]
	v_mfma_i32_16x16x64_i8 v[96:99], v[168:171], v[216:219], v[96:99]
	s_setprio 0
	s_setprio 1
	v_mfma_i32_16x16x64_i8 v[92:95], v[172:175], v[188:191], 0
	v_mfma_i32_16x16x64_i8 v[88:91], v[180:183], v[188:191], 0
	v_mfma_i32_16x16x64_i8 v[84:87], v[172:175], v[196:199], 0
	v_mfma_i32_16x16x64_i8 v[80:83], v[180:183], v[196:199], 0
	v_mfma_i32_16x16x64_i8 v[76:79], v[172:175], v[204:207], 0
	v_mfma_i32_16x16x64_i8 v[72:75], v[180:183], v[204:207], 0
	v_mfma_i32_16x16x64_i8 v[68:71], v[172:175], v[212:215], 0
	v_mfma_i32_16x16x64_i8 v[64:67], v[180:183], v[212:215], 0
	v_mfma_i32_16x16x64_i8 v[92:95], v[176:179], v[192:195], v[92:95]
	v_mfma_i32_16x16x64_i8 v[88:91], v[184:187], v[192:195], v[88:91]
	v_mfma_i32_16x16x64_i8 v[84:87], v[176:179], v[200:203], v[84:87]
	v_mfma_i32_16x16x64_i8 v[80:83], v[184:187], v[200:203], v[80:83]
	v_mfma_i32_16x16x64_i8 v[76:79], v[176:179], v[208:211], v[76:79]
	v_mfma_i32_16x16x64_i8 v[72:75], v[184:187], v[208:211], v[72:75]
	v_mfma_i32_16x16x64_i8 v[68:71], v[176:179], v[216:219], v[68:71]
	v_mfma_i32_16x16x64_i8 v[64:67], v[184:187], v[216:219], v[64:67]
	s_setprio 0
	s_barrier
	s_add_i32 s66, s61, s34
	v_lshl_add_u64 v[220:221], v[146:147], 0, v[128:129]
	s_mov_b32 m0, s66
	ds_read_b128 v[188:191], v153 offset:16384
	ds_read_b128 v[192:195], v153 offset:17408
	ds_read_b128 v[196:199], v153 offset:18432
	ds_read_b128 v[200:203], v153 offset:19456
	ds_read_b128 v[204:207], v153 offset:20480
	ds_read_b128 v[208:211], v153 offset:21504
	ds_read_b128 v[212:215], v153 offset:22528
	ds_read_b128 v[216:219], v153 offset:23552
	global_load_lds_dwordx4 v[220:221], off
	v_lshl_add_u64 v[222:223], v[146:147], 0, v[134:135]
	s_add_i32 m0, s66, 0x2000
	v_lshl_add_u64 v[224:225], v[146:147], 0, s[12:13]
	s_add_i32 s66, s62, s34
	global_load_lds_dwordx4 v[222:223], off
	v_lshl_add_u64 v[226:227], v[224:225], 0, v[128:129]
	s_mov_b32 m0, s66
	v_lshl_add_u64 v[224:225], v[224:225], 0, v[134:135]
	global_load_lds_dwordx4 v[226:227], off
	s_add_i32 m0, s66, 0x2000
	v_lshl_add_u64 v[226:227], s[46:47], 0, v[136:137]
	global_load_lds_dwordx4 v[224:225], off
	v_lshl_add_u64 v[224:225], s[46:47], 0, v[132:133]
	s_mov_b32 m0, s43
	s_nop 0
	global_load_lds_dwordx4 v[224:225], off
	s_mov_b32 m0, s45
	s_nop 0
	global_load_lds_dwordx4 v[226:227], off
	s_waitcnt vmcnt(8)
	s_waitcnt lgkmcnt(0)
	s_barrier
	s_setprio 1
	s_waitcnt lgkmcnt(0)
	v_mfma_i32_16x16x64_i8 v[60:63], v[156:159], v[188:191], 0
	v_mfma_i32_16x16x64_i8 v[56:59], v[164:167], v[188:191], 0
	v_mfma_i32_16x16x64_i8 v[52:55], v[156:159], v[196:199], 0
	v_mfma_i32_16x16x64_i8 v[48:51], v[164:167], v[196:199], 0
	v_mfma_i32_16x16x64_i8 v[44:47], v[156:159], v[204:207], 0
	v_mfma_i32_16x16x64_i8 v[40:43], v[164:167], v[204:207], 0
	v_mfma_i32_16x16x64_i8 v[36:39], v[156:159], v[212:215], 0
	v_mfma_i32_16x16x64_i8 v[32:35], v[164:167], v[212:215], 0
	v_mfma_i32_16x16x64_i8 v[60:63], v[160:163], v[192:195], v[60:63]
	v_mfma_i32_16x16x64_i8 v[56:59], v[168:171], v[192:195], v[56:59]
	v_mfma_i32_16x16x64_i8 v[52:55], v[160:163], v[200:203], v[52:55]
	v_mfma_i32_16x16x64_i8 v[48:51], v[168:171], v[200:203], v[48:51]
	v_mfma_i32_16x16x64_i8 v[44:47], v[160:163], v[208:211], v[44:47]
	v_mfma_i32_16x16x64_i8 v[40:43], v[168:171], v[208:211], v[40:43]
	v_mfma_i32_16x16x64_i8 v[36:39], v[160:163], v[216:219], v[36:39]
	v_mfma_i32_16x16x64_i8 v[32:35], v[168:171], v[216:219], v[32:35]
	s_setprio 0
	s_setprio 1
	v_mfma_i32_16x16x64_i8 v[28:31], v[172:175], v[188:191], 0
	v_mfma_i32_16x16x64_i8 v[24:27], v[180:183], v[188:191], 0
	v_mfma_i32_16x16x64_i8 v[20:23], v[172:175], v[196:199], 0
	v_mfma_i32_16x16x64_i8 v[16:19], v[180:183], v[196:199], 0
	v_mfma_i32_16x16x64_i8 v[12:15], v[172:175], v[204:207], 0
	v_mfma_i32_16x16x64_i8 v[8:11], v[180:183], v[204:207], 0
	v_mfma_i32_16x16x64_i8 v[4:7], v[172:175], v[212:215], 0
	v_mfma_i32_16x16x64_i8 v[0:3], v[180:183], v[212:215], 0
	v_mfma_i32_16x16x64_i8 v[28:31], v[176:179], v[192:195], v[28:31]
	v_mfma_i32_16x16x64_i8 v[24:27], v[184:187], v[192:195], v[24:27]
	v_mfma_i32_16x16x64_i8 v[20:23], v[176:179], v[200:203], v[20:23]
	v_mfma_i32_16x16x64_i8 v[16:19], v[184:187], v[200:203], v[16:19]
	v_mfma_i32_16x16x64_i8 v[12:15], v[176:179], v[208:211], v[12:15]
	v_mfma_i32_16x16x64_i8 v[8:11], v[184:187], v[208:211], v[8:11]
	v_mfma_i32_16x16x64_i8 v[4:7], v[176:179], v[216:219], v[4:7]
	v_mfma_i32_16x16x64_i8 v[0:3], v[184:187], v[216:219], v[0:3]
	s_setprio 0
	s_barrier
; #define PG8_STAGE(bufoff, gbase, voff) do { _Pragma("unroll") for (int _i = 0; _i < 2; ++_i) \
;         __builtin_amdgcn_global_load_lds((const unsigned*)((const char*)(gbase) + (voff)[_i]), (LAS unsigned*)(lds + (bufoff) + ldsw + _i * 8192), 16, 0, 0); } while (0)
; #define PG8_LDA(dst, b, h) do { _Pragma("unroll") for (int m = 0; m < 4; ++m) _Pragma("unroll") for (int k = 0; k < 2; ++k) dst[m][k] = *(const LAS bf16x8*)(lds + PG8_SA(b, h) + aoff + m * 2048 + k * 1024); } while (0)
; #define PG8_LDB(dst, b, h) do { _Pragma("unroll") for (int n = 0; n < 2; ++n) _Pragma("unroll") for (int k = 0; k < 2; ++k) dst[n][k] = *(const LAS bf16x8*)(lds + PG8_SB(b, h) + boff + n * 2048 + k * 1024); } while (0)
; #define PG8_WAIT_V(n) asm volatile("s_waitcnt vmcnt(" #n ")" ::: "memory")
; #define PG8_WAIT_L(n) asm volatile("s_waitcnt lgkmcnt(" #n ")" ::: "memory")
; #define PG8_BAR __builtin_amdgcn_s_barrier()
; #define PG8_SCHED __builtin_amdgcn_sched_barrier(0)
;     ...
;             PG8_LDB(B0, 1, 0); PG8_LDB(B1, 1, 1); PG8_SCHED; PG8_LDA(At, 1, 0); PG8_STAGE(PG8_SA(0, 1), a2 + hstep, voffA);
;             PG8_WAIT_V(8); PG8_WAIT_L(0); PG8_BAR; PG8_MMA(0, 0, At, B0); PG8_MMA(0, 1, At, B1); PG8_BAR; PG8_SCHED;
;             PG8_LDA(At, 1, 1); PG8_STAGE(PG8_SB(1, 0), b3, voffB); PG8_STAGE(PG8_SB(1, 1), b3 + hstep, voffB); PG8_STAGE(PG8_SA(1, 0), a3, voffA);
;             PG8_WAIT_V(8); PG8_WAIT_L(0); PG8_BAR; PG8_MMA(1, 0, At, B0); PG8_MMA(1, 1, At, B1); PG8_BAR; PG8_SCHED;
;         }
	s_add_i32 s66, 0, 0x18000
	s_add_i32 s67, 0, 0x1c000
	v_add_u32_e32 v168, s66, v149
	v_add_u32_e32 v184, s67, v149
	ds_read_b128 v[156:159], v168
	ds_read_b128 v[160:163], v168 offset:1024
	ds_read_b128 v[164:167], v168 offset:2048
	ds_read_b128 v[168:171], v168 offset:3072
	ds_read_b128 v[172:175], v184
	ds_read_b128 v[176:179], v184 offset:1024
	ds_read_b128 v[180:183], v184 offset:2048
	ds_read_b128 v[184:187], v184 offset:3072
	s_add_u32 s46, s46, 0x40000
	s_addc_u32 s47, s47, 0
	s_mov_b32 m0, s51
	v_lshl_add_u64 v[228:229], s[46:47], 0, v[132:133]
	ds_read_b128 v[188:191], v153 offset:32768
	ds_read_b128 v[192:195], v153 offset:33792
	ds_read_b128 v[196:199], v153 offset:34816
	ds_read_b128 v[200:203], v153 offset:35840
	ds_read_b128 v[204:207], v153 offset:36864
	ds_read_b128 v[208:211], v153 offset:37888
	ds_read_b128 v[212:215], v153 offset:38912
	ds_read_b128 v[216:219], v153 offset:39936
	global_load_lds_dwordx4 v[228:229], off
	v_lshl_add_u64 v[228:229], s[46:47], 0, v[136:137]
	s_mov_b32 m0, s54
	s_nop 0
	global_load_lds_dwordx4 v[228:229], off
	s_waitcnt vmcnt(8)
	s_waitcnt lgkmcnt(0)
	s_barrier
	s_setprio 1
	s_waitcnt lgkmcnt(0)
	v_mfma_i32_16x16x64_i8 v[124:127], v[156:159], v[188:191], v[124:127]
	v_mfma_i32_16x16x64_i8 v[120:123], v[164:167], v[188:191], v[120:123]
	v_mfma_i32_16x16x64_i8 v[116:119], v[156:159], v[196:199], v[116:119]
	v_mfma_i32_16x16x64_i8 v[112:115], v[164:167], v[196:199], v[112:115]
	v_mfma_i32_16x16x64_i8 v[108:111], v[156:159], v[204:207], v[108:111]
	v_mfma_i32_16x16x64_i8 v[104:107], v[164:167], v[204:207], v[104:107]
	v_mfma_i32_16x16x64_i8 v[100:103], v[156:159], v[212:215], v[100:103]
	v_mfma_i32_16x16x64_i8 v[96:99], v[164:167], v[212:215], v[96:99]
	v_mfma_i32_16x16x64_i8 v[124:127], v[160:163], v[192:195], v[124:127]
	v_mfma_i32_16x16x64_i8 v[120:123], v[168:171], v[192:195], v[120:123]
	v_mfma_i32_16x16x64_i8 v[116:119], v[160:163], v[200:203], v[116:119]
	v_mfma_i32_16x16x64_i8 v[112:115], v[168:171], v[200:203], v[112:115]
	v_mfma_i32_16x16x64_i8 v[108:111], v[160:163], v[208:211], v[108:111]
	v_mfma_i32_16x16x64_i8 v[104:107], v[168:171], v[208:211], v[104:107]
	v_mfma_i32_16x16x64_i8 v[100:103], v[160:163], v[216:219], v[100:103]
	v_mfma_i32_16x16x64_i8 v[96:99], v[168:171], v[216:219], v[96:99]
	s_setprio 0
	s_setprio 1
	v_mfma_i32_16x16x64_i8 v[92:95], v[172:175], v[188:191], v[92:95]
	v_mfma_i32_16x16x64_i8 v[88:91], v[180:183], v[188:191], v[88:91]
	v_mfma_i32_16x16x64_i8 v[84:87], v[172:175], v[196:199], v[84:87]
	v_mfma_i32_16x16x64_i8 v[80:83], v[180:183], v[196:199], v[80:83]
	v_mfma_i32_16x16x64_i8 v[76:79], v[172:175], v[204:207], v[76:79]
	v_mfma_i32_16x16x64_i8 v[72:75], v[180:183], v[204:207], v[72:75]
	v_mfma_i32_16x16x64_i8 v[68:71], v[172:175], v[212:215], v[68:71]
	v_mfma_i32_16x16x64_i8 v[64:67], v[180:183], v[212:215], v[64:67]
	v_mfma_i32_16x16x64_i8 v[92:95], v[176:179], v[192:195], v[92:95]
	v_mfma_i32_16x16x64_i8 v[88:91], v[184:187], v[192:195], v[88:91]
	v_mfma_i32_16x16x64_i8 v[84:87], v[176:179], v[200:203], v[84:87]
	v_mfma_i32_16x16x64_i8 v[80:83], v[184:187], v[200:203], v[80:83]
	v_mfma_i32_16x16x64_i8 v[76:79], v[176:179], v[208:211], v[76:79]
	v_mfma_i32_16x16x64_i8 v[72:75], v[184:187], v[208:211], v[72:75]
	v_mfma_i32_16x16x64_i8 v[68:71], v[176:179], v[216:219], v[68:71]
	v_mfma_i32_16x16x64_i8 v[64:67], v[184:187], v[216:219], v[64:67]
	s_setprio 0
	s_barrier
	s_add_i32 s46, s66, s34
	v_lshl_add_u64 v[220:221], v[220:221], 0, s[18:19]
	s_mov_b32 m0, s46
	ds_read_b128 v[188:191], v153 offset:49152
	ds_read_b128 v[192:195], v153 offset:50176
	ds_read_b128 v[196:199], v153 offset:51200
	ds_read_b128 v[200:203], v153 offset:52224
	ds_read_b128 v[204:207], v153 offset:53248
	ds_read_b128 v[208:211], v153 offset:54272
	ds_read_b128 v[212:215], v153 offset:55296
	ds_read_b128 v[216:219], v153 offset:56320
	global_load_lds_dwordx4 v[220:221], off
	v_lshl_add_u64 v[220:221], v[222:223], 0, s[18:19]
	s_add_i32 m0, s46, 0x2000
	v_lshl_add_u64 v[146:147], v[146:147], 0, s[20:21]
	s_add_i32 s46, s67, s34
	global_load_lds_dwordx4 v[220:221], off
	v_lshl_add_u64 v[220:221], v[146:147], 0, v[128:129]
	s_mov_b32 m0, s46
	v_lshl_add_u64 v[146:147], v[146:147], 0, v[134:135]
	global_load_lds_dwordx4 v[220:221], off
	s_add_i32 m0, s46, 0x2000
	s_nop 0
	global_load_lds_dwordx4 v[146:147], off
	v_lshl_add_u64 v[146:147], v[224:225], 0, s[18:19]
	s_mov_b32 m0, s58
	s_nop 0
	global_load_lds_dwordx4 v[146:147], off
	v_lshl_add_u64 v[146:147], v[226:227], 0, s[18:19]
	s_mov_b32 m0, s59
	s_nop 0
	global_load_lds_dwordx4 v[146:147], off
	s_waitcnt vmcnt(8)
	s_waitcnt lgkmcnt(0)
	s_barrier
	s_setprio 1
	s_waitcnt lgkmcnt(0)
	v_mfma_i32_16x16x64_i8 v[60:63], v[156:159], v[188:191], v[60:63]
	v_mfma_i32_16x16x64_i8 v[56:59], v[164:167], v[188:191], v[56:59]
	v_mfma_i32_16x16x64_i8 v[52:55], v[156:159], v[196:199], v[52:55]
	v_mfma_i32_16x16x64_i8 v[48:51], v[164:167], v[196:199], v[48:51]
	v_mfma_i32_16x16x64_i8 v[44:47], v[156:159], v[204:207], v[44:47]
	v_mfma_i32_16x16x64_i8 v[40:43], v[164:167], v[204:207], v[40:43]
	v_mfma_i32_16x16x64_i8 v[36:39], v[156:159], v[212:215], v[36:39]
	v_mfma_i32_16x16x64_i8 v[32:35], v[164:167], v[212:215], v[32:35]
	v_mfma_i32_16x16x64_i8 v[60:63], v[160:163], v[192:195], v[60:63]
	v_mfma_i32_16x16x64_i8 v[56:59], v[168:171], v[192:195], v[56:59]
	v_mfma_i32_16x16x64_i8 v[52:55], v[160:163], v[200:203], v[52:55]
	v_mfma_i32_16x16x64_i8 v[48:51], v[168:171], v[200:203], v[48:51]
	v_mfma_i32_16x16x64_i8 v[44:47], v[160:163], v[208:211], v[44:47]
	v_mfma_i32_16x16x64_i8 v[40:43], v[168:171], v[208:211], v[40:43]
	v_mfma_i32_16x16x64_i8 v[36:39], v[160:163], v[216:219], v[36:39]
	v_mfma_i32_16x16x64_i8 v[32:35], v[168:171], v[216:219], v[32:35]
	s_setprio 0
	s_setprio 1
	v_mfma_i32_16x16x64_i8 v[28:31], v[172:175], v[188:191], v[28:31]
	v_mfma_i32_16x16x64_i8 v[24:27], v[180:183], v[188:191], v[24:27]
	v_mfma_i32_16x16x64_i8 v[20:23], v[172:175], v[196:199], v[20:23]
	v_mfma_i32_16x16x64_i8 v[16:19], v[180:183], v[196:199], v[16:19]
	v_mfma_i32_16x16x64_i8 v[12:15], v[172:175], v[204:207], v[12:15]
	v_mfma_i32_16x16x64_i8 v[8:11], v[180:183], v[204:207], v[8:11]
	v_mfma_i32_16x16x64_i8 v[4:7], v[172:175], v[212:215], v[4:7]
	v_mfma_i32_16x16x64_i8 v[0:3], v[180:183], v[212:215], v[0:3]
	v_mfma_i32_16x16x64_i8 v[28:31], v[176:179], v[192:195], v[28:31]
	v_mfma_i32_16x16x64_i8 v[24:27], v[184:187], v[192:195], v[24:27]
	v_mfma_i32_16x16x64_i8 v[20:23], v[176:179], v[200:203], v[20:23]
	v_mfma_i32_16x16x64_i8 v[16:19], v[184:187], v[200:203], v[16:19]
	v_mfma_i32_16x16x64_i8 v[12:15], v[176:179], v[208:211], v[12:15]
	v_mfma_i32_16x16x64_i8 v[8:11], v[184:187], v[208:211], v[8:11]
	v_mfma_i32_16x16x64_i8 v[4:7], v[176:179], v[216:219], v[4:7]
	v_mfma_i32_16x16x64_i8 v[0:3], v[184:187], v[216:219], v[0:3]
	s_setprio 0
	s_barrier
	s_add_i32 s65, s65, 2
	s_add_u32 s4, s4, 0x100
	s_addc_u32 s5, s5, 0
	s_cmp_gt_u32 s65, 13
	v_lshl_add_u64 v[144:145], v[144:145], 0, s[26:27]
	s_cbranch_scc0 .LBB0_4738
